# race-proofing for drifting sibling groups: FFN hidden image moved off its zatt/zdn overlay to the dQD..oraw region (dead during the proj..in chain); row-stat partial slots moved from z to og
# speedup vs baseline: 1.0152x; 1.0152x over previous
.LBB0_72:
	s_or_b64 exec, exec, s[0:1]
	s_add_u32 s0, s72, 0x26600000
	v_writelane_b32 v253, s0, 45
	s_addc_u32 s0, s73, 0
	s_lshl_b32 s20, s74, 3
	v_writelane_b32 v253, s0, 46
	s_add_u32 s0, s72, 0x6d00000
	s_addc_u32 s1, s73, 0
	v_writelane_b32 v253, s0, 47
	v_mov_b32_e32 v137, 0
	v_mov_b32_e32 v155, 0x358637bd
	v_writelane_b32 v253, s1, 48
	s_add_u32 s0, s72, 0xed00000
	s_addc_u32 s1, s73, 0
	v_writelane_b32 v253, s0, 49
	v_mov_b32_e32 v156, 0x24000
	v_mov_b32_e32 v157, 0x24004
	v_writelane_b32 v253, s1, 50
	s_add_u32 s0, s72, 0x1f500000
	s_addc_u32 s1, s73, 0
	v_writelane_b32 v255, s0, 2
	s_nop 1
	v_writelane_b32 v255, s1, 3
	s_add_u32 s0, s72, 0x1f516000
	s_addc_u32 s1, s73, 0
	v_writelane_b32 v253, s0, 51
	v_mov_b32_e32 v158, 1
	s_movk_i32 s75, 0x3000
	v_writelane_b32 v253, s1, 52
	s_add_u32 s0, s72, 0x1f52c000
	s_addc_u32 s1, s73, 0
	v_writelane_b32 v253, s0, 53
	s_movk_i32 s33, 0x1600
	v_mov_b32_e32 v160, 0xff61b1e6
	v_writelane_b32 v253, s1, 54
	s_add_u32 s0, s72, 0x1f542000
	s_addc_u32 s1, s73, 0
	v_writelane_b32 v253, s0, 55
	v_mov_b32_e32 v161, 0x41b17218
	v_mov_b32_e32 v252, 64
	v_writelane_b32 v253, s1, 56
	s_add_u32 s0, s72, 0xb00000
	v_writelane_b32 v253, s0, 57
	s_addc_u32 s0, s73, 0
	v_writelane_b32 v253, s0, 58
	s_add_u32 s0, s72, 0x1080000
	v_writelane_b32 v253, s0, 59
	s_addc_u32 s0, s73, 0
	v_writelane_b32 v253, s0, 60
	s_add_u32 s0, s72, 0x26500000
	s_addc_u32 s1, s73, 0
	v_writelane_b32 v253, s0, 61
	v_mov_b32_e32 v138, 0x3f317218
	v_mov_b32_e32 v250, 0x7f800000
	v_writelane_b32 v253, s1, 62
	s_add_u32 s0, s72, 0x26500400
	s_addc_u32 s1, s73, 0
	v_writelane_b32 v253, s0, 63
	v_mov_b32_e32 v251, 0x7fc00000
	v_mov_b32_e32 v159, 0xff800000
	v_writelane_b32 v254, s1, 0
	s_add_u32 s0, s72, 0x26500800
	s_addc_u32 s1, s73, 0
	v_writelane_b32 v254, s0, 1
	v_mov_b32_e32 v166, 3
	v_mov_b32_e32 v167, 4
	v_writelane_b32 v254, s1, 2
	s_add_u32 s0, s72, 0x26500c00
	s_addc_u32 s1, s73, 0
	v_writelane_b32 v254, s0, 3
	v_mov_b32_e32 v168, 6
	v_mov_b32_e32 v169, 7
	v_writelane_b32 v254, s1, 4
	s_add_u32 s0, s72, 0x13500000
	s_addc_u32 s1, s73, 0
	v_writelane_b32 v254, s0, 5
	s_mov_b32 s3, 0xfe967699
	s_mov_b32 s5, 0
	v_writelane_b32 v254, s1, 6
	s_add_u32 s0, s72, 0x19500000
	s_addc_u32 s1, s73, 0
	v_writelane_b32 v254, s0, 7
	s_mov_b64 s[76:77], 0x6d40080
	s_mov_b64 s[16:17], 0x6d60080
	v_writelane_b32 v254, s1, 8
	s_add_u32 s0, s72, 0x26720000
	s_addc_u32 s1, s73, 0
	v_writelane_b32 v254, s0, 9
	s_mov_b64 s[86:87], 0x100
	s_mov_b64 s[88:89], 0x6d00100
	v_writelane_b32 v254, s1, 10
	s_add_u32 s0, s72, 0x267e0000
	v_writelane_b32 v254, s0, 11
	s_addc_u32 s0, s73, 0
	v_writelane_b32 v254, s0, 12
	s_add_u32 s0, s72, 0x1f500000
	s_addc_u32 s1, s73, 0
	v_writelane_b32 v254, s0, 13
	s_mov_b64 s[90:91], 0x6d20100
	s_mov_b64 s[94:95], 0x6d40100
	v_writelane_b32 v254, s1, 14
	s_add_u32 s0, s72, 0x21500000
	v_writelane_b32 v254, s0, 15
	s_addc_u32 s0, s73, 0
	v_writelane_b32 v254, s0, 16
	s_add_u32 s0, s72, 0x23500000
	v_writelane_b32 v254, s0, 17
	s_addc_u32 s0, s73, 0
	v_writelane_b32 v254, s0, 18
	s_add_u32 s0, s72, 0x1d500000
	s_addc_u32 s1, s73, 0
	v_writelane_b32 v254, s0, 19
	s_mov_b64 s[78:79], 0x6d60100
	s_mov_b64 s[24:25], 0x6d00180
	v_writelane_b32 v254, s1, 20
	s_add_u32 s0, s72, 0x1b500000
	s_addc_u32 s1, s73, 0
	v_writelane_b32 v254, s0, 21
	s_mov_b64 s[28:29], 0x6d20180
	s_mov_b64 s[96:97], 0x1f608080
	v_writelane_b32 v254, s1, 22
	s_add_i32 s0, s52, 0xffffff00
	v_writelane_b32 v254, s0, 23
	s_add_u32 s0, s72, 0x2180000
	v_writelane_b32 v254, s0, 24
	s_addc_u32 s0, s73, 0
	v_writelane_b32 v254, s0, 25
	s_add_u32 s0, s72, 0x2200000
	v_writelane_b32 v254, s0, 26
	s_addc_u32 s0, s73, 0
	v_writelane_b32 v254, s0, 27
	s_add_u32 s0, s72, 0x2400000
	v_writelane_b32 v254, s0, 28
	s_addc_u32 s0, s73, 0
	v_writelane_b32 v254, s0, 29
	s_add_u32 s0, s72, 0x2600000
	v_writelane_b32 v254, s0, 30
	s_addc_u32 s0, s73, 0
	v_writelane_b32 v254, s0, 31
	s_add_u32 s0, s72, 0x3100000
	v_writelane_b32 v254, s0, 32
	s_addc_u32 s0, s73, 0
	v_writelane_b32 v254, s0, 33
	s_add_u32 s0, s72, 0x24500000
	s_addc_u32 s1, s73, 0
	v_writelane_b32 v254, s0, 34
	s_mov_b64 s[34:35], 0x1f500100
	s_mov_b64 s[80:81], 0x1f558100
	v_writelane_b32 v254, s1, 35
	s_add_u32 s0, s72, 0x248e0000
	s_addc_u32 s1, s73, 0
	v_writelane_b32 v254, s0, 36
	s_ashr_i32 s53, s52, 31
	s_mov_b64 s[18:19], 0x1f5b0100
	v_writelane_b32 v254, s1, 37
	s_lshl_b64 s[0:1], s[52:53], 8
	v_writelane_b32 v254, s0, 38
	s_mov_b64 s[84:85], 0x1f608100
	s_mov_b64 s[30:31], 0x1f500180
	v_writelane_b32 v254, s1, 39
	s_add_u32 s0, s72, 0x1ad00000
	s_addc_u32 s1, s73, 0
	v_writelane_b32 v254, s0, 40
	s_mov_b32 s2, 0x3db504f3
	s_waitcnt lgkmcnt(0)
	v_writelane_b32 v254, s1, 41
	s_add_u32 s0, s72, 0x8d00000
	s_addc_u32 s1, s73, 0
	v_writelane_b32 v254, s0, 42
	s_ashr_i32 s21, s20, 31
	s_barrier
	v_writelane_b32 v254, s1, 43
	s_lshl_b32 s0, s74, 7
	v_writelane_b32 v254, s0, 44
	s_addk_i32 s0, 0xc000
	v_writelane_b32 v254, s0, 45
	s_lshl_b32 s0, s74, 12
	v_writelane_b32 v254, s0, 46
	s_lshl_b64 s[0:1], s[20:21], 11
	v_writelane_b32 v254, s0, 47
	s_nop 1
	v_writelane_b32 v254, s1, 48
	s_lshl_b64 s[0:1], s[20:21], 12
	v_writelane_b32 v254, s0, 49
	s_nop 1
	v_writelane_b32 v254, s1, 50
	s_mov_b32 s0, s52
	v_writelane_b32 v254, s0, 51
	s_nop 1
	v_writelane_b32 v254, s1, 52
	s_lshl_b64 s[0:1], s[52:53], 11
	v_writelane_b32 v254, s0, 53
	s_mov_b32 s52, 0
	s_nop 0
	v_writelane_b32 v254, s1, 54
	s_branch .LBB0_75

.LBB0_74:
	s_or_b64 exec, exec, s[0:1]
	v_readlane_b32 s5, v254, 57
	v_readlane_b32 s36, v253, 27
	s_add_i32 s5, s5, 1
	v_readlane_b32 s42, v253, 33
	v_readlane_b32 s43, v253, 34
	s_add_u32 s42, s42, 0xc000
	v_readlane_b32 s37, v253, 28
	v_readlane_b32 s38, v253, 29
	v_readlane_b32 s39, v253, 30
	v_readlane_b32 s40, v253, 31
	v_readlane_b32 s41, v253, 32
	v_readlane_b32 s44, v253, 35
	v_readlane_b32 s45, v253, 36
	v_readlane_b32 s46, v253, 37
	v_readlane_b32 s47, v253, 38
	v_readlane_b32 s48, v253, 39
	v_readlane_b32 s49, v253, 40
	v_readlane_b32 s50, v253, 41
	v_readlane_b32 s51, v253, 42
	s_addc_u32 s43, s43, 0
	v_writelane_b32 v253, s36, 27
	s_cmp_eq_u32 s5, 4
	s_waitcnt lgkmcnt(0)
	v_writelane_b32 v253, s37, 28
	v_writelane_b32 v253, s38, 29
	v_writelane_b32 v253, s39, 30
	v_writelane_b32 v253, s40, 31
	v_writelane_b32 v253, s41, 32
	v_writelane_b32 v253, s42, 33
	v_writelane_b32 v253, s43, 34
	v_writelane_b32 v253, s44, 35
	v_writelane_b32 v253, s45, 36
	v_writelane_b32 v253, s46, 37
	v_writelane_b32 v253, s47, 38
	v_writelane_b32 v253, s48, 39
	v_writelane_b32 v253, s49, 40
	v_writelane_b32 v253, s50, 41
	v_writelane_b32 v253, s51, 42
	s_barrier
	s_cbranch_scc1 .Lfn_skip_c
	s_lshl_b32 s0, s92, 3
	s_and_b32 s0, s0, 56
	s_bfe_u32 s1, s92, 0x30003
	s_or_b32 s0, s0, s1
	s_lshr_b32 s1, s92, 6
	v_lshrrev_b32_e32 v140, 8, v154
	v_and_b32_e32 v141, 15, v154
	v_lshl_add_u32 v140, v140, 6, v141
	v_bfe_u32 v141, v154, 6, 2
	v_bfe_u32 v142, v154, 4, 2
	v_lshlrev_b32_e32 v141, 5, v141
	v_lshl_add_u32 v141, v142, 3, v141
	v_lshlrev_b32_e32 v142, 2, v140
	v_lshlrev_b32_e32 v143, 2, v141
	v_lshlrev_b32_e32 v144, 11, v140
	v_lshl_add_u32 v144, v141, 1, v144
	s_lshl_b32 s6, s0, 12
	s_add_u32 s6, s6, s72
	s_addc_u32 s7, s73, 0
	s_add_u32 s6, s6, 0x19500000
	s_addc_u32 s7, s7, 0
	global_load_dword v170, v142, s[6:7] offset:0
	global_load_dword v171, v142, s[6:7] offset:1024
	global_load_dword v172, v142, s[6:7] offset:2048
	global_load_dword v173, v142, s[6:7] offset:3072
	global_load_dword v174, v142, s[6:7] offset:64
	global_load_dword v175, v142, s[6:7] offset:1088
	global_load_dword v176, v142, s[6:7] offset:2112
	global_load_dword v177, v142, s[6:7] offset:3136
	global_load_dword v178, v142, s[6:7] offset:128
	global_load_dword v179, v142, s[6:7] offset:1152
	global_load_dword v180, v142, s[6:7] offset:2176
	global_load_dword v181, v142, s[6:7] offset:3200
	global_load_dword v182, v142, s[6:7] offset:192
	global_load_dword v183, v142, s[6:7] offset:1216
	global_load_dword v184, v142, s[6:7] offset:2240
	global_load_dword v185, v142, s[6:7] offset:3264
	global_load_dword v186, v142, s[6:7] offset:512
	global_load_dword v187, v142, s[6:7] offset:1536
	global_load_dword v188, v142, s[6:7] offset:2560
	global_load_dword v189, v142, s[6:7] offset:3584
	global_load_dword v190, v142, s[6:7] offset:576
	global_load_dword v191, v142, s[6:7] offset:1600
	global_load_dword v192, v142, s[6:7] offset:2624
	global_load_dword v193, v142, s[6:7] offset:3648
	global_load_dword v194, v142, s[6:7] offset:640
	global_load_dword v195, v142, s[6:7] offset:1664
	global_load_dword v196, v142, s[6:7] offset:2688
	global_load_dword v197, v142, s[6:7] offset:3712
	global_load_dword v198, v142, s[6:7] offset:704
	global_load_dword v199, v142, s[6:7] offset:1728
	global_load_dword v200, v142, s[6:7] offset:2752
	global_load_dword v201, v142, s[6:7] offset:3776
	v_readlane_b32 s4, v254, 57
	s_add_i32 s4, s4, 1
	s_lshl_b32 s4, s4, 12
	s_lshl_b32 s1, s1, 10
	v_readlane_b32 s8, v253, 19
	v_readlane_b32 s9, v253, 20
	s_add_u32 s8, s8, s4
	s_addc_u32 s9, s9, 0
	s_add_u32 s8, s8, s1
	s_addc_u32 s9, s9, 0
	s_lshr_b32 s4, s0, 3
	s_mul_i32 s4, s4, 0x9000
	s_add_u32 s4, s4, s1
	v_readlane_b32 s10, v254, 55
	v_readlane_b32 s11, v254, 56
	s_add_u32 s10, s10, s4
	s_addc_u32 s11, s11, 0
	s_add_u32 s12, s10, 0x48000
	s_addc_u32 s13, s11, 0
	s_add_u32 s10, s10, 0x49000
	s_addc_u32 s11, s11, 0
	global_load_dwordx4 v[204:207], v143, s[8:9]
	global_load_dwordx4 v[220:223], v143, s[10:11]
	global_load_dwordx4 v[236:239], v143, s[12:13]
	global_load_dwordx4 v[208:211], v143, s[8:9] offset:16
	global_load_dwordx4 v[224:227], v143, s[10:11] offset:16
	global_load_dwordx4 v[146:149], v143, s[12:13] offset:16
	global_load_dwordx4 v[212:215], v143, s[8:9] offset:512
	global_load_dwordx4 v[228:231], v143, s[10:11] offset:512
	global_load_dwordx4 v[150:153], v143, s[12:13] offset:512
	global_load_dwordx4 v[216:219], v143, s[8:9] offset:528
	global_load_dwordx4 v[232:235], v143, s[10:11] offset:528
	global_load_dwordx4 v[162:165], v143, s[12:13] offset:528
	v_readlane_b32 s14, v253, 47
	v_readlane_b32 s15, v253, 48
	s_lshl_b32 s4, s0, 19
	s_add_u32 s14, s14, s4
	s_addc_u32 s15, s15, 0
	s_lshr_b32 s4, s1, 1
	s_add_u32 s14, s14, s4
	s_addc_u32 s15, s15, 0
	s_waitcnt vmcnt(0)
	v_add_f32_e32 v170, v170, v171
	v_add_f32_e32 v172, v172, v173
	v_add_f32_e32 v174, v174, v175
	v_add_f32_e32 v176, v176, v177
	v_add_f32_e32 v178, v178, v179
	v_add_f32_e32 v180, v180, v181
	v_add_f32_e32 v182, v182, v183
	v_add_f32_e32 v184, v184, v185
	v_add_f32_e32 v186, v186, v187
	v_add_f32_e32 v188, v188, v189
	v_add_f32_e32 v190, v190, v191
	v_add_f32_e32 v192, v192, v193
	v_add_f32_e32 v194, v194, v195
	v_add_f32_e32 v196, v196, v197
	v_add_f32_e32 v198, v198, v199
	v_add_f32_e32 v200, v200, v201
	v_add_f32_e32 v170, v170, v172
	v_add_f32_e32 v174, v174, v176
	v_add_f32_e32 v178, v178, v180
	v_add_f32_e32 v182, v182, v184
	v_add_f32_e32 v186, v186, v188
	v_add_f32_e32 v190, v190, v192
	v_add_f32_e32 v194, v194, v196
	v_add_f32_e32 v198, v198, v200
	v_fmamk_f32 v170, v170, 0x3a800000, v155
	v_fmamk_f32 v174, v174, 0x3a800000, v155
	v_fmamk_f32 v178, v178, 0x3a800000, v155
	v_fmamk_f32 v182, v182, 0x3a800000, v155
	v_fmamk_f32 v186, v186, 0x3a800000, v155
	v_fmamk_f32 v190, v190, 0x3a800000, v155
	v_fmamk_f32 v194, v194, 0x3a800000, v155
	v_fmamk_f32 v198, v198, 0x3a800000, v155
	v_rsq_f32_e32 v170, v170
	v_rsq_f32_e32 v174, v174
	v_rsq_f32_e32 v178, v178
	v_rsq_f32_e32 v182, v182
	v_rsq_f32_e32 v186, v186
	v_rsq_f32_e32 v190, v190
	v_rsq_f32_e32 v194, v194
	v_rsq_f32_e32 v198, v198
	v_pk_add_f32 v[220:221], v[220:221], 1.0 op_sel_hi:[1,0]
	v_pk_add_f32 v[222:223], v[222:223], 1.0 op_sel_hi:[1,0]
	v_pk_add_f32 v[224:225], v[224:225], 1.0 op_sel_hi:[1,0]
	v_pk_add_f32 v[226:227], v[226:227], 1.0 op_sel_hi:[1,0]
	v_pk_add_f32 v[228:229], v[228:229], 1.0 op_sel_hi:[1,0]
	v_pk_add_f32 v[230:231], v[230:231], 1.0 op_sel_hi:[1,0]
	v_pk_add_f32 v[232:233], v[232:233], 1.0 op_sel_hi:[1,0]
	v_pk_add_f32 v[234:235], v[234:235], 1.0 op_sel_hi:[1,0]
	v_pk_mul_f32 v[132:133], v[132:133], v[170:171] op_sel_hi:[1,0]
	v_pk_mul_f32 v[134:135], v[134:135], v[170:171] op_sel_hi:[1,0]
	v_pk_mul_f32 v[128:129], v[128:129], v[170:171] op_sel_hi:[1,0]
	v_pk_mul_f32 v[130:131], v[130:131], v[170:171] op_sel_hi:[1,0]
	v_pk_mul_f32 v[132:133], v[204:205], v[132:133]
	v_pk_mul_f32 v[134:135], v[206:207], v[134:135]
	v_pk_mul_f32 v[128:129], v[208:209], v[128:129]
	v_pk_mul_f32 v[130:131], v[210:211], v[130:131]
	v_pk_fma_f32 v[132:133], v[220:221], v[132:133], v[236:237]
	v_pk_fma_f32 v[134:135], v[222:223], v[134:135], v[238:239]
	v_pk_fma_f32 v[128:129], v[224:225], v[128:129], v[146:147]
	v_pk_fma_f32 v[130:131], v[226:227], v[130:131], v[148:149]
	v_cvt_pk_bf16_f32 v132, v132, v133
	v_cvt_pk_bf16_f32 v133, v134, v135
	v_cvt_pk_bf16_f32 v134, v128, v129
	v_cvt_pk_bf16_f32 v135, v130, v131
	global_store_dwordx4 v144, v[132:135], s[14:15]
	v_pk_mul_f32 v[60:61], v[60:61], v[170:171] op_sel_hi:[1,0]
	v_pk_mul_f32 v[62:63], v[62:63], v[170:171] op_sel_hi:[1,0]
	v_pk_mul_f32 v[56:57], v[56:57], v[170:171] op_sel_hi:[1,0]
	v_pk_mul_f32 v[58:59], v[58:59], v[170:171] op_sel_hi:[1,0]
	v_pk_mul_f32 v[60:61], v[212:213], v[60:61]
	v_pk_mul_f32 v[62:63], v[214:215], v[62:63]
	v_pk_mul_f32 v[56:57], v[216:217], v[56:57]
	v_pk_mul_f32 v[58:59], v[218:219], v[58:59]
	v_pk_fma_f32 v[60:61], v[228:229], v[60:61], v[150:151]
	v_pk_fma_f32 v[62:63], v[230:231], v[62:63], v[152:153]
	v_pk_fma_f32 v[56:57], v[232:233], v[56:57], v[162:163]
	v_pk_fma_f32 v[58:59], v[234:235], v[58:59], v[164:165]
	v_cvt_pk_bf16_f32 v60, v60, v61
	v_cvt_pk_bf16_f32 v61, v62, v63
	v_cvt_pk_bf16_f32 v62, v56, v57
	v_cvt_pk_bf16_f32 v63, v58, v59
	global_store_dwordx4 v144, v[60:63], s[14:15] offset:256
	s_add_u32 s14, s14, 0x8000
	s_addc_u32 s15, s15, 0
	v_pk_mul_f32 v[124:125], v[124:125], v[174:175] op_sel_hi:[1,0]
	v_pk_mul_f32 v[126:127], v[126:127], v[174:175] op_sel_hi:[1,0]
	v_pk_mul_f32 v[120:121], v[120:121], v[174:175] op_sel_hi:[1,0]
	v_pk_mul_f32 v[122:123], v[122:123], v[174:175] op_sel_hi:[1,0]
	v_pk_mul_f32 v[124:125], v[204:205], v[124:125]
	v_pk_mul_f32 v[126:127], v[206:207], v[126:127]
	v_pk_mul_f32 v[120:121], v[208:209], v[120:121]
	v_pk_mul_f32 v[122:123], v[210:211], v[122:123]
	v_pk_fma_f32 v[124:125], v[220:221], v[124:125], v[236:237]
	v_pk_fma_f32 v[126:127], v[222:223], v[126:127], v[238:239]
	v_pk_fma_f32 v[120:121], v[224:225], v[120:121], v[146:147]
	v_pk_fma_f32 v[122:123], v[226:227], v[122:123], v[148:149]
	v_cvt_pk_bf16_f32 v124, v124, v125
	v_cvt_pk_bf16_f32 v125, v126, v127
	v_cvt_pk_bf16_f32 v126, v120, v121
	v_cvt_pk_bf16_f32 v127, v122, v123
	global_store_dwordx4 v144, v[124:127], s[14:15]
	v_pk_mul_f32 v[52:53], v[52:53], v[174:175] op_sel_hi:[1,0]
	v_pk_mul_f32 v[54:55], v[54:55], v[174:175] op_sel_hi:[1,0]
	v_pk_mul_f32 v[48:49], v[48:49], v[174:175] op_sel_hi:[1,0]
	v_pk_mul_f32 v[50:51], v[50:51], v[174:175] op_sel_hi:[1,0]
	v_pk_mul_f32 v[52:53], v[212:213], v[52:53]
	v_pk_mul_f32 v[54:55], v[214:215], v[54:55]
	v_pk_mul_f32 v[48:49], v[216:217], v[48:49]
	v_pk_mul_f32 v[50:51], v[218:219], v[50:51]
	v_pk_fma_f32 v[52:53], v[228:229], v[52:53], v[150:151]
	v_pk_fma_f32 v[54:55], v[230:231], v[54:55], v[152:153]
	v_pk_fma_f32 v[48:49], v[232:233], v[48:49], v[162:163]
	v_pk_fma_f32 v[50:51], v[234:235], v[50:51], v[164:165]
	v_cvt_pk_bf16_f32 v52, v52, v53
	v_cvt_pk_bf16_f32 v53, v54, v55
	v_cvt_pk_bf16_f32 v54, v48, v49
	v_cvt_pk_bf16_f32 v55, v50, v51
	global_store_dwordx4 v144, v[52:55], s[14:15] offset:256
	s_add_u32 s14, s14, 0x8000
	s_addc_u32 s15, s15, 0
	v_pk_mul_f32 v[116:117], v[116:117], v[178:179] op_sel_hi:[1,0]
	v_pk_mul_f32 v[118:119], v[118:119], v[178:179] op_sel_hi:[1,0]
	v_pk_mul_f32 v[112:113], v[112:113], v[178:179] op_sel_hi:[1,0]
	v_pk_mul_f32 v[114:115], v[114:115], v[178:179] op_sel_hi:[1,0]
	v_pk_mul_f32 v[116:117], v[204:205], v[116:117]
	v_pk_mul_f32 v[118:119], v[206:207], v[118:119]
	v_pk_mul_f32 v[112:113], v[208:209], v[112:113]
	v_pk_mul_f32 v[114:115], v[210:211], v[114:115]
	v_pk_fma_f32 v[116:117], v[220:221], v[116:117], v[236:237]
	v_pk_fma_f32 v[118:119], v[222:223], v[118:119], v[238:239]
	v_pk_fma_f32 v[112:113], v[224:225], v[112:113], v[146:147]
	v_pk_fma_f32 v[114:115], v[226:227], v[114:115], v[148:149]
	v_cvt_pk_bf16_f32 v116, v116, v117
	v_cvt_pk_bf16_f32 v117, v118, v119
	v_cvt_pk_bf16_f32 v118, v112, v113
	v_cvt_pk_bf16_f32 v119, v114, v115
	global_store_dwordx4 v144, v[116:119], s[14:15]
	v_pk_mul_f32 v[44:45], v[44:45], v[178:179] op_sel_hi:[1,0]
	v_pk_mul_f32 v[46:47], v[46:47], v[178:179] op_sel_hi:[1,0]
	v_pk_mul_f32 v[40:41], v[40:41], v[178:179] op_sel_hi:[1,0]
	v_pk_mul_f32 v[42:43], v[42:43], v[178:179] op_sel_hi:[1,0]
	v_pk_mul_f32 v[44:45], v[212:213], v[44:45]
	v_pk_mul_f32 v[46:47], v[214:215], v[46:47]
	v_pk_mul_f32 v[40:41], v[216:217], v[40:41]
	v_pk_mul_f32 v[42:43], v[218:219], v[42:43]
	v_pk_fma_f32 v[44:45], v[228:229], v[44:45], v[150:151]
	v_pk_fma_f32 v[46:47], v[230:231], v[46:47], v[152:153]
	v_pk_fma_f32 v[40:41], v[232:233], v[40:41], v[162:163]
	v_pk_fma_f32 v[42:43], v[234:235], v[42:43], v[164:165]
	v_cvt_pk_bf16_f32 v44, v44, v45
	v_cvt_pk_bf16_f32 v45, v46, v47
	v_cvt_pk_bf16_f32 v46, v40, v41
	v_cvt_pk_bf16_f32 v47, v42, v43
	global_store_dwordx4 v144, v[44:47], s[14:15] offset:256
	s_add_u32 s14, s14, 0x8000
	s_addc_u32 s15, s15, 0
	v_pk_mul_f32 v[108:109], v[108:109], v[182:183] op_sel_hi:[1,0]
	v_pk_mul_f32 v[110:111], v[110:111], v[182:183] op_sel_hi:[1,0]
	v_pk_mul_f32 v[104:105], v[104:105], v[182:183] op_sel_hi:[1,0]
	v_pk_mul_f32 v[106:107], v[106:107], v[182:183] op_sel_hi:[1,0]
	v_pk_mul_f32 v[108:109], v[204:205], v[108:109]
	v_pk_mul_f32 v[110:111], v[206:207], v[110:111]
	v_pk_mul_f32 v[104:105], v[208:209], v[104:105]
	v_pk_mul_f32 v[106:107], v[210:211], v[106:107]
	v_pk_fma_f32 v[108:109], v[220:221], v[108:109], v[236:237]
	v_pk_fma_f32 v[110:111], v[222:223], v[110:111], v[238:239]
	v_pk_fma_f32 v[104:105], v[224:225], v[104:105], v[146:147]
	v_pk_fma_f32 v[106:107], v[226:227], v[106:107], v[148:149]
	v_cvt_pk_bf16_f32 v108, v108, v109
	v_cvt_pk_bf16_f32 v109, v110, v111
	v_cvt_pk_bf16_f32 v110, v104, v105
	v_cvt_pk_bf16_f32 v111, v106, v107
	global_store_dwordx4 v144, v[108:111], s[14:15]
	v_pk_mul_f32 v[36:37], v[36:37], v[182:183] op_sel_hi:[1,0]
	v_pk_mul_f32 v[38:39], v[38:39], v[182:183] op_sel_hi:[1,0]
	v_pk_mul_f32 v[32:33], v[32:33], v[182:183] op_sel_hi:[1,0]
	v_pk_mul_f32 v[34:35], v[34:35], v[182:183] op_sel_hi:[1,0]
	v_pk_mul_f32 v[36:37], v[212:213], v[36:37]
	v_pk_mul_f32 v[38:39], v[214:215], v[38:39]
	v_pk_mul_f32 v[32:33], v[216:217], v[32:33]
	v_pk_mul_f32 v[34:35], v[218:219], v[34:35]
	v_pk_fma_f32 v[36:37], v[228:229], v[36:37], v[150:151]
	v_pk_fma_f32 v[38:39], v[230:231], v[38:39], v[152:153]
	v_pk_fma_f32 v[32:33], v[232:233], v[32:33], v[162:163]
	v_pk_fma_f32 v[34:35], v[234:235], v[34:35], v[164:165]
	v_cvt_pk_bf16_f32 v36, v36, v37
	v_cvt_pk_bf16_f32 v37, v38, v39
	v_cvt_pk_bf16_f32 v38, v32, v33
	v_cvt_pk_bf16_f32 v39, v34, v35
	global_store_dwordx4 v144, v[36:39], s[14:15] offset:256
	s_add_u32 s14, s14, 0x28000
	s_addc_u32 s15, s15, 0
	v_pk_mul_f32 v[100:101], v[100:101], v[186:187] op_sel_hi:[1,0]
	v_pk_mul_f32 v[102:103], v[102:103], v[186:187] op_sel_hi:[1,0]
	v_pk_mul_f32 v[96:97], v[96:97], v[186:187] op_sel_hi:[1,0]
	v_pk_mul_f32 v[98:99], v[98:99], v[186:187] op_sel_hi:[1,0]
	v_pk_mul_f32 v[100:101], v[204:205], v[100:101]
	v_pk_mul_f32 v[102:103], v[206:207], v[102:103]
	v_pk_mul_f32 v[96:97], v[208:209], v[96:97]
	v_pk_mul_f32 v[98:99], v[210:211], v[98:99]
	v_pk_fma_f32 v[100:101], v[220:221], v[100:101], v[236:237]
	v_pk_fma_f32 v[102:103], v[222:223], v[102:103], v[238:239]
	v_pk_fma_f32 v[96:97], v[224:225], v[96:97], v[146:147]
	v_pk_fma_f32 v[98:99], v[226:227], v[98:99], v[148:149]
	v_cvt_pk_bf16_f32 v100, v100, v101
	v_cvt_pk_bf16_f32 v101, v102, v103
	v_cvt_pk_bf16_f32 v102, v96, v97
	v_cvt_pk_bf16_f32 v103, v98, v99
	global_store_dwordx4 v144, v[100:103], s[14:15]
	v_pk_mul_f32 v[28:29], v[28:29], v[186:187] op_sel_hi:[1,0]
	v_pk_mul_f32 v[30:31], v[30:31], v[186:187] op_sel_hi:[1,0]
	v_pk_mul_f32 v[24:25], v[24:25], v[186:187] op_sel_hi:[1,0]
	v_pk_mul_f32 v[26:27], v[26:27], v[186:187] op_sel_hi:[1,0]
	v_pk_mul_f32 v[28:29], v[212:213], v[28:29]
	v_pk_mul_f32 v[30:31], v[214:215], v[30:31]
	v_pk_mul_f32 v[24:25], v[216:217], v[24:25]
	v_pk_mul_f32 v[26:27], v[218:219], v[26:27]
	v_pk_fma_f32 v[28:29], v[228:229], v[28:29], v[150:151]
	v_pk_fma_f32 v[30:31], v[230:231], v[30:31], v[152:153]
	v_pk_fma_f32 v[24:25], v[232:233], v[24:25], v[162:163]
	v_pk_fma_f32 v[26:27], v[234:235], v[26:27], v[164:165]
	v_cvt_pk_bf16_f32 v28, v28, v29
	v_cvt_pk_bf16_f32 v29, v30, v31
	v_cvt_pk_bf16_f32 v30, v24, v25
	v_cvt_pk_bf16_f32 v31, v26, v27
	global_store_dwordx4 v144, v[28:31], s[14:15] offset:256
	s_add_u32 s14, s14, 0x8000
	s_addc_u32 s15, s15, 0
	v_pk_mul_f32 v[92:93], v[92:93], v[190:191] op_sel_hi:[1,0]
	v_pk_mul_f32 v[94:95], v[94:95], v[190:191] op_sel_hi:[1,0]
	v_pk_mul_f32 v[88:89], v[88:89], v[190:191] op_sel_hi:[1,0]
	v_pk_mul_f32 v[90:91], v[90:91], v[190:191] op_sel_hi:[1,0]
	v_pk_mul_f32 v[92:93], v[204:205], v[92:93]
	v_pk_mul_f32 v[94:95], v[206:207], v[94:95]
	v_pk_mul_f32 v[88:89], v[208:209], v[88:89]
	v_pk_mul_f32 v[90:91], v[210:211], v[90:91]
	v_pk_fma_f32 v[92:93], v[220:221], v[92:93], v[236:237]
	v_pk_fma_f32 v[94:95], v[222:223], v[94:95], v[238:239]
	v_pk_fma_f32 v[88:89], v[224:225], v[88:89], v[146:147]
	v_pk_fma_f32 v[90:91], v[226:227], v[90:91], v[148:149]
	v_cvt_pk_bf16_f32 v92, v92, v93
	v_cvt_pk_bf16_f32 v93, v94, v95
	v_cvt_pk_bf16_f32 v94, v88, v89
	v_cvt_pk_bf16_f32 v95, v90, v91
	global_store_dwordx4 v144, v[92:95], s[14:15]
	v_pk_mul_f32 v[20:21], v[20:21], v[190:191] op_sel_hi:[1,0]
	v_pk_mul_f32 v[22:23], v[22:23], v[190:191] op_sel_hi:[1,0]
	v_pk_mul_f32 v[16:17], v[16:17], v[190:191] op_sel_hi:[1,0]
	v_pk_mul_f32 v[18:19], v[18:19], v[190:191] op_sel_hi:[1,0]
	v_pk_mul_f32 v[20:21], v[212:213], v[20:21]
	v_pk_mul_f32 v[22:23], v[214:215], v[22:23]
	v_pk_mul_f32 v[16:17], v[216:217], v[16:17]
	v_pk_mul_f32 v[18:19], v[218:219], v[18:19]
	v_pk_fma_f32 v[20:21], v[228:229], v[20:21], v[150:151]
	v_pk_fma_f32 v[22:23], v[230:231], v[22:23], v[152:153]
	v_pk_fma_f32 v[16:17], v[232:233], v[16:17], v[162:163]
	v_pk_fma_f32 v[18:19], v[234:235], v[18:19], v[164:165]
	v_cvt_pk_bf16_f32 v20, v20, v21
	v_cvt_pk_bf16_f32 v21, v22, v23
	v_cvt_pk_bf16_f32 v22, v16, v17
	v_cvt_pk_bf16_f32 v23, v18, v19
	global_store_dwordx4 v144, v[20:23], s[14:15] offset:256
	s_add_u32 s14, s14, 0x8000
	s_addc_u32 s15, s15, 0
	v_pk_mul_f32 v[76:77], v[76:77], v[194:195] op_sel_hi:[1,0]
	v_pk_mul_f32 v[78:79], v[78:79], v[194:195] op_sel_hi:[1,0]
	v_pk_mul_f32 v[72:73], v[72:73], v[194:195] op_sel_hi:[1,0]
	v_pk_mul_f32 v[74:75], v[74:75], v[194:195] op_sel_hi:[1,0]
	v_pk_mul_f32 v[76:77], v[204:205], v[76:77]
	v_pk_mul_f32 v[78:79], v[206:207], v[78:79]
	v_pk_mul_f32 v[72:73], v[208:209], v[72:73]
	v_pk_mul_f32 v[74:75], v[210:211], v[74:75]
	v_pk_fma_f32 v[76:77], v[220:221], v[76:77], v[236:237]
	v_pk_fma_f32 v[78:79], v[222:223], v[78:79], v[238:239]
	v_pk_fma_f32 v[72:73], v[224:225], v[72:73], v[146:147]
	v_pk_fma_f32 v[74:75], v[226:227], v[74:75], v[148:149]
	v_cvt_pk_bf16_f32 v76, v76, v77
	v_cvt_pk_bf16_f32 v77, v78, v79
	v_cvt_pk_bf16_f32 v78, v72, v73
	v_cvt_pk_bf16_f32 v79, v74, v75
	global_store_dwordx4 v144, v[76:79], s[14:15]
	v_pk_mul_f32 v[12:13], v[12:13], v[194:195] op_sel_hi:[1,0]
	v_pk_mul_f32 v[14:15], v[14:15], v[194:195] op_sel_hi:[1,0]
	v_pk_mul_f32 v[8:9], v[8:9], v[194:195] op_sel_hi:[1,0]
	v_pk_mul_f32 v[10:11], v[10:11], v[194:195] op_sel_hi:[1,0]
	v_pk_mul_f32 v[12:13], v[212:213], v[12:13]
	v_pk_mul_f32 v[14:15], v[214:215], v[14:15]
	v_pk_mul_f32 v[8:9], v[216:217], v[8:9]
	v_pk_mul_f32 v[10:11], v[218:219], v[10:11]
	v_pk_fma_f32 v[12:13], v[228:229], v[12:13], v[150:151]
	v_pk_fma_f32 v[14:15], v[230:231], v[14:15], v[152:153]
	v_pk_fma_f32 v[8:9], v[232:233], v[8:9], v[162:163]
	v_pk_fma_f32 v[10:11], v[234:235], v[10:11], v[164:165]
	v_cvt_pk_bf16_f32 v12, v12, v13
	v_cvt_pk_bf16_f32 v13, v14, v15
	v_cvt_pk_bf16_f32 v14, v8, v9
	v_cvt_pk_bf16_f32 v15, v10, v11
	global_store_dwordx4 v144, v[12:15], s[14:15] offset:256
	s_add_u32 s14, s14, 0x8000
	s_addc_u32 s15, s15, 0
	v_pk_mul_f32 v[68:69], v[68:69], v[198:199] op_sel_hi:[1,0]
	v_pk_mul_f32 v[70:71], v[70:71], v[198:199] op_sel_hi:[1,0]
	v_pk_mul_f32 v[64:65], v[64:65], v[198:199] op_sel_hi:[1,0]
	v_pk_mul_f32 v[66:67], v[66:67], v[198:199] op_sel_hi:[1,0]
	v_pk_mul_f32 v[68:69], v[204:205], v[68:69]
	v_pk_mul_f32 v[70:71], v[206:207], v[70:71]
	v_pk_mul_f32 v[64:65], v[208:209], v[64:65]
	v_pk_mul_f32 v[66:67], v[210:211], v[66:67]
	v_pk_fma_f32 v[68:69], v[220:221], v[68:69], v[236:237]
	v_pk_fma_f32 v[70:71], v[222:223], v[70:71], v[238:239]
	v_pk_fma_f32 v[64:65], v[224:225], v[64:65], v[146:147]
	v_pk_fma_f32 v[66:67], v[226:227], v[66:67], v[148:149]
	v_cvt_pk_bf16_f32 v68, v68, v69
	v_cvt_pk_bf16_f32 v69, v70, v71
	v_cvt_pk_bf16_f32 v70, v64, v65
	v_cvt_pk_bf16_f32 v71, v66, v67
	global_store_dwordx4 v144, v[68:71], s[14:15]
	v_pk_mul_f32 v[246:247], v[246:247], v[198:199] op_sel_hi:[1,0]
	v_pk_mul_f32 v[248:249], v[248:249], v[198:199] op_sel_hi:[1,0]
	v_pk_mul_f32 v[242:243], v[242:243], v[198:199] op_sel_hi:[1,0]
	v_pk_mul_f32 v[244:245], v[244:245], v[198:199] op_sel_hi:[1,0]
	v_pk_mul_f32 v[246:247], v[212:213], v[246:247]
	v_pk_mul_f32 v[248:249], v[214:215], v[248:249]
	v_pk_mul_f32 v[242:243], v[216:217], v[242:243]
	v_pk_mul_f32 v[244:245], v[218:219], v[244:245]
	v_pk_fma_f32 v[246:247], v[228:229], v[246:247], v[150:151]
	v_pk_fma_f32 v[248:249], v[230:231], v[248:249], v[152:153]
	v_pk_fma_f32 v[242:243], v[232:233], v[242:243], v[162:163]
	v_pk_fma_f32 v[244:245], v[234:235], v[244:245], v[164:165]
	v_cvt_pk_bf16_f32 v246, v246, v247
	v_cvt_pk_bf16_f32 v247, v248, v249
	v_cvt_pk_bf16_f32 v248, v242, v243
	v_cvt_pk_bf16_f32 v249, v244, v245
	global_store_dwordx4 v144, v[246:249], s[14:15] offset:256

.Lt2_skip_up1:
	v_mov_b32_e32 v128, v154
	v_mul_f32_e32 v130, 0xbfb8aa3b, v121
	v_ashrrev_i32_e32 v129, 2, v128
	v_and_b32_e32 v129, 0xffffffc0, v129
	v_lshl_add_u32 v129, s12, 8, v129
	v_and_or_b32 v132, v128, 15, v129
	v_mul_f32_e32 v129, 0xbfb8aa3b, v120
	v_exp_f32_e32 v129, v129
	v_exp_f32_e32 v130, v130
	v_lshrrev_b32_e32 v131, 1, v128
	s_add_i32 s10, s10, s74
	v_add_f32_e32 v128, 1.0, v129
	v_add_f32_e32 v129, 1.0, v130
	v_rcp_f32_e32 v128, v128
	v_rcp_f32_e32 v129, v129
	v_and_b32_e32 v130, 0x78, v131
	v_lshl_or_b32 v130, s4, 7, v130
	v_readlane_b32 s4, v255, 2
	v_pk_mul_f32 v[120:121], v[120:121], v[128:129]
	v_mul_f32_e32 v128, 0xbfb8aa3b, v122
	v_mul_f32_e32 v129, 0xbfb8aa3b, v123
	v_exp_f32_e32 v128, v128
	v_exp_f32_e32 v129, v129
	v_pk_mul_f32 v[120:121], v[120:121], v[124:125]
	v_readlane_b32 s5, v255, 3
	v_add_f32_e32 v124, 1.0, v128
	v_add_f32_e32 v125, 1.0, v129
	v_mul_f32_e32 v128, 0xbfb8aa3b, v112
	v_mul_f32_e32 v129, 0xbfb8aa3b, v113
	v_rcp_f32_e32 v124, v124
	v_rcp_f32_e32 v125, v125
	v_exp_f32_e32 v128, v128
	v_exp_f32_e32 v129, v129
	v_ashrrev_i32_e32 v131, 31, v130
	v_pk_mul_f32 v[122:123], v[122:123], v[124:125]
	v_add_f32_e32 v124, 1.0, v128
	v_add_f32_e32 v125, 1.0, v129
	v_mul_f32_e32 v128, 0xbfb8aa3b, v114
	v_mul_f32_e32 v129, 0xbfb8aa3b, v115
	v_exp_f32_e32 v128, v128
	v_exp_f32_e32 v129, v129
	v_rcp_f32_e32 v124, v124
	v_rcp_f32_e32 v125, v125
	v_add_f32_e32 v128, 1.0, v128
	v_add_f32_e32 v129, 1.0, v129
	v_rcp_f32_e32 v128, v128
	v_rcp_f32_e32 v129, v129
	v_pk_mul_f32 v[112:113], v[112:113], v[124:125]
	v_pk_mul_f32 v[122:123], v[122:123], v[126:127]
	v_pk_mul_f32 v[112:113], v[112:113], v[116:117]
	v_pk_mul_f32 v[114:115], v[114:115], v[128:129]
	v_cvt_pk_bf16_f32 v116, v120, v121
	v_pk_mul_f32 v[114:115], v[114:115], v[118:119]
	v_cvt_pk_bf16_f32 v118, v112, v113
	v_cvt_pk_bf16_f32 v119, v114, v115
	v_mul_f32_e32 v114, 0xbfb8aa3b, v104
	v_exp_f32_e32 v114, v114
	v_mul_f32_e32 v115, 0xbfb8aa3b, v105
	v_exp_f32_e32 v115, v115
	v_mov_b64_e32 v[112:113], s[4:5]
	v_add_f32_e32 v114, 1.0, v114
	v_rcp_f32_e32 v120, v114
	v_add_f32_e32 v114, 1.0, v115
	v_mad_i64_i32 v[112:113], s[4:5], v132, s33, v[112:113]
	v_rcp_f32_e32 v121, v114
	v_lshlrev_b64 v[114:115], 1, v[130:131]
	v_cvt_pk_bf16_f32 v117, v122, v123
	v_lshl_add_u64 v[112:113], v[112:113], 0, v[114:115]
	global_store_dwordx4 v[112:113], v[116:119], off
	v_pk_mul_f32 v[104:105], v[104:105], v[120:121]
	v_readlane_b32 s4, v253, 51
	v_mul_f32_e32 v116, 0xbfb8aa3b, v106
	v_mul_f32_e32 v117, 0xbfb8aa3b, v107
	v_exp_f32_e32 v116, v116
	v_exp_f32_e32 v117, v117
	v_pk_mul_f32 v[104:105], v[104:105], v[108:109]
	v_readlane_b32 s5, v253, 52
	v_add_f32_e32 v108, 1.0, v116
	v_add_f32_e32 v109, 1.0, v117
	v_mul_f32_e32 v116, 0xbfb8aa3b, v96
	v_mul_f32_e32 v117, 0xbfb8aa3b, v97
	v_rcp_f32_e32 v108, v108
	v_rcp_f32_e32 v109, v109
	v_exp_f32_e32 v116, v116
	v_exp_f32_e32 v117, v117
	s_add_i32 s11, s11, s20
	v_pk_mul_f32 v[106:107], v[106:107], v[108:109]
	v_add_f32_e32 v108, 1.0, v116
	v_add_f32_e32 v109, 1.0, v117
	v_mul_f32_e32 v116, 0xbfb8aa3b, v98
	v_mul_f32_e32 v117, 0xbfb8aa3b, v99
	v_exp_f32_e32 v116, v116
	v_exp_f32_e32 v117, v117
	v_rcp_f32_e32 v108, v108
	v_rcp_f32_e32 v109, v109
	v_add_f32_e32 v116, 1.0, v116
	v_add_f32_e32 v117, 1.0, v117
	v_rcp_f32_e32 v116, v116
	v_rcp_f32_e32 v117, v117
	v_pk_mul_f32 v[96:97], v[96:97], v[108:109]
	v_pk_mul_f32 v[106:107], v[106:107], v[110:111]
	v_pk_mul_f32 v[96:97], v[96:97], v[100:101]
	v_pk_mul_f32 v[98:99], v[98:99], v[116:117]
	v_cvt_pk_bf16_f32 v100, v96, v97
	v_pk_mul_f32 v[102:103], v[98:99], v[102:103]
	v_mul_f32_e32 v96, 0xbfb8aa3b, v88
	v_cvt_pk_bf16_f32 v101, v102, v103
	v_exp_f32_e32 v102, v96
	v_mul_f32_e32 v96, 0xbfb8aa3b, v89
	v_exp_f32_e32 v103, v96
	v_mov_b64_e32 v[96:97], s[4:5]
	v_mad_i64_i32 v[96:97], s[4:5], v132, s33, v[96:97]
	v_cvt_pk_bf16_f32 v98, v104, v105
	v_cvt_pk_bf16_f32 v99, v106, v107
	v_add_f32_e32 v102, 1.0, v102
	v_add_f32_e32 v103, 1.0, v103
	v_lshl_add_u64 v[96:97], v[96:97], 0, v[114:115]
	v_rcp_f32_e32 v102, v102
	v_rcp_f32_e32 v103, v103
	global_store_dwordx4 v[96:97], v[98:101], off
	v_readlane_b32 s4, v253, 53
	v_readlane_b32 s5, v253, 54
	v_mul_f32_e32 v98, 0xbfb8aa3b, v90
	v_mul_f32_e32 v99, 0xbfb8aa3b, v91
	v_exp_f32_e32 v98, v98
	v_exp_f32_e32 v99, v99
	v_pk_mul_f32 v[88:89], v[88:89], v[102:103]
	s_cmpk_lt_i32 s10, 0x580
	v_pk_mul_f32 v[88:89], v[88:89], v[92:93]
	v_add_f32_e32 v92, 1.0, v98
	v_add_f32_e32 v93, 1.0, v99
	v_mul_f32_e32 v98, 0xbfb8aa3b, v80
	v_mul_f32_e32 v99, 0xbfb8aa3b, v81
	v_rcp_f32_e32 v92, v92
	v_rcp_f32_e32 v93, v93
	v_exp_f32_e32 v98, v98
	v_exp_f32_e32 v99, v99
	v_pk_mul_f32 v[90:91], v[90:91], v[92:93]
	v_add_f32_e32 v92, 1.0, v98
	v_add_f32_e32 v93, 1.0, v99
	v_mul_f32_e32 v98, 0xbfb8aa3b, v82
	v_mul_f32_e32 v99, 0xbfb8aa3b, v83
	v_exp_f32_e32 v98, v98
	v_exp_f32_e32 v99, v99
	v_rcp_f32_e32 v92, v92
	v_rcp_f32_e32 v93, v93
	v_add_f32_e32 v98, 1.0, v98
	v_add_f32_e32 v99, 1.0, v99
	v_rcp_f32_e32 v98, v98
	v_rcp_f32_e32 v99, v99
	v_pk_mul_f32 v[80:81], v[80:81], v[92:93]
	v_pk_mul_f32 v[90:91], v[90:91], v[94:95]
	v_pk_mul_f32 v[80:81], v[80:81], v[84:85]
	v_pk_mul_f32 v[82:83], v[82:83], v[98:99]
	v_cvt_pk_bf16_f32 v84, v80, v81
	v_pk_mul_f32 v[86:87], v[82:83], v[86:87]
	v_mul_f32_e32 v80, 0xbfb8aa3b, v72
	v_cvt_pk_bf16_f32 v85, v86, v87
	v_exp_f32_e32 v86, v80
	v_mul_f32_e32 v80, 0xbfb8aa3b, v73
	v_exp_f32_e32 v87, v80
	v_mov_b64_e32 v[80:81], s[4:5]
	v_mad_i64_i32 v[80:81], s[4:5], v132, s33, v[80:81]
	v_cvt_pk_bf16_f32 v82, v88, v89
	v_cvt_pk_bf16_f32 v83, v90, v91
	v_add_f32_e32 v86, 1.0, v86
	v_add_f32_e32 v87, 1.0, v87
	v_lshl_add_u64 v[80:81], v[80:81], 0, v[114:115]
	v_rcp_f32_e32 v86, v86
	v_rcp_f32_e32 v87, v87
	global_store_dwordx4 v[80:81], v[82:85], off
	v_readlane_b32 s4, v253, 55
	v_readlane_b32 s5, v253, 56
	v_mul_f32_e32 v82, 0xbfb8aa3b, v74
	v_mul_f32_e32 v83, 0xbfb8aa3b, v75
	v_exp_f32_e32 v82, v82
	v_exp_f32_e32 v83, v83
	v_pk_mul_f32 v[72:73], v[72:73], v[86:87]
	s_nop 0
	v_pk_mul_f32 v[72:73], v[72:73], v[76:77]
	v_add_f32_e32 v76, 1.0, v82
	v_add_f32_e32 v77, 1.0, v83
	v_mul_f32_e32 v82, 0xbfb8aa3b, v64
	v_mul_f32_e32 v83, 0xbfb8aa3b, v65
	v_rcp_f32_e32 v76, v76
	v_rcp_f32_e32 v77, v77
	v_exp_f32_e32 v82, v82
	v_exp_f32_e32 v83, v83
	v_pk_mul_f32 v[74:75], v[74:75], v[76:77]
	v_add_f32_e32 v76, 1.0, v82
	v_add_f32_e32 v77, 1.0, v83
	v_mul_f32_e32 v82, 0xbfb8aa3b, v66
	v_mul_f32_e32 v83, 0xbfb8aa3b, v67
	v_exp_f32_e32 v82, v82
	v_exp_f32_e32 v83, v83
	v_rcp_f32_e32 v76, v76
	v_rcp_f32_e32 v77, v77
	v_add_f32_e32 v82, 1.0, v82
	v_add_f32_e32 v83, 1.0, v83
	v_rcp_f32_e32 v82, v82
	v_rcp_f32_e32 v83, v83
	v_pk_mul_f32 v[64:65], v[64:65], v[76:77]
	v_pk_mul_f32 v[74:75], v[74:75], v[78:79]
	v_pk_mul_f32 v[64:65], v[64:65], v[68:69]
	v_pk_mul_f32 v[66:67], v[66:67], v[82:83]
	v_cvt_pk_bf16_f32 v68, v64, v65
	v_pk_mul_f32 v[70:71], v[66:67], v[70:71]
	v_mul_f32_e32 v64, 0xbfb8aa3b, v60
	v_cvt_pk_bf16_f32 v69, v70, v71
	v_exp_f32_e32 v70, v64
	v_mul_f32_e32 v64, 0xbfb8aa3b, v61
	v_exp_f32_e32 v71, v64
	v_mov_b64_e32 v[64:65], s[4:5]
	v_mad_i64_i32 v[64:65], s[4:5], v132, s33, v[64:65]
	v_cvt_pk_bf16_f32 v66, v72, v73
	v_cvt_pk_bf16_f32 v67, v74, v75
	v_add_f32_e32 v70, 1.0, v70
	v_add_f32_e32 v71, 1.0, v71
	v_lshl_add_u64 v[64:65], v[64:65], 0, v[114:115]
	v_rcp_f32_e32 v70, v70
	v_rcp_f32_e32 v71, v71
	global_store_dwordx4 v[64:65], v[66:69], off
	s_mov_b32 s4, 0xb0000
	v_pk_mul_f32 v[60:61], v[60:61], v[70:71]
	v_mul_f32_e32 v66, 0xbfb8aa3b, v62
	v_mul_f32_e32 v67, 0xbfb8aa3b, v63
	v_exp_f32_e32 v66, v66
	v_exp_f32_e32 v67, v67
	v_pk_mul_f32 v[56:57], v[60:61], v[56:57]
	v_add_f32_e32 v60, 1.0, v66
	v_add_f32_e32 v61, 1.0, v67
	v_mul_f32_e32 v66, 0xbfb8aa3b, v48
	v_mul_f32_e32 v67, 0xbfb8aa3b, v49
	v_rcp_f32_e32 v60, v60
	v_rcp_f32_e32 v61, v61
	v_exp_f32_e32 v66, v66
	v_exp_f32_e32 v67, v67
	v_pk_mul_f32 v[60:61], v[62:63], v[60:61]
	v_add_f32_e32 v62, 1.0, v66
	v_add_f32_e32 v63, 1.0, v67
	v_mul_f32_e32 v66, 0xbfb8aa3b, v50
	v_mul_f32_e32 v67, 0xbfb8aa3b, v51
	v_exp_f32_e32 v66, v66
	v_exp_f32_e32 v67, v67
	v_rcp_f32_e32 v62, v62
	v_rcp_f32_e32 v63, v63
	v_add_f32_e32 v66, 1.0, v66
	v_add_f32_e32 v67, 1.0, v67
	v_rcp_f32_e32 v66, v66
	v_rcp_f32_e32 v67, v67
	v_pk_mul_f32 v[48:49], v[48:49], v[62:63]
	v_pk_mul_f32 v[58:59], v[60:61], v[58:59]
	v_pk_mul_f32 v[52:53], v[48:49], v[52:53]
	v_pk_mul_f32 v[48:49], v[50:51], v[66:67]
	v_mul_f32_e32 v51, 0xbfb8aa3b, v44
	v_cvt_pk_bf16_f32 v50, v52, v53
	v_exp_f32_e32 v52, v51
	v_mul_f32_e32 v51, 0xbfb8aa3b, v45
	v_exp_f32_e32 v53, v51
	v_pk_mul_f32 v[54:55], v[48:49], v[54:55]
	v_cvt_pk_bf16_f32 v48, v56, v57
	v_cvt_pk_bf16_f32 v51, v54, v55
	v_add_co_u32_e32 v54, vcc, s4, v112
	v_cvt_pk_bf16_f32 v49, v58, v59
	v_add_f32_e32 v52, 1.0, v52
	v_add_f32_e32 v53, 1.0, v53
	v_addc_co_u32_e32 v55, vcc, 0, v113, vcc
	v_rcp_f32_e32 v52, v52
	v_rcp_f32_e32 v53, v53
	global_store_dwordx4 v[54:55], v[48:51], off
	v_pk_mul_f32 v[44:45], v[44:45], v[52:53]
	s_nop 0
	v_mul_f32_e32 v48, 0xbfb8aa3b, v46
	v_mul_f32_e32 v49, 0xbfb8aa3b, v47
	v_exp_f32_e32 v48, v48
	v_exp_f32_e32 v49, v49
	v_pk_mul_f32 v[40:41], v[44:45], v[40:41]
	v_add_f32_e32 v44, 1.0, v48
	v_add_f32_e32 v45, 1.0, v49
	v_mul_f32_e32 v48, 0xbfb8aa3b, v32
	v_mul_f32_e32 v49, 0xbfb8aa3b, v33
	v_rcp_f32_e32 v44, v44
	v_rcp_f32_e32 v45, v45
	v_exp_f32_e32 v48, v48
	v_exp_f32_e32 v49, v49
	v_pk_mul_f32 v[44:45], v[46:47], v[44:45]
	v_add_f32_e32 v46, 1.0, v48
	v_add_f32_e32 v47, 1.0, v49
	v_mul_f32_e32 v48, 0xbfb8aa3b, v34
	v_mul_f32_e32 v49, 0xbfb8aa3b, v35
	v_exp_f32_e32 v48, v48
	v_exp_f32_e32 v49, v49
	v_rcp_f32_e32 v46, v46
	v_rcp_f32_e32 v47, v47
	v_add_f32_e32 v48, 1.0, v48
	v_add_f32_e32 v49, 1.0, v49
	v_rcp_f32_e32 v48, v48
	v_rcp_f32_e32 v49, v49
	v_pk_mul_f32 v[32:33], v[32:33], v[46:47]
	v_pk_mul_f32 v[42:43], v[44:45], v[42:43]
	v_pk_mul_f32 v[36:37], v[32:33], v[36:37]
	v_pk_mul_f32 v[32:33], v[34:35], v[48:49]
	v_mul_f32_e32 v35, 0xbfb8aa3b, v28
	v_cvt_pk_bf16_f32 v34, v36, v37
	v_exp_f32_e32 v36, v35
	v_mul_f32_e32 v35, 0xbfb8aa3b, v29
	v_exp_f32_e32 v37, v35
	v_pk_mul_f32 v[38:39], v[32:33], v[38:39]
	v_cvt_pk_bf16_f32 v32, v40, v41
	v_cvt_pk_bf16_f32 v35, v38, v39
	v_add_co_u32_e32 v38, vcc, s4, v96
	v_cvt_pk_bf16_f32 v33, v42, v43
	v_add_f32_e32 v36, 1.0, v36
	v_add_f32_e32 v37, 1.0, v37
	v_addc_co_u32_e32 v39, vcc, 0, v97, vcc
	v_rcp_f32_e32 v36, v36
	v_rcp_f32_e32 v37, v37
	global_store_dwordx4 v[38:39], v[32:35], off
	v_pk_mul_f32 v[28:29], v[28:29], v[36:37]
	s_nop 0
	v_mul_f32_e32 v32, 0xbfb8aa3b, v30
	v_mul_f32_e32 v33, 0xbfb8aa3b, v31
	v_exp_f32_e32 v32, v32
	v_exp_f32_e32 v33, v33
	v_pk_mul_f32 v[24:25], v[28:29], v[24:25]
	v_add_f32_e32 v28, 1.0, v32
	v_add_f32_e32 v29, 1.0, v33
	v_mul_f32_e32 v32, 0xbfb8aa3b, v16
	v_mul_f32_e32 v33, 0xbfb8aa3b, v17
	v_rcp_f32_e32 v28, v28
	v_rcp_f32_e32 v29, v29
	v_exp_f32_e32 v32, v32
	v_exp_f32_e32 v33, v33
	v_pk_mul_f32 v[28:29], v[30:31], v[28:29]
	v_add_f32_e32 v30, 1.0, v32
	v_add_f32_e32 v31, 1.0, v33
	v_mul_f32_e32 v32, 0xbfb8aa3b, v18
	v_mul_f32_e32 v33, 0xbfb8aa3b, v19
	v_exp_f32_e32 v32, v32
	v_exp_f32_e32 v33, v33
	v_rcp_f32_e32 v30, v30
	v_rcp_f32_e32 v31, v31
	v_add_f32_e32 v32, 1.0, v32
	v_add_f32_e32 v33, 1.0, v33
	v_rcp_f32_e32 v32, v32
	v_rcp_f32_e32 v33, v33
	v_pk_mul_f32 v[16:17], v[16:17], v[30:31]
	v_pk_mul_f32 v[26:27], v[28:29], v[26:27]
	v_pk_mul_f32 v[20:21], v[16:17], v[20:21]
	v_pk_mul_f32 v[16:17], v[18:19], v[32:33]
	v_mul_f32_e32 v19, 0xbfb8aa3b, v12
	v_cvt_pk_bf16_f32 v18, v20, v21
	v_exp_f32_e32 v20, v19
	v_mul_f32_e32 v19, 0xbfb8aa3b, v13
	v_exp_f32_e32 v21, v19
	v_pk_mul_f32 v[22:23], v[16:17], v[22:23]
	v_cvt_pk_bf16_f32 v16, v24, v25
	v_cvt_pk_bf16_f32 v19, v22, v23
	v_add_co_u32_e32 v22, vcc, s4, v80
	v_cvt_pk_bf16_f32 v17, v26, v27
	v_add_f32_e32 v20, 1.0, v20
	v_add_f32_e32 v21, 1.0, v21
	v_addc_co_u32_e32 v23, vcc, 0, v81, vcc
	v_rcp_f32_e32 v20, v20
	v_rcp_f32_e32 v21, v21
	global_store_dwordx4 v[22:23], v[16:19], off
	v_pk_mul_f32 v[12:13], v[12:13], v[20:21]
	s_nop 0
	v_mul_f32_e32 v16, 0xbfb8aa3b, v14
	v_mul_f32_e32 v17, 0xbfb8aa3b, v15
	v_exp_f32_e32 v16, v16
	v_exp_f32_e32 v17, v17
	v_pk_mul_f32 v[8:9], v[12:13], v[8:9]
	v_add_f32_e32 v12, 1.0, v16
	v_add_f32_e32 v13, 1.0, v17
	v_mul_f32_e32 v16, 0xbfb8aa3b, v0
	v_mul_f32_e32 v17, 0xbfb8aa3b, v1
	v_rcp_f32_e32 v12, v12
	v_rcp_f32_e32 v13, v13
	v_exp_f32_e32 v16, v16
	v_exp_f32_e32 v17, v17
	v_pk_mul_f32 v[12:13], v[14:15], v[12:13]
	v_add_f32_e32 v14, 1.0, v16
	v_add_f32_e32 v15, 1.0, v17
	v_mul_f32_e32 v16, 0xbfb8aa3b, v2
	v_mul_f32_e32 v17, 0xbfb8aa3b, v3
	v_exp_f32_e32 v16, v16
	v_exp_f32_e32 v17, v17
	v_rcp_f32_e32 v14, v14
	v_rcp_f32_e32 v15, v15
	v_add_f32_e32 v16, 1.0, v16
	v_add_f32_e32 v17, 1.0, v17
	v_rcp_f32_e32 v16, v16
	v_rcp_f32_e32 v17, v17
	v_pk_mul_f32 v[0:1], v[0:1], v[14:15]
	v_pk_mul_f32 v[10:11], v[12:13], v[10:11]
	v_pk_mul_f32 v[4:5], v[0:1], v[4:5]
	v_pk_mul_f32 v[0:1], v[2:3], v[16:17]
	v_cvt_pk_bf16_f32 v2, v4, v5
	v_pk_mul_f32 v[6:7], v[0:1], v[6:7]
	v_add_co_u32_e32 v4, vcc, 0xb0000, v64
	v_cvt_pk_bf16_f32 v0, v8, v9
	v_cvt_pk_bf16_f32 v1, v10, v11
	v_cvt_pk_bf16_f32 v3, v6, v7
	v_addc_co_u32_e32 v5, vcc, 0, v65, vcc
	global_store_dwordx4 v[4:5], v[0:3], off
	s_cbranch_scc0 .LBB0_117
	s_branch .LP2_up1

.LBB0_149:
	s_or_b64 exec, exec, s[4:5]
	v_mov_b32_e32 v72, v154
	s_lshr_b32 s5, s12, 3
	v_and_b32_e32 v136, 15, v72
	v_lshrrev_b32_e32 v73, 1, v72
	v_ashrrev_i32_e32 v72, 2, v72
	s_lshl_b32 s4, s14, 8
	s_mul_i32 s5, s5, 0x9000
	v_and_b32_e32 v152, 0xffffffc0, v72
	s_add_u32 s12, s9, s5
	v_ashrrev_i32_e32 v153, 31, v152
	s_mov_b32 s5, s52
	v_and_b32_e32 v73, 0x78, v73
	v_lshl_add_u64 v[140:141], v[152:153], 0, s[4:5]
	v_lshl_or_b32 v146, s13, 8, v73
	v_or_b32_e32 v140, v140, v136
	v_ashrrev_i32_e32 v147, 31, v146
	v_lshlrev_b64 v[144:145], 10, v[140:141]
	s_addc_u32 s13, s10, 0
	v_lshl_add_u64 v[140:141], v[144:145], 0, v[146:147]
	v_lshl_add_u64 v[148:149], v[146:147], 2, s[12:13]
	v_lshlrev_b64 v[140:141], 2, v[140:141]
	s_nop 1
	v_readfirstlane_b32 s38, v140
	v_readfirstlane_b32 s39, v141
	s_nop 1
	v_subrev_u32_e32 v139, s38, v140
	s_add_u32 s40, s0, s38
	s_addc_u32 s41, s1, s39
	s_add_u32 s42, s70, s38
	s_addc_u32 s43, s71, s39
	s_mov_b64 s[44:45], s[40:41]
	s_mov_b64 s[46:47], s[42:43]
	global_load_dwordx4 v[234:237], v[148:149], off
	global_load_dwordx4 v[238:241], v[148:149], off offset:16
	global_load_dwordx4 v[242:245], v[148:149], off offset:512
	global_load_dwordx4 v[246:249], v[148:149], off offset:528
	global_load_dwordx4 v[178:181], v139, s[40:41]
	global_load_dwordx4 v[182:185], v139, s[40:41] offset:16
	s_add_u32 s40, s40, 0x10000
	s_addc_u32 s41, s41, 0
	global_load_dwordx4 v[186:189], v139, s[40:41]
	global_load_dwordx4 v[190:193], v139, s[40:41] offset:16
	s_add_u32 s40, s40, 0x10000
	s_addc_u32 s41, s41, 0
	global_load_dwordx4 v[194:197], v139, s[40:41]
	global_load_dwordx4 v[198:201], v139, s[40:41] offset:16
	s_add_u32 s40, s40, 0x10000
	s_addc_u32 s41, s41, 0
	global_load_dwordx4 v[202:205], v139, s[40:41]
	global_load_dwordx4 v[206:209], v139, s[40:41] offset:16
	s_add_u32 s40, s40, 0x50000
	s_addc_u32 s41, s41, 0
	global_load_dwordx4 v[210:213], v139, s[40:41]
	global_load_dwordx4 v[214:217], v139, s[40:41] offset:16
	s_add_u32 s40, s40, 0x10000
	s_addc_u32 s41, s41, 0
	global_load_dwordx4 v[218:221], v139, s[40:41]
	global_load_dwordx4 v[222:225], v139, s[40:41] offset:16
	s_add_u32 s40, s40, 0x10000
	s_addc_u32 s41, s41, 0
	global_load_dwordx4 v[226:229], v139, s[40:41]
	global_load_dwordx4 v[230:233], v139, s[40:41] offset:16
	s_add_u32 s40, s40, 0x10000
	s_addc_u32 s41, s41, 0
	s_waitcnt vmcnt(12)
	v_pk_mul_f32 v[132:133], v[132:133], v[234:235]
	v_pk_mul_f32 v[134:135], v[134:135], v[236:237]
	v_pk_mul_f32 v[128:129], v[128:129], v[238:239]
	v_pk_mul_f32 v[130:131], v[130:131], v[240:241]
	v_pk_fma_f32 v[132:133], v[132:133], 0.5, v[178:179] op_sel_hi:[1,0,1]
	v_pk_fma_f32 v[134:135], v[134:135], 0.5, v[180:181] op_sel_hi:[1,0,1]
	v_pk_fma_f32 v[128:129], v[128:129], 0.5, v[182:183] op_sel_hi:[1,0,1]
	v_pk_fma_f32 v[130:131], v[130:131], 0.5, v[184:185] op_sel_hi:[1,0,1]
	global_store_dwordx4 v139, v[132:135], s[42:43]
	global_store_dwordx4 v139, v[128:131], s[42:43] offset:16
	s_add_u32 s42, s42, 0x10000
	s_addc_u32 s43, s43, 0
	global_load_dwordx4 v[178:181], v139, s[40:41]
	global_load_dwordx4 v[182:185], v139, s[40:41] offset:16
	s_mov_b64 s[40:41], s[44:45]
	s_waitcnt vmcnt(14)
	v_pk_mul_f32 v[124:125], v[124:125], v[234:235]
	v_pk_mul_f32 v[126:127], v[126:127], v[236:237]
	v_pk_mul_f32 v[120:121], v[120:121], v[238:239]
	v_pk_mul_f32 v[122:123], v[122:123], v[240:241]
	v_pk_fma_f32 v[124:125], v[124:125], 0.5, v[186:187] op_sel_hi:[1,0,1]
	v_pk_fma_f32 v[126:127], v[126:127], 0.5, v[188:189] op_sel_hi:[1,0,1]
	v_pk_fma_f32 v[120:121], v[120:121], 0.5, v[190:191] op_sel_hi:[1,0,1]
	v_pk_fma_f32 v[122:123], v[122:123], 0.5, v[192:193] op_sel_hi:[1,0,1]
	global_store_dwordx4 v139, v[124:127], s[42:43]
	global_store_dwordx4 v139, v[120:123], s[42:43] offset:16
	s_add_u32 s42, s42, 0x10000
	s_addc_u32 s43, s43, 0
	global_load_dwordx4 v[186:189], v139, s[40:41] offset:512
	global_load_dwordx4 v[190:193], v139, s[40:41] offset:528
	s_add_u32 s40, s40, 0x10000
	s_addc_u32 s41, s41, 0
	s_waitcnt vmcnt(16)
	v_pk_mul_f32 v[116:117], v[116:117], v[234:235]
	v_pk_mul_f32 v[118:119], v[118:119], v[236:237]
	v_pk_mul_f32 v[112:113], v[112:113], v[238:239]
	v_pk_mul_f32 v[114:115], v[114:115], v[240:241]
	v_pk_fma_f32 v[116:117], v[116:117], 0.5, v[194:195] op_sel_hi:[1,0,1]
	v_pk_fma_f32 v[118:119], v[118:119], 0.5, v[196:197] op_sel_hi:[1,0,1]
	v_pk_fma_f32 v[112:113], v[112:113], 0.5, v[198:199] op_sel_hi:[1,0,1]
	v_pk_fma_f32 v[114:115], v[114:115], 0.5, v[200:201] op_sel_hi:[1,0,1]
	global_store_dwordx4 v139, v[116:119], s[42:43]
	global_store_dwordx4 v139, v[112:115], s[42:43] offset:16
	s_add_u32 s42, s42, 0x10000
	s_addc_u32 s43, s43, 0
	global_load_dwordx4 v[194:197], v139, s[40:41] offset:512
	global_load_dwordx4 v[198:201], v139, s[40:41] offset:528
	s_add_u32 s40, s40, 0x10000
	s_addc_u32 s41, s41, 0
	s_waitcnt vmcnt(18)
	v_pk_mul_f32 v[108:109], v[108:109], v[234:235]
	v_pk_mul_f32 v[110:111], v[110:111], v[236:237]
	v_pk_mul_f32 v[104:105], v[104:105], v[238:239]
	v_pk_mul_f32 v[106:107], v[106:107], v[240:241]
	v_pk_fma_f32 v[108:109], v[108:109], 0.5, v[202:203] op_sel_hi:[1,0,1]
	v_pk_fma_f32 v[110:111], v[110:111], 0.5, v[204:205] op_sel_hi:[1,0,1]
	v_pk_fma_f32 v[104:105], v[104:105], 0.5, v[206:207] op_sel_hi:[1,0,1]
	v_pk_fma_f32 v[106:107], v[106:107], 0.5, v[208:209] op_sel_hi:[1,0,1]
	global_store_dwordx4 v139, v[108:111], s[42:43]
	global_store_dwordx4 v139, v[104:107], s[42:43] offset:16
	s_add_u32 s42, s42, 0x50000
	s_addc_u32 s43, s43, 0
	global_load_dwordx4 v[202:205], v139, s[40:41] offset:512
	global_load_dwordx4 v[206:209], v139, s[40:41] offset:528
	s_add_u32 s40, s40, 0x10000
	s_addc_u32 s41, s41, 0
	s_waitcnt vmcnt(20)
	v_pk_mul_f32 v[100:101], v[100:101], v[234:235]
	v_pk_mul_f32 v[102:103], v[102:103], v[236:237]
	v_pk_mul_f32 v[96:97], v[96:97], v[238:239]
	v_pk_mul_f32 v[98:99], v[98:99], v[240:241]
	v_pk_fma_f32 v[100:101], v[100:101], 0.5, v[210:211] op_sel_hi:[1,0,1]
	v_pk_fma_f32 v[102:103], v[102:103], 0.5, v[212:213] op_sel_hi:[1,0,1]
	v_pk_fma_f32 v[96:97], v[96:97], 0.5, v[214:215] op_sel_hi:[1,0,1]
	v_pk_fma_f32 v[98:99], v[98:99], 0.5, v[216:217] op_sel_hi:[1,0,1]
	global_store_dwordx4 v139, v[100:103], s[42:43]
	global_store_dwordx4 v139, v[96:99], s[42:43] offset:16
	s_add_u32 s42, s42, 0x10000
	s_addc_u32 s43, s43, 0
	global_load_dwordx4 v[210:213], v139, s[40:41] offset:512
	global_load_dwordx4 v[214:217], v139, s[40:41] offset:528
	s_add_u32 s40, s40, 0x50000
	s_addc_u32 s41, s41, 0
	s_waitcnt vmcnt(22)
	v_pk_mul_f32 v[92:93], v[92:93], v[234:235]
	v_pk_mul_f32 v[94:95], v[94:95], v[236:237]
	v_pk_mul_f32 v[88:89], v[88:89], v[238:239]
	v_pk_mul_f32 v[90:91], v[90:91], v[240:241]
	v_pk_fma_f32 v[92:93], v[92:93], 0.5, v[218:219] op_sel_hi:[1,0,1]
	v_pk_fma_f32 v[94:95], v[94:95], 0.5, v[220:221] op_sel_hi:[1,0,1]
	v_pk_fma_f32 v[88:89], v[88:89], 0.5, v[222:223] op_sel_hi:[1,0,1]
	v_pk_fma_f32 v[90:91], v[90:91], 0.5, v[224:225] op_sel_hi:[1,0,1]
	global_store_dwordx4 v139, v[92:95], s[42:43]
	global_store_dwordx4 v139, v[88:91], s[42:43] offset:16
	s_add_u32 s42, s42, 0x10000
	s_addc_u32 s43, s43, 0
	global_load_dwordx4 v[218:221], v139, s[40:41] offset:512
	global_load_dwordx4 v[222:225], v139, s[40:41] offset:528
	s_add_u32 s40, s40, 0x10000
	s_addc_u32 s41, s41, 0
	s_waitcnt vmcnt(24)
	v_pk_mul_f32 v[84:85], v[84:85], v[234:235]
	v_pk_mul_f32 v[86:87], v[86:87], v[236:237]
	v_pk_mul_f32 v[80:81], v[80:81], v[238:239]
	v_pk_mul_f32 v[82:83], v[82:83], v[240:241]
	v_pk_fma_f32 v[84:85], v[84:85], 0.5, v[226:227] op_sel_hi:[1,0,1]
	v_pk_fma_f32 v[86:87], v[86:87], 0.5, v[228:229] op_sel_hi:[1,0,1]
	v_pk_fma_f32 v[80:81], v[80:81], 0.5, v[230:231] op_sel_hi:[1,0,1]
	v_pk_fma_f32 v[82:83], v[82:83], 0.5, v[232:233] op_sel_hi:[1,0,1]
	global_store_dwordx4 v139, v[84:87], s[42:43]
	global_store_dwordx4 v139, v[80:83], s[42:43] offset:16
	s_add_u32 s42, s42, 0x10000
	s_addc_u32 s43, s43, 0
	global_load_dwordx4 v[226:229], v139, s[40:41] offset:512
	global_load_dwordx4 v[230:233], v139, s[40:41] offset:528
	s_add_u32 s40, s40, 0x10000
	s_addc_u32 s41, s41, 0
	s_waitcnt vmcnt(24)
	v_pk_mul_f32 v[68:69], v[68:69], v[234:235]
	v_pk_mul_f32 v[70:71], v[70:71], v[236:237]
	v_pk_mul_f32 v[64:65], v[64:65], v[238:239]
	v_pk_mul_f32 v[66:67], v[66:67], v[240:241]
	v_pk_fma_f32 v[68:69], v[68:69], 0.5, v[178:179] op_sel_hi:[1,0,1]
	v_pk_fma_f32 v[70:71], v[70:71], 0.5, v[180:181] op_sel_hi:[1,0,1]
	v_pk_fma_f32 v[64:65], v[64:65], 0.5, v[182:183] op_sel_hi:[1,0,1]
	v_pk_fma_f32 v[66:67], v[66:67], 0.5, v[184:185] op_sel_hi:[1,0,1]
	global_store_dwordx4 v139, v[68:71], s[42:43]
	global_store_dwordx4 v139, v[64:67], s[42:43] offset:16
	s_mov_b64 s[42:43], s[46:47]
	global_load_dwordx4 v[178:181], v139, s[40:41] offset:512
	global_load_dwordx4 v[182:185], v139, s[40:41] offset:528
	s_add_u32 s40, s40, 0x10000
	s_addc_u32 s41, s41, 0
	s_waitcnt vmcnt(24)
	v_pk_mul_f32 v[60:61], v[60:61], v[242:243]
	v_pk_mul_f32 v[62:63], v[62:63], v[244:245]
	v_pk_mul_f32 v[56:57], v[56:57], v[246:247]
	v_pk_mul_f32 v[58:59], v[58:59], v[248:249]
	v_pk_fma_f32 v[60:61], v[60:61], 0.5, v[186:187] op_sel_hi:[1,0,1]
	v_pk_fma_f32 v[62:63], v[62:63], 0.5, v[188:189] op_sel_hi:[1,0,1]
	v_pk_fma_f32 v[56:57], v[56:57], 0.5, v[190:191] op_sel_hi:[1,0,1]
	v_pk_fma_f32 v[58:59], v[58:59], 0.5, v[192:193] op_sel_hi:[1,0,1]
	global_store_dwordx4 v139, v[60:63], s[42:43] offset:512
	global_store_dwordx4 v139, v[56:59], s[42:43] offset:528
	s_add_u32 s42, s42, 0x10000
	s_addc_u32 s43, s43, 0
	global_load_dwordx4 v[186:189], v139, s[40:41] offset:512
	global_load_dwordx4 v[190:193], v139, s[40:41] offset:528
	s_waitcnt vmcnt(24)
	v_pk_mul_f32 v[52:53], v[52:53], v[242:243]
	v_pk_mul_f32 v[54:55], v[54:55], v[244:245]
	v_pk_mul_f32 v[48:49], v[48:49], v[246:247]
	v_pk_mul_f32 v[50:51], v[50:51], v[248:249]
	v_pk_fma_f32 v[52:53], v[52:53], 0.5, v[194:195] op_sel_hi:[1,0,1]
	v_pk_fma_f32 v[54:55], v[54:55], 0.5, v[196:197] op_sel_hi:[1,0,1]
	v_pk_fma_f32 v[48:49], v[48:49], 0.5, v[198:199] op_sel_hi:[1,0,1]
	v_pk_fma_f32 v[50:51], v[50:51], 0.5, v[200:201] op_sel_hi:[1,0,1]
	global_store_dwordx4 v139, v[52:55], s[42:43] offset:512
	global_store_dwordx4 v139, v[48:51], s[42:43] offset:528
	s_add_u32 s42, s42, 0x10000
	s_addc_u32 s43, s43, 0
	s_waitcnt vmcnt(22)
	v_pk_mul_f32 v[44:45], v[44:45], v[242:243]
	v_pk_mul_f32 v[46:47], v[46:47], v[244:245]
	v_pk_mul_f32 v[40:41], v[40:41], v[246:247]
	v_pk_mul_f32 v[42:43], v[42:43], v[248:249]
	v_pk_fma_f32 v[44:45], v[44:45], 0.5, v[202:203] op_sel_hi:[1,0,1]
	v_pk_fma_f32 v[46:47], v[46:47], 0.5, v[204:205] op_sel_hi:[1,0,1]
	v_pk_fma_f32 v[40:41], v[40:41], 0.5, v[206:207] op_sel_hi:[1,0,1]
	v_pk_fma_f32 v[42:43], v[42:43], 0.5, v[208:209] op_sel_hi:[1,0,1]
	global_store_dwordx4 v139, v[44:47], s[42:43] offset:512
	global_store_dwordx4 v139, v[40:43], s[42:43] offset:528
	s_add_u32 s42, s42, 0x10000
	s_addc_u32 s43, s43, 0
	s_waitcnt vmcnt(20)
	v_pk_mul_f32 v[32:33], v[32:33], v[242:243]
	v_pk_mul_f32 v[34:35], v[34:35], v[244:245]
	v_pk_mul_f32 v[24:25], v[24:25], v[246:247]
	v_pk_mul_f32 v[26:27], v[26:27], v[248:249]
	v_pk_fma_f32 v[32:33], v[32:33], 0.5, v[210:211] op_sel_hi:[1,0,1]
	v_pk_fma_f32 v[34:35], v[34:35], 0.5, v[212:213] op_sel_hi:[1,0,1]
	v_pk_fma_f32 v[24:25], v[24:25], 0.5, v[214:215] op_sel_hi:[1,0,1]
	v_pk_fma_f32 v[26:27], v[26:27], 0.5, v[216:217] op_sel_hi:[1,0,1]
	global_store_dwordx4 v139, v[32:35], s[42:43] offset:512
	global_store_dwordx4 v139, v[24:27], s[42:43] offset:528
	s_add_u32 s42, s42, 0x50000
	s_addc_u32 s43, s43, 0
	s_waitcnt vmcnt(18)
	v_pk_mul_f32 v[36:37], v[36:37], v[242:243]
	v_pk_mul_f32 v[38:39], v[38:39], v[244:245]
	v_pk_mul_f32 v[28:29], v[28:29], v[246:247]
	v_pk_mul_f32 v[30:31], v[30:31], v[248:249]
	v_pk_fma_f32 v[36:37], v[36:37], 0.5, v[218:219] op_sel_hi:[1,0,1]
	v_pk_fma_f32 v[38:39], v[38:39], 0.5, v[220:221] op_sel_hi:[1,0,1]
	v_pk_fma_f32 v[28:29], v[28:29], 0.5, v[222:223] op_sel_hi:[1,0,1]
	v_pk_fma_f32 v[30:31], v[30:31], 0.5, v[224:225] op_sel_hi:[1,0,1]
	global_store_dwordx4 v139, v[36:39], s[42:43] offset:512
	global_store_dwordx4 v139, v[28:31], s[42:43] offset:528
	s_add_u32 s42, s42, 0x10000
	s_addc_u32 s43, s43, 0
	s_waitcnt vmcnt(16)
	v_pk_mul_f32 v[20:21], v[20:21], v[242:243]
	v_pk_mul_f32 v[22:23], v[22:23], v[244:245]
	v_pk_mul_f32 v[16:17], v[16:17], v[246:247]
	v_pk_mul_f32 v[18:19], v[18:19], v[248:249]
	v_pk_fma_f32 v[20:21], v[20:21], 0.5, v[226:227] op_sel_hi:[1,0,1]
	v_pk_fma_f32 v[22:23], v[22:23], 0.5, v[228:229] op_sel_hi:[1,0,1]
	v_pk_fma_f32 v[16:17], v[16:17], 0.5, v[230:231] op_sel_hi:[1,0,1]
	v_pk_fma_f32 v[18:19], v[18:19], 0.5, v[232:233] op_sel_hi:[1,0,1]
	global_store_dwordx4 v139, v[20:23], s[42:43] offset:512
	global_store_dwordx4 v139, v[16:19], s[42:43] offset:528
	s_add_u32 s42, s42, 0x10000
	s_addc_u32 s43, s43, 0
	s_waitcnt vmcnt(14)
	v_pk_mul_f32 v[12:13], v[12:13], v[242:243]
	v_pk_mul_f32 v[14:15], v[14:15], v[244:245]
	v_pk_mul_f32 v[8:9], v[8:9], v[246:247]
	v_pk_mul_f32 v[10:11], v[10:11], v[248:249]
	v_pk_fma_f32 v[12:13], v[12:13], 0.5, v[178:179] op_sel_hi:[1,0,1]
	v_pk_fma_f32 v[14:15], v[14:15], 0.5, v[180:181] op_sel_hi:[1,0,1]
	v_pk_fma_f32 v[8:9], v[8:9], 0.5, v[182:183] op_sel_hi:[1,0,1]
	v_pk_fma_f32 v[10:11], v[10:11], 0.5, v[184:185] op_sel_hi:[1,0,1]
	global_store_dwordx4 v139, v[12:15], s[42:43] offset:512
	global_store_dwordx4 v139, v[8:11], s[42:43] offset:528
	s_add_u32 s42, s42, 0x10000
	s_addc_u32 s43, s43, 0
	s_waitcnt vmcnt(12)
	v_pk_mul_f32 v[4:5], v[4:5], v[242:243]
	v_pk_mul_f32 v[6:7], v[6:7], v[244:245]
	v_pk_mul_f32 v[0:1], v[0:1], v[246:247]
	v_pk_mul_f32 v[2:3], v[2:3], v[248:249]
	v_pk_fma_f32 v[4:5], v[4:5], 0.5, v[186:187] op_sel_hi:[1,0,1]
	v_pk_fma_f32 v[6:7], v[6:7], 0.5, v[188:189] op_sel_hi:[1,0,1]
	v_pk_fma_f32 v[0:1], v[0:1], 0.5, v[190:191] op_sel_hi:[1,0,1]
	v_pk_fma_f32 v[2:3], v[2:3], 0.5, v[192:193] op_sel_hi:[1,0,1]
	global_store_dwordx4 v139, v[4:7], s[42:43] offset:512
	global_store_dwordx4 v139, v[0:3], s[42:43] offset:528
	v_pk_mul_f32 v[200:201], v[132:133], v[132:133]
	v_pk_mul_f32 v[202:203], v[124:125], v[124:125]
	v_pk_mul_f32 v[204:205], v[116:117], v[116:117]
	v_pk_mul_f32 v[206:207], v[108:109], v[108:109]
	v_pk_mul_f32 v[208:209], v[100:101], v[100:101]
	v_pk_mul_f32 v[210:211], v[92:93], v[92:93]
	v_pk_mul_f32 v[212:213], v[84:85], v[84:85]
	v_pk_mul_f32 v[214:215], v[68:69], v[68:69]
	v_pk_fma_f32 v[200:201], v[134:135], v[134:135], v[200:201]
	v_pk_fma_f32 v[202:203], v[126:127], v[126:127], v[202:203]
	v_pk_fma_f32 v[204:205], v[118:119], v[118:119], v[204:205]
	v_pk_fma_f32 v[206:207], v[110:111], v[110:111], v[206:207]
	v_pk_fma_f32 v[208:209], v[102:103], v[102:103], v[208:209]
	v_pk_fma_f32 v[210:211], v[94:95], v[94:95], v[210:211]
	v_pk_fma_f32 v[212:213], v[86:87], v[86:87], v[212:213]
	v_pk_fma_f32 v[214:215], v[70:71], v[70:71], v[214:215]
	v_pk_fma_f32 v[200:201], v[128:129], v[128:129], v[200:201]
	v_pk_fma_f32 v[202:203], v[120:121], v[120:121], v[202:203]
	v_pk_fma_f32 v[204:205], v[112:113], v[112:113], v[204:205]
	v_pk_fma_f32 v[206:207], v[104:105], v[104:105], v[206:207]
	v_pk_fma_f32 v[208:209], v[96:97], v[96:97], v[208:209]
	v_pk_fma_f32 v[210:211], v[88:89], v[88:89], v[210:211]
	v_pk_fma_f32 v[212:213], v[80:81], v[80:81], v[212:213]
	v_pk_fma_f32 v[214:215], v[64:65], v[64:65], v[214:215]
	v_pk_fma_f32 v[200:201], v[130:131], v[130:131], v[200:201]
	v_pk_fma_f32 v[202:203], v[122:123], v[122:123], v[202:203]
	v_pk_fma_f32 v[204:205], v[114:115], v[114:115], v[204:205]
	v_pk_fma_f32 v[206:207], v[106:107], v[106:107], v[206:207]
	v_pk_fma_f32 v[208:209], v[98:99], v[98:99], v[208:209]
	v_pk_fma_f32 v[210:211], v[90:91], v[90:91], v[210:211]
	v_pk_fma_f32 v[212:213], v[82:83], v[82:83], v[212:213]
	v_pk_fma_f32 v[214:215], v[66:67], v[66:67], v[214:215]
	v_pk_fma_f32 v[200:201], v[60:61], v[60:61], v[200:201]
	v_pk_fma_f32 v[202:203], v[52:53], v[52:53], v[202:203]
	v_pk_fma_f32 v[204:205], v[44:45], v[44:45], v[204:205]
	v_pk_fma_f32 v[206:207], v[32:33], v[32:33], v[206:207]
	v_pk_fma_f32 v[208:209], v[36:37], v[36:37], v[208:209]
	v_pk_fma_f32 v[210:211], v[20:21], v[20:21], v[210:211]
	v_pk_fma_f32 v[212:213], v[12:13], v[12:13], v[212:213]
	v_pk_fma_f32 v[214:215], v[4:5], v[4:5], v[214:215]
	v_pk_fma_f32 v[200:201], v[62:63], v[62:63], v[200:201]
	v_pk_fma_f32 v[202:203], v[54:55], v[54:55], v[202:203]
	v_pk_fma_f32 v[204:205], v[46:47], v[46:47], v[204:205]
	v_pk_fma_f32 v[206:207], v[34:35], v[34:35], v[206:207]
	v_pk_fma_f32 v[208:209], v[38:39], v[38:39], v[208:209]
	v_pk_fma_f32 v[210:211], v[22:23], v[22:23], v[210:211]
	v_pk_fma_f32 v[212:213], v[14:15], v[14:15], v[212:213]
	v_pk_fma_f32 v[214:215], v[6:7], v[6:7], v[214:215]
	v_pk_fma_f32 v[200:201], v[56:57], v[56:57], v[200:201]
	v_pk_fma_f32 v[202:203], v[48:49], v[48:49], v[202:203]
	v_pk_fma_f32 v[204:205], v[40:41], v[40:41], v[204:205]
	v_pk_fma_f32 v[206:207], v[24:25], v[24:25], v[206:207]
	v_pk_fma_f32 v[208:209], v[28:29], v[28:29], v[208:209]
	v_pk_fma_f32 v[210:211], v[16:17], v[16:17], v[210:211]
	v_pk_fma_f32 v[212:213], v[8:9], v[8:9], v[212:213]
	v_pk_fma_f32 v[214:215], v[0:1], v[0:1], v[214:215]
	v_pk_fma_f32 v[200:201], v[58:59], v[58:59], v[200:201]
	v_pk_fma_f32 v[202:203], v[50:51], v[50:51], v[202:203]
	v_pk_fma_f32 v[204:205], v[42:43], v[42:43], v[204:205]
	v_pk_fma_f32 v[206:207], v[26:27], v[26:27], v[206:207]
	v_pk_fma_f32 v[208:209], v[30:31], v[30:31], v[208:209]
	v_pk_fma_f32 v[210:211], v[18:19], v[18:19], v[210:211]
	v_pk_fma_f32 v[212:213], v[10:11], v[10:11], v[212:213]
	v_pk_fma_f32 v[214:215], v[2:3], v[2:3], v[214:215]
	v_add_f32_e32 v216, v200, v201
	v_add_f32_e32 v217, v202, v203
	v_add_f32_e32 v218, v204, v205
	v_add_f32_e32 v219, v206, v207
	v_add_f32_e32 v220, v208, v209
	v_add_f32_e32 v221, v210, v211
	v_add_f32_e32 v222, v212, v213
	v_add_f32_e32 v223, v214, v215
	v_and_b32_e32 v224, 63, v154
	v_xor_b32_e32 v225, 32, v224
	v_xor_b32_e32 v224, 16, v224
	v_lshlrev_b32_e32 v224, 2, v224
	v_lshlrev_b32_e32 v225, 2, v225
	ds_bpermute_b32 v226, v224, v216
	ds_bpermute_b32 v227, v224, v217
	ds_bpermute_b32 v228, v224, v218
	ds_bpermute_b32 v229, v224, v219
	ds_bpermute_b32 v230, v224, v220
	ds_bpermute_b32 v231, v224, v221
	ds_bpermute_b32 v232, v224, v222
	ds_bpermute_b32 v233, v224, v223
	s_waitcnt lgkmcnt(0)
	v_add_f32_e32 v216, v216, v226
	v_add_f32_e32 v217, v217, v227
	v_add_f32_e32 v218, v218, v228
	v_add_f32_e32 v219, v219, v229
	v_add_f32_e32 v220, v220, v230
	v_add_f32_e32 v221, v221, v231
	v_add_f32_e32 v222, v222, v232
	v_add_f32_e32 v223, v223, v233
	ds_bpermute_b32 v226, v225, v216
	ds_bpermute_b32 v227, v225, v217
	ds_bpermute_b32 v228, v225, v218
	ds_bpermute_b32 v229, v225, v219
	ds_bpermute_b32 v230, v225, v220
	ds_bpermute_b32 v231, v225, v221
	ds_bpermute_b32 v232, v225, v222
	ds_bpermute_b32 v233, v225, v223
	s_waitcnt lgkmcnt(0)
	v_add_f32_e32 v216, v216, v226
	v_add_f32_e32 v217, v217, v227
	v_add_f32_e32 v218, v218, v228
	v_add_f32_e32 v219, v219, v229
	v_add_f32_e32 v220, v220, v230
	v_add_f32_e32 v221, v221, v231
	v_add_f32_e32 v222, v222, v232
	v_add_f32_e32 v223, v223, v233
	v_bfe_u32 v234, v154, 6, 2
	v_lshlrev_b32_e32 v234, 8, v234
	v_lshrrev_b32_e32 v235, 8, v154
	v_lshl_add_u32 v234, v235, 6, v234
	v_and_b32_e32 v235, 15, v154
	v_add_u32_e32 v234, v234, v235
	v_lshlrev_b32_e32 v234, 2, v234
	ds_write_b32 v234, v216 offset:0
	ds_write_b32 v234, v217 offset:64
	ds_write_b32 v234, v218 offset:128
	ds_write_b32 v234, v219 offset:192
	ds_write_b32 v234, v220 offset:512
	ds_write_b32 v234, v221 offset:576
	ds_write_b32 v234, v222 offset:640
	ds_write_b32 v234, v223 offset:704
	s_waitcnt lgkmcnt(0)
	s_barrier
	v_cmp_gt_u32_e32 vcc, 0x100, v154
	s_and_saveexec_b64 s[48:49], vcc
	v_lshlrev_b32_e32 v235, 2, v154
	ds_read_b32 v236, v235
	ds_read_b32 v237, v235 offset:1024
	ds_read_b32 v238, v235 offset:2048
	ds_read_b32 v239, v235 offset:3072
	s_lshl_b32 s50, s6, 3
	s_and_b32 s50, s50, 56
	s_bfe_u32 s51, s6, 0x30003
	s_or_b32 s50, s50, s51
	s_lshl_b32 s50, s50, 2
	s_lshr_b32 s51, s6, 6
	s_or_b32 s50, s50, s51
	s_lshl_b32 s50, s50, 10
	s_add_u32 s50, s50, s72
	s_addc_u32 s51, s73, 0
	s_add_u32 s50, s50, 0x19500000
	s_addc_u32 s51, s51, 0
	s_waitcnt lgkmcnt(0)
	v_add_f32_e32 v236, v236, v237
	v_add_f32_e32 v238, v238, v239
	v_add_f32_e32 v236, v236, v238
	global_store_dword v235, v236, s[50:51]
	s_mov_b64 exec, s[48:49]
	s_mov_b32 s92, s6
	v_mov_b64_e32 v[242:243], v[0:1]
	v_mov_b64_e32 v[244:245], v[2:3]
	v_mov_b64_e32 v[246:247], v[4:5]
	v_mov_b64_e32 v[248:249], v[6:7]
	s_add_i32 s6, s6, s74
	s_add_i32 s11, s11, s20
	s_cmpk_lt_i32 s6, 0x100
	s_cbranch_scc0 .LBB0_156
.LBB0_150:
	s_lshl_b32 s4, s6, 3
	v_mov_b32_e32 v139, v154
	s_and_b32 s12, s4, 56
	s_bfe_u32 s4, s6, 0x30003
	s_or_b32 s14, s12, s4
	v_ashrrev_i32_e32 v5, 6, v139
	v_ashrrev_i32_e32 v4, 3, v139
	v_lshrrev_b32_e32 v1, 2, v139
	v_bfi_b32 v9, -16, v4, v1
	v_lshlrev_b32_e32 v1, 5, v5
	s_ashr_i32 s13, s6, 6
	s_mul_i32 s4, s14, 0x160000
	v_readlane_b32 s26, v255, 2
	v_lshrrev_b32_e32 v0, 4, v139
	v_and_b32_e32 v2, 32, v1
	v_and_b32_e32 v1, 3, v139
	v_readlane_b32 s27, v255, 3
	s_add_u32 s4, s26, s4
	v_bitop3_b32 v0, v0, v1, 2 bitop3:0x6c
	s_addc_u32 s5, s27, 0
	s_mul_i32 s23, s13, 0x160000
	v_lshlrev_b32_e32 v3, 3, v0
	s_mul_hi_i32 s15, s13, 0x160000
	s_add_u32 s26, s7, s23
	v_or_b32_e32 v10, v3, v2
	v_mov_b64_e32 v[0:1], s[4:5]
	s_addc_u32 s27, s8, s15
	v_and_b32_e32 v6, 15, v139
	v_mad_i64_i32 v[0:1], s[4:5], v9, s33, v[0:1]
	v_lshlrev_b32_e32 v136, 1, v10
	v_lshlrev_b32_e32 v10, 2, v139
	v_ashrrev_i32_e32 v8, 8, v139
	v_and_b32_e32 v7, 48, v139
	v_lshl_add_u64 v[128:129], v[0:1], 0, v[136:137]
	v_mov_b64_e32 v[0:1], s[26:27]
	v_lshlrev_b32_e32 v6, 6, v6
	v_and_b32_e32 v10, 32, v10
	v_mad_i64_i32 v[0:1], s[4:5], v9, s33, v[0:1]
	v_or_b32_e32 v9, v6, v7
	v_bitop3_b32 v6, v6, v10, v7 bitop3:0x36
	v_lshlrev_b32_e32 v7, 13, v8
	v_lshlrev_b32_e32 v5, 12, v5
	v_lshlrev_b32_e32 v146, 4, v139
	v_bitop3_b32 v134, v9, v7, v10 bitop3:0xde
	v_and_or_b32 v5, v5, s75, v6
	v_add_u32_e32 v147, 0x10000, v146
	v_add_u32_e32 v144, 0x10000, v134
	v_or_b32_e32 v135, 0x8000, v5
	v_or_b32_e32 v145, 0x18000, v5
	v_lshl_add_u64 v[0:1], v[0:1], 0, v[136:137]
	v_add_u32_e32 v148, 0x8000, v146
	v_add_u32_e32 v149, 0xa000, v146
	v_readfirstlane_b32 s4, v148
	s_waitcnt vmcnt(0)
	s_mov_b32 m0, s4
	s_mov_b64 s[26:27], 0x58000
	v_readfirstlane_b32 s4, v149
	global_load_lds_dwordx4 v[0:1], off
	v_lshl_add_u64 v[6:7], v[0:1], 0, s[26:27]
	s_mov_b32 m0, s4
	v_readfirstlane_b32 s4, v146
	v_add_u32_e32 v150, 0x2000, v146
	global_load_lds_dwordx4 v[6:7], off
	s_mov_b32 m0, s4
	v_readfirstlane_b32 s4, v150
	v_add_u32_e32 v151, 0xc000, v146
	global_load_lds_dwordx4 v[128:129], off
	v_lshl_add_u64 v[6:7], v[128:129], 0, s[26:27]
	s_mov_b32 m0, s4
	s_mov_b64 s[26:27], 0xb0000
	v_readfirstlane_b32 s4, v151
	v_add_u32_e32 v152, 0xe000, v146
	global_load_lds_dwordx4 v[6:7], off
	v_lshl_add_u64 v[6:7], v[0:1], 0, s[26:27]
	s_mov_b32 m0, s4
	s_mov_b64 s[36:37], 0x108000
	v_readfirstlane_b32 s4, v152
	v_add_u32_e32 v153, 0x4000, v146
	global_load_lds_dwordx4 v[6:7], off
	v_lshl_add_u64 v[6:7], v[0:1], 0, s[36:37]
	s_mov_b32 m0, s4
	v_readfirstlane_b32 s4, v153
	v_add_u32_e32 v170, 0x6000, v146
	global_load_lds_dwordx4 v[6:7], off
	v_lshl_add_u64 v[6:7], v[128:129], 0, s[26:27]
	s_mov_b32 m0, s4
	v_readfirstlane_b32 s4, v170
	global_load_lds_dwordx4 v[6:7], off
	v_lshl_add_u64 v[6:7], v[128:129], 0, s[36:37]
	s_mov_b32 m0, s4
	v_cmp_eq_u32_e32 vcc, 1, v8
	global_load_lds_dwordx4 v[6:7], off
	s_and_saveexec_b64 s[4:5], vcc
	s_cbranch_execz .LBB0_152
	s_barrier
.LBB0_152:
	s_or_b64 exec, exec, s[4:5]
	s_lshr_b32 s4, s6, 3
	s_bfe_u32 s5, s11, 0x30003
	s_and_b32 s4, s4, 7
	s_mul_i32 s5, s5, 0x580000
	s_mul_i32 s4, s4, 0xb0000
	v_add_u32_e32 v171, 0x8000, v147
	s_add_i32 s5, s5, s4
	s_mov_b64 s[36:37], 0x80
	v_readfirstlane_b32 s4, v171
	v_add_u32_e32 v172, 0xa000, v147
	v_and_b32_e32 v6, -16, v4
	v_lshl_add_u64 v[4:5], v[0:1], 0, s[36:37]
	s_mov_b32 m0, s4
	s_mov_b64 s[38:39], 0x58080
	v_readfirstlane_b32 s4, v172
	s_waitcnt vmcnt(4)
	s_barrier
	global_load_lds_dwordx4 v[4:5], off
	v_lshl_add_u64 v[4:5], v[0:1], 0, s[38:39]
	s_mov_b32 m0, s4
	v_readfirstlane_b32 s4, v147
	v_add_u32_e32 v173, 0x2000, v147
	global_load_lds_dwordx4 v[4:5], off
	v_lshl_add_u64 v[4:5], v[128:129], 0, s[36:37]
	s_mov_b32 m0, s4
	v_readfirstlane_b32 s4, v173
	s_lshl_b32 s26, s5, 1
	global_load_lds_dwordx4 v[4:5], off
	v_lshl_add_u64 v[4:5], v[128:129], 0, s[38:39]
	s_mov_b32 m0, s4
	s_mov_b64 s[4:5], 0xb0080
	v_add_u32_e32 v174, 0xc000, v147
	global_load_lds_dwordx4 v[4:5], off
	v_lshl_add_u64 v[4:5], v[0:1], 0, s[4:5]
	v_readfirstlane_b32 s4, v174
	s_mov_b32 m0, s4
	s_mov_b64 s[4:5], 0x108080
	v_add_u32_e32 v175, 0xe000, v147
	v_lshl_add_u64 v[0:1], v[0:1], 0, s[4:5]
	v_readfirstlane_b32 s4, v175
	global_load_lds_dwordx4 v[4:5], off
	s_mov_b32 m0, s4
	s_add_u32 s4, s21, s23
	global_load_lds_dwordx4 v[0:1], off
	v_bfe_u32 v7, v139, 2, 4
	s_addc_u32 s5, s22, s15
	v_add_lshl_u32 v136, v2, v3, 1
	v_add_u32_e32 v2, v6, v7
	v_mov_b64_e32 v[0:1], s[4:5]
	v_mad_i64_i32 v[130:131], s[4:5], v2, s33, v[0:1]
	s_add_u32 s4, s72, s26
	s_addc_u32 s5, s73, 0
	s_waitcnt vmcnt(6)
	v_mov_b64_e32 v[0:1], s[4:5]
	v_mad_i64_i32 v[132:133], s[4:5], v2, s33, v[0:1]
	v_mov_b32_e32 v0, 0
	s_mov_b32 s4, -2
	v_mov_b32_e32 v1, v0
	v_mov_b32_e32 v2, v0
	v_mov_b32_e32 v3, v0
	v_mov_b32_e32 v4, v0
	v_mov_b32_e32 v5, v0
	v_mov_b32_e32 v6, v0
	v_mov_b32_e32 v7, v0
	v_mov_b32_e32 v12, v0
	v_mov_b32_e32 v13, v0
	v_mov_b32_e32 v14, v0
	v_mov_b32_e32 v15, v0
	v_mov_b32_e32 v20, v0
	v_mov_b32_e32 v21, v0
	v_mov_b32_e32 v22, v0
	v_mov_b32_e32 v23, v0
	v_mov_b32_e32 v8, v0
	v_mov_b32_e32 v9, v0
	v_mov_b32_e32 v10, v0
	v_mov_b32_e32 v11, v0
	v_mov_b32_e32 v16, v0
	v_mov_b32_e32 v17, v0
	v_mov_b32_e32 v18, v0
	v_mov_b32_e32 v19, v0
	v_mov_b32_e32 v28, v0
	v_mov_b32_e32 v29, v0
	v_mov_b32_e32 v30, v0
	v_mov_b32_e32 v31, v0
	v_mov_b32_e32 v36, v0
	v_mov_b32_e32 v37, v0
	v_mov_b32_e32 v38, v0
	v_mov_b32_e32 v39, v0
	v_mov_b32_e32 v24, v0
	v_mov_b32_e32 v25, v0
	v_mov_b32_e32 v26, v0
	v_mov_b32_e32 v27, v0
	v_mov_b32_e32 v32, v0
	v_mov_b32_e32 v33, v0
	v_mov_b32_e32 v34, v0
	v_mov_b32_e32 v35, v0
	v_mov_b32_e32 v44, v0
	v_mov_b32_e32 v45, v0
	v_mov_b32_e32 v46, v0
	v_mov_b32_e32 v47, v0
	v_mov_b32_e32 v52, v0
	v_mov_b32_e32 v53, v0
	v_mov_b32_e32 v54, v0
	v_mov_b32_e32 v55, v0
	v_mov_b32_e32 v40, v0
	v_mov_b32_e32 v41, v0
	v_mov_b32_e32 v42, v0
	v_mov_b32_e32 v43, v0
	v_mov_b32_e32 v48, v0
	v_mov_b32_e32 v49, v0
	v_mov_b32_e32 v50, v0
	v_mov_b32_e32 v51, v0
	v_mov_b32_e32 v56, v0
	v_mov_b32_e32 v57, v0
	v_mov_b32_e32 v58, v0
	v_mov_b32_e32 v59, v0
	v_mov_b32_e32 v60, v0
	v_mov_b32_e32 v61, v0
	v_mov_b32_e32 v62, v0
	v_mov_b32_e32 v63, v0
	v_mov_b32_e32 v64, v0
	v_mov_b32_e32 v65, v0
	v_mov_b32_e32 v66, v0
	v_mov_b32_e32 v67, v0
	v_mov_b32_e32 v68, v0
	v_mov_b32_e32 v69, v0
	v_mov_b32_e32 v70, v0
	v_mov_b32_e32 v71, v0
	v_mov_b32_e32 v80, v0
	v_mov_b32_e32 v81, v0
	v_mov_b32_e32 v82, v0
	v_mov_b32_e32 v83, v0
	v_mov_b32_e32 v84, v0
	v_mov_b32_e32 v85, v0
	v_mov_b32_e32 v86, v0
	v_mov_b32_e32 v87, v0
	v_mov_b32_e32 v72, v0
	v_mov_b32_e32 v73, v0
	v_mov_b32_e32 v74, v0
	v_mov_b32_e32 v75, v0
	v_mov_b32_e32 v76, v0
	v_mov_b32_e32 v77, v0
	v_mov_b32_e32 v78, v0
	v_mov_b32_e32 v79, v0
	v_mov_b32_e32 v96, v0
	v_mov_b32_e32 v97, v0
	v_mov_b32_e32 v98, v0
	v_mov_b32_e32 v99, v0
	v_mov_b32_e32 v100, v0
	v_mov_b32_e32 v101, v0
	v_mov_b32_e32 v102, v0
	v_mov_b32_e32 v103, v0
	v_mov_b32_e32 v88, v0
	v_mov_b32_e32 v89, v0
	v_mov_b32_e32 v90, v0
	v_mov_b32_e32 v91, v0
	v_mov_b32_e32 v92, v0
	v_mov_b32_e32 v93, v0
	v_mov_b32_e32 v94, v0
	v_mov_b32_e32 v95, v0
	v_mov_b32_e32 v112, v0
	v_mov_b32_e32 v113, v0
	v_mov_b32_e32 v114, v0
	v_mov_b32_e32 v115, v0
	v_mov_b32_e32 v116, v0
	v_mov_b32_e32 v117, v0
	v_mov_b32_e32 v118, v0
	v_mov_b32_e32 v119, v0
	v_mov_b32_e32 v104, v0
	v_mov_b32_e32 v105, v0
	v_mov_b32_e32 v106, v0
	v_mov_b32_e32 v107, v0
	v_mov_b32_e32 v108, v0
	v_mov_b32_e32 v109, v0
	v_mov_b32_e32 v110, v0
	v_mov_b32_e32 v111, v0
	v_mov_b32_e32 v120, v0
	v_mov_b32_e32 v121, v0
	v_mov_b32_e32 v122, v0
	v_mov_b32_e32 v123, v0
	v_mov_b32_e32 v124, v0
	v_mov_b32_e32 v125, v0
	v_mov_b32_e32 v126, v0
	v_mov_b32_e32 v127, v0
	s_mov_b64 s[36:37], 0x1f5b0080
	s_mov_b64 s[38:39], 0x1f558180
	s_barrier

.LBB0_186:
	s_or_b64 exec, exec, s[0:1]
	v_mov_b32_e32 v0, v154
	v_mov_b32_e32 v2, v154
	s_waitcnt lgkmcnt(0)
	s_barrier
	s_lshl_b32 s0, s92, 3
	s_and_b32 s0, s0, 56
	s_bfe_u32 s1, s92, 0x30003
	s_or_b32 s0, s0, s1
	s_lshr_b32 s1, s92, 6
	v_lshrrev_b32_e32 v140, 8, v154
	v_and_b32_e32 v141, 15, v154
	v_lshl_add_u32 v140, v140, 6, v141
	v_bfe_u32 v141, v154, 6, 2
	v_bfe_u32 v142, v154, 4, 2
	v_lshlrev_b32_e32 v141, 5, v141
	v_lshl_add_u32 v141, v142, 3, v141
	v_lshlrev_b32_e32 v142, 2, v140
	v_lshlrev_b32_e32 v143, 2, v141
	v_lshlrev_b32_e32 v144, 11, v140
	v_lshl_add_u32 v144, v141, 1, v144
	s_lshl_b32 s6, s0, 12
	s_add_u32 s6, s6, s72
	s_addc_u32 s7, s73, 0
	s_add_u32 s6, s6, 0x19500000
	s_addc_u32 s7, s7, 0
	global_load_dword v170, v142, s[6:7] offset:0
	global_load_dword v171, v142, s[6:7] offset:1024
	global_load_dword v172, v142, s[6:7] offset:2048
	global_load_dword v173, v142, s[6:7] offset:3072
	global_load_dword v174, v142, s[6:7] offset:64
	global_load_dword v175, v142, s[6:7] offset:1088
	global_load_dword v176, v142, s[6:7] offset:2112
	global_load_dword v177, v142, s[6:7] offset:3136
	global_load_dword v178, v142, s[6:7] offset:128
	global_load_dword v179, v142, s[6:7] offset:1152
	global_load_dword v180, v142, s[6:7] offset:2176
	global_load_dword v181, v142, s[6:7] offset:3200
	global_load_dword v182, v142, s[6:7] offset:192
	global_load_dword v183, v142, s[6:7] offset:1216
	global_load_dword v184, v142, s[6:7] offset:2240
	global_load_dword v185, v142, s[6:7] offset:3264
	global_load_dword v186, v142, s[6:7] offset:512
	global_load_dword v187, v142, s[6:7] offset:1536
	global_load_dword v188, v142, s[6:7] offset:2560
	global_load_dword v189, v142, s[6:7] offset:3584
	global_load_dword v190, v142, s[6:7] offset:576
	global_load_dword v191, v142, s[6:7] offset:1600
	global_load_dword v192, v142, s[6:7] offset:2624
	global_load_dword v193, v142, s[6:7] offset:3648
	global_load_dword v194, v142, s[6:7] offset:640
	global_load_dword v195, v142, s[6:7] offset:1664
	global_load_dword v196, v142, s[6:7] offset:2688
	global_load_dword v197, v142, s[6:7] offset:3712
	global_load_dword v198, v142, s[6:7] offset:704
	global_load_dword v199, v142, s[6:7] offset:1728
	global_load_dword v200, v142, s[6:7] offset:2752
	global_load_dword v201, v142, s[6:7] offset:3776
	v_readlane_b32 s4, v254, 57
	s_lshl_b32 s4, s4, 12
	s_lshl_b32 s1, s1, 10
	v_readlane_b32 s8, v253, 25
	v_readlane_b32 s9, v253, 26
	s_add_u32 s8, s8, s4
	s_addc_u32 s9, s9, 0
	s_add_u32 s8, s8, s1
	s_addc_u32 s9, s9, 0
	s_lshr_b32 s4, s0, 3
	s_mul_i32 s4, s4, 0x9000
	s_add_u32 s4, s4, s1
	v_readlane_b32 s10, v254, 55
	v_readlane_b32 s11, v254, 56
	s_add_u32 s10, s10, s4
	s_addc_u32 s11, s11, 0
	s_add_u32 s12, s10, 0x3000
	s_addc_u32 s13, s11, 0
	s_add_u32 s10, s10, 0x4000
	s_addc_u32 s11, s11, 0
	global_load_dwordx4 v[204:207], v143, s[8:9]
	global_load_dwordx4 v[220:223], v143, s[10:11]
	global_load_dwordx4 v[236:239], v143, s[12:13]
	global_load_dwordx4 v[208:211], v143, s[8:9] offset:16
	global_load_dwordx4 v[224:227], v143, s[10:11] offset:16
	global_load_dwordx4 v[146:149], v143, s[12:13] offset:16
	global_load_dwordx4 v[212:215], v143, s[8:9] offset:512
	global_load_dwordx4 v[228:231], v143, s[10:11] offset:512
	global_load_dwordx4 v[150:153], v143, s[12:13] offset:512
	global_load_dwordx4 v[216:219], v143, s[8:9] offset:528
	global_load_dwordx4 v[232:235], v143, s[10:11] offset:528
	global_load_dwordx4 v[162:165], v143, s[12:13] offset:528
	v_readlane_b32 s14, v253, 47
	v_readlane_b32 s15, v253, 48
	s_lshl_b32 s4, s0, 19
	s_add_u32 s14, s14, s4
	s_addc_u32 s15, s15, 0
	s_lshr_b32 s4, s1, 1
	s_add_u32 s14, s14, s4
	s_addc_u32 s15, s15, 0
	s_waitcnt vmcnt(0)
	v_add_f32_e32 v170, v170, v171
	v_add_f32_e32 v172, v172, v173
	v_add_f32_e32 v174, v174, v175
	v_add_f32_e32 v176, v176, v177
	v_add_f32_e32 v178, v178, v179
	v_add_f32_e32 v180, v180, v181
	v_add_f32_e32 v182, v182, v183
	v_add_f32_e32 v184, v184, v185
	v_add_f32_e32 v186, v186, v187
	v_add_f32_e32 v188, v188, v189
	v_add_f32_e32 v190, v190, v191
	v_add_f32_e32 v192, v192, v193
	v_add_f32_e32 v194, v194, v195
	v_add_f32_e32 v196, v196, v197
	v_add_f32_e32 v198, v198, v199
	v_add_f32_e32 v200, v200, v201
	v_add_f32_e32 v170, v170, v172
	v_add_f32_e32 v174, v174, v176
	v_add_f32_e32 v178, v178, v180
	v_add_f32_e32 v182, v182, v184
	v_add_f32_e32 v186, v186, v188
	v_add_f32_e32 v190, v190, v192
	v_add_f32_e32 v194, v194, v196
	v_add_f32_e32 v198, v198, v200
	v_fmamk_f32 v170, v170, 0x3a800000, v155
	v_fmamk_f32 v174, v174, 0x3a800000, v155
	v_fmamk_f32 v178, v178, 0x3a800000, v155
	v_fmamk_f32 v182, v182, 0x3a800000, v155
	v_fmamk_f32 v186, v186, 0x3a800000, v155
	v_fmamk_f32 v190, v190, 0x3a800000, v155
	v_fmamk_f32 v194, v194, 0x3a800000, v155
	v_fmamk_f32 v198, v198, 0x3a800000, v155
	v_rsq_f32_e32 v170, v170
	v_rsq_f32_e32 v174, v174
	v_rsq_f32_e32 v178, v178
	v_rsq_f32_e32 v182, v182
	v_rsq_f32_e32 v186, v186
	v_rsq_f32_e32 v190, v190
	v_rsq_f32_e32 v194, v194
	v_rsq_f32_e32 v198, v198
	v_pk_add_f32 v[220:221], v[220:221], 1.0 op_sel_hi:[1,0]
	v_pk_add_f32 v[222:223], v[222:223], 1.0 op_sel_hi:[1,0]
	v_pk_add_f32 v[224:225], v[224:225], 1.0 op_sel_hi:[1,0]
	v_pk_add_f32 v[226:227], v[226:227], 1.0 op_sel_hi:[1,0]
	v_pk_add_f32 v[228:229], v[228:229], 1.0 op_sel_hi:[1,0]
	v_pk_add_f32 v[230:231], v[230:231], 1.0 op_sel_hi:[1,0]
	v_pk_add_f32 v[232:233], v[232:233], 1.0 op_sel_hi:[1,0]
	v_pk_add_f32 v[234:235], v[234:235], 1.0 op_sel_hi:[1,0]
	v_pk_mul_f32 v[132:133], v[132:133], v[170:171] op_sel_hi:[1,0]
	v_pk_mul_f32 v[134:135], v[134:135], v[170:171] op_sel_hi:[1,0]
	v_pk_mul_f32 v[128:129], v[128:129], v[170:171] op_sel_hi:[1,0]
	v_pk_mul_f32 v[130:131], v[130:131], v[170:171] op_sel_hi:[1,0]
	v_pk_mul_f32 v[132:133], v[204:205], v[132:133]
	v_pk_mul_f32 v[134:135], v[206:207], v[134:135]
	v_pk_mul_f32 v[128:129], v[208:209], v[128:129]
	v_pk_mul_f32 v[130:131], v[210:211], v[130:131]
	v_pk_fma_f32 v[132:133], v[220:221], v[132:133], v[236:237]
	v_pk_fma_f32 v[134:135], v[222:223], v[134:135], v[238:239]
	v_pk_fma_f32 v[128:129], v[224:225], v[128:129], v[146:147]
	v_pk_fma_f32 v[130:131], v[226:227], v[130:131], v[148:149]
	v_cvt_pk_bf16_f32 v132, v132, v133
	v_cvt_pk_bf16_f32 v133, v134, v135
	v_cvt_pk_bf16_f32 v134, v128, v129
	v_cvt_pk_bf16_f32 v135, v130, v131
	global_store_dwordx4 v144, v[132:135], s[14:15]
	v_pk_mul_f32 v[60:61], v[60:61], v[170:171] op_sel_hi:[1,0]
	v_pk_mul_f32 v[62:63], v[62:63], v[170:171] op_sel_hi:[1,0]
	v_pk_mul_f32 v[56:57], v[56:57], v[170:171] op_sel_hi:[1,0]
	v_pk_mul_f32 v[58:59], v[58:59], v[170:171] op_sel_hi:[1,0]
	v_pk_mul_f32 v[60:61], v[212:213], v[60:61]
	v_pk_mul_f32 v[62:63], v[214:215], v[62:63]
	v_pk_mul_f32 v[56:57], v[216:217], v[56:57]
	v_pk_mul_f32 v[58:59], v[218:219], v[58:59]
	v_pk_fma_f32 v[60:61], v[228:229], v[60:61], v[150:151]
	v_pk_fma_f32 v[62:63], v[230:231], v[62:63], v[152:153]
	v_pk_fma_f32 v[56:57], v[232:233], v[56:57], v[162:163]
	v_pk_fma_f32 v[58:59], v[234:235], v[58:59], v[164:165]
	v_cvt_pk_bf16_f32 v60, v60, v61
	v_cvt_pk_bf16_f32 v61, v62, v63
	v_cvt_pk_bf16_f32 v62, v56, v57
	v_cvt_pk_bf16_f32 v63, v58, v59
	global_store_dwordx4 v144, v[60:63], s[14:15] offset:256
	s_add_u32 s14, s14, 0x8000
	s_addc_u32 s15, s15, 0
	v_pk_mul_f32 v[124:125], v[124:125], v[174:175] op_sel_hi:[1,0]
	v_pk_mul_f32 v[126:127], v[126:127], v[174:175] op_sel_hi:[1,0]
	v_pk_mul_f32 v[120:121], v[120:121], v[174:175] op_sel_hi:[1,0]
	v_pk_mul_f32 v[122:123], v[122:123], v[174:175] op_sel_hi:[1,0]
	v_pk_mul_f32 v[124:125], v[204:205], v[124:125]
	v_pk_mul_f32 v[126:127], v[206:207], v[126:127]
	v_pk_mul_f32 v[120:121], v[208:209], v[120:121]
	v_pk_mul_f32 v[122:123], v[210:211], v[122:123]
	v_pk_fma_f32 v[124:125], v[220:221], v[124:125], v[236:237]
	v_pk_fma_f32 v[126:127], v[222:223], v[126:127], v[238:239]
	v_pk_fma_f32 v[120:121], v[224:225], v[120:121], v[146:147]
	v_pk_fma_f32 v[122:123], v[226:227], v[122:123], v[148:149]
	v_cvt_pk_bf16_f32 v124, v124, v125
	v_cvt_pk_bf16_f32 v125, v126, v127
	v_cvt_pk_bf16_f32 v126, v120, v121
	v_cvt_pk_bf16_f32 v127, v122, v123
	global_store_dwordx4 v144, v[124:127], s[14:15]
	v_pk_mul_f32 v[52:53], v[52:53], v[174:175] op_sel_hi:[1,0]
	v_pk_mul_f32 v[54:55], v[54:55], v[174:175] op_sel_hi:[1,0]
	v_pk_mul_f32 v[48:49], v[48:49], v[174:175] op_sel_hi:[1,0]
	v_pk_mul_f32 v[50:51], v[50:51], v[174:175] op_sel_hi:[1,0]
	v_pk_mul_f32 v[52:53], v[212:213], v[52:53]
	v_pk_mul_f32 v[54:55], v[214:215], v[54:55]
	v_pk_mul_f32 v[48:49], v[216:217], v[48:49]
	v_pk_mul_f32 v[50:51], v[218:219], v[50:51]
	v_pk_fma_f32 v[52:53], v[228:229], v[52:53], v[150:151]
	v_pk_fma_f32 v[54:55], v[230:231], v[54:55], v[152:153]
	v_pk_fma_f32 v[48:49], v[232:233], v[48:49], v[162:163]
	v_pk_fma_f32 v[50:51], v[234:235], v[50:51], v[164:165]
	v_cvt_pk_bf16_f32 v52, v52, v53
	v_cvt_pk_bf16_f32 v53, v54, v55
	v_cvt_pk_bf16_f32 v54, v48, v49
	v_cvt_pk_bf16_f32 v55, v50, v51
	global_store_dwordx4 v144, v[52:55], s[14:15] offset:256
	s_add_u32 s14, s14, 0x8000
	s_addc_u32 s15, s15, 0
	v_pk_mul_f32 v[116:117], v[116:117], v[178:179] op_sel_hi:[1,0]
	v_pk_mul_f32 v[118:119], v[118:119], v[178:179] op_sel_hi:[1,0]
	v_pk_mul_f32 v[112:113], v[112:113], v[178:179] op_sel_hi:[1,0]
	v_pk_mul_f32 v[114:115], v[114:115], v[178:179] op_sel_hi:[1,0]
	v_pk_mul_f32 v[116:117], v[204:205], v[116:117]
	v_pk_mul_f32 v[118:119], v[206:207], v[118:119]
	v_pk_mul_f32 v[112:113], v[208:209], v[112:113]
	v_pk_mul_f32 v[114:115], v[210:211], v[114:115]
	v_pk_fma_f32 v[116:117], v[220:221], v[116:117], v[236:237]
	v_pk_fma_f32 v[118:119], v[222:223], v[118:119], v[238:239]
	v_pk_fma_f32 v[112:113], v[224:225], v[112:113], v[146:147]
	v_pk_fma_f32 v[114:115], v[226:227], v[114:115], v[148:149]
	v_cvt_pk_bf16_f32 v116, v116, v117
	v_cvt_pk_bf16_f32 v117, v118, v119
	v_cvt_pk_bf16_f32 v118, v112, v113
	v_cvt_pk_bf16_f32 v119, v114, v115
	global_store_dwordx4 v144, v[116:119], s[14:15]
	v_pk_mul_f32 v[44:45], v[44:45], v[178:179] op_sel_hi:[1,0]
	v_pk_mul_f32 v[46:47], v[46:47], v[178:179] op_sel_hi:[1,0]
	v_pk_mul_f32 v[40:41], v[40:41], v[178:179] op_sel_hi:[1,0]
	v_pk_mul_f32 v[42:43], v[42:43], v[178:179] op_sel_hi:[1,0]
	v_pk_mul_f32 v[44:45], v[212:213], v[44:45]
	v_pk_mul_f32 v[46:47], v[214:215], v[46:47]
	v_pk_mul_f32 v[40:41], v[216:217], v[40:41]
	v_pk_mul_f32 v[42:43], v[218:219], v[42:43]
	v_pk_fma_f32 v[44:45], v[228:229], v[44:45], v[150:151]
	v_pk_fma_f32 v[46:47], v[230:231], v[46:47], v[152:153]
	v_pk_fma_f32 v[40:41], v[232:233], v[40:41], v[162:163]
	v_pk_fma_f32 v[42:43], v[234:235], v[42:43], v[164:165]
	v_cvt_pk_bf16_f32 v44, v44, v45
	v_cvt_pk_bf16_f32 v45, v46, v47
	v_cvt_pk_bf16_f32 v46, v40, v41
	v_cvt_pk_bf16_f32 v47, v42, v43
	global_store_dwordx4 v144, v[44:47], s[14:15] offset:256
	s_add_u32 s14, s14, 0x8000
	s_addc_u32 s15, s15, 0
	v_pk_mul_f32 v[108:109], v[108:109], v[182:183] op_sel_hi:[1,0]
	v_pk_mul_f32 v[110:111], v[110:111], v[182:183] op_sel_hi:[1,0]
	v_pk_mul_f32 v[104:105], v[104:105], v[182:183] op_sel_hi:[1,0]
	v_pk_mul_f32 v[106:107], v[106:107], v[182:183] op_sel_hi:[1,0]
	v_pk_mul_f32 v[108:109], v[204:205], v[108:109]
	v_pk_mul_f32 v[110:111], v[206:207], v[110:111]
	v_pk_mul_f32 v[104:105], v[208:209], v[104:105]
	v_pk_mul_f32 v[106:107], v[210:211], v[106:107]
	v_pk_fma_f32 v[108:109], v[220:221], v[108:109], v[236:237]
	v_pk_fma_f32 v[110:111], v[222:223], v[110:111], v[238:239]
	v_pk_fma_f32 v[104:105], v[224:225], v[104:105], v[146:147]
	v_pk_fma_f32 v[106:107], v[226:227], v[106:107], v[148:149]
	v_cvt_pk_bf16_f32 v108, v108, v109
	v_cvt_pk_bf16_f32 v109, v110, v111
	v_cvt_pk_bf16_f32 v110, v104, v105
	v_cvt_pk_bf16_f32 v111, v106, v107
	global_store_dwordx4 v144, v[108:111], s[14:15]
	v_pk_mul_f32 v[32:33], v[32:33], v[182:183] op_sel_hi:[1,0]
	v_pk_mul_f32 v[34:35], v[34:35], v[182:183] op_sel_hi:[1,0]
	v_pk_mul_f32 v[24:25], v[24:25], v[182:183] op_sel_hi:[1,0]
	v_pk_mul_f32 v[26:27], v[26:27], v[182:183] op_sel_hi:[1,0]
	v_pk_mul_f32 v[32:33], v[212:213], v[32:33]
	v_pk_mul_f32 v[34:35], v[214:215], v[34:35]
	v_pk_mul_f32 v[24:25], v[216:217], v[24:25]
	v_pk_mul_f32 v[26:27], v[218:219], v[26:27]
	v_pk_fma_f32 v[32:33], v[228:229], v[32:33], v[150:151]
	v_pk_fma_f32 v[34:35], v[230:231], v[34:35], v[152:153]
	v_pk_fma_f32 v[24:25], v[232:233], v[24:25], v[162:163]
	v_pk_fma_f32 v[26:27], v[234:235], v[26:27], v[164:165]
	v_cvt_pk_bf16_f32 v32, v32, v33
	v_cvt_pk_bf16_f32 v33, v34, v35
	v_cvt_pk_bf16_f32 v34, v24, v25
	v_cvt_pk_bf16_f32 v35, v26, v27
	global_store_dwordx4 v144, v[32:35], s[14:15] offset:256
	s_add_u32 s14, s14, 0x28000
	s_addc_u32 s15, s15, 0
	v_pk_mul_f32 v[100:101], v[100:101], v[186:187] op_sel_hi:[1,0]
	v_pk_mul_f32 v[102:103], v[102:103], v[186:187] op_sel_hi:[1,0]
	v_pk_mul_f32 v[96:97], v[96:97], v[186:187] op_sel_hi:[1,0]
	v_pk_mul_f32 v[98:99], v[98:99], v[186:187] op_sel_hi:[1,0]
	v_pk_mul_f32 v[100:101], v[204:205], v[100:101]
	v_pk_mul_f32 v[102:103], v[206:207], v[102:103]
	v_pk_mul_f32 v[96:97], v[208:209], v[96:97]
	v_pk_mul_f32 v[98:99], v[210:211], v[98:99]
	v_pk_fma_f32 v[100:101], v[220:221], v[100:101], v[236:237]
	v_pk_fma_f32 v[102:103], v[222:223], v[102:103], v[238:239]
	v_pk_fma_f32 v[96:97], v[224:225], v[96:97], v[146:147]
	v_pk_fma_f32 v[98:99], v[226:227], v[98:99], v[148:149]
	v_cvt_pk_bf16_f32 v100, v100, v101
	v_cvt_pk_bf16_f32 v101, v102, v103
	v_cvt_pk_bf16_f32 v102, v96, v97
	v_cvt_pk_bf16_f32 v103, v98, v99
	global_store_dwordx4 v144, v[100:103], s[14:15]
	v_pk_mul_f32 v[36:37], v[36:37], v[186:187] op_sel_hi:[1,0]
	v_pk_mul_f32 v[38:39], v[38:39], v[186:187] op_sel_hi:[1,0]
	v_pk_mul_f32 v[28:29], v[28:29], v[186:187] op_sel_hi:[1,0]
	v_pk_mul_f32 v[30:31], v[30:31], v[186:187] op_sel_hi:[1,0]
	v_pk_mul_f32 v[36:37], v[212:213], v[36:37]
	v_pk_mul_f32 v[38:39], v[214:215], v[38:39]
	v_pk_mul_f32 v[28:29], v[216:217], v[28:29]
	v_pk_mul_f32 v[30:31], v[218:219], v[30:31]
	v_pk_fma_f32 v[36:37], v[228:229], v[36:37], v[150:151]
	v_pk_fma_f32 v[38:39], v[230:231], v[38:39], v[152:153]
	v_pk_fma_f32 v[28:29], v[232:233], v[28:29], v[162:163]
	v_pk_fma_f32 v[30:31], v[234:235], v[30:31], v[164:165]
	v_cvt_pk_bf16_f32 v36, v36, v37
	v_cvt_pk_bf16_f32 v37, v38, v39
	v_cvt_pk_bf16_f32 v38, v28, v29
	v_cvt_pk_bf16_f32 v39, v30, v31
	global_store_dwordx4 v144, v[36:39], s[14:15] offset:256
	s_add_u32 s14, s14, 0x8000
	s_addc_u32 s15, s15, 0
	v_pk_mul_f32 v[92:93], v[92:93], v[190:191] op_sel_hi:[1,0]
	v_pk_mul_f32 v[94:95], v[94:95], v[190:191] op_sel_hi:[1,0]
	v_pk_mul_f32 v[88:89], v[88:89], v[190:191] op_sel_hi:[1,0]
	v_pk_mul_f32 v[90:91], v[90:91], v[190:191] op_sel_hi:[1,0]
	v_pk_mul_f32 v[92:93], v[204:205], v[92:93]
	v_pk_mul_f32 v[94:95], v[206:207], v[94:95]
	v_pk_mul_f32 v[88:89], v[208:209], v[88:89]
	v_pk_mul_f32 v[90:91], v[210:211], v[90:91]
	v_pk_fma_f32 v[92:93], v[220:221], v[92:93], v[236:237]
	v_pk_fma_f32 v[94:95], v[222:223], v[94:95], v[238:239]
	v_pk_fma_f32 v[88:89], v[224:225], v[88:89], v[146:147]
	v_pk_fma_f32 v[90:91], v[226:227], v[90:91], v[148:149]
	v_cvt_pk_bf16_f32 v92, v92, v93
	v_cvt_pk_bf16_f32 v93, v94, v95
	v_cvt_pk_bf16_f32 v94, v88, v89
	v_cvt_pk_bf16_f32 v95, v90, v91
	global_store_dwordx4 v144, v[92:95], s[14:15]
	v_pk_mul_f32 v[20:21], v[20:21], v[190:191] op_sel_hi:[1,0]
	v_pk_mul_f32 v[22:23], v[22:23], v[190:191] op_sel_hi:[1,0]
	v_pk_mul_f32 v[16:17], v[16:17], v[190:191] op_sel_hi:[1,0]
	v_pk_mul_f32 v[18:19], v[18:19], v[190:191] op_sel_hi:[1,0]
	v_pk_mul_f32 v[20:21], v[212:213], v[20:21]
	v_pk_mul_f32 v[22:23], v[214:215], v[22:23]
	v_pk_mul_f32 v[16:17], v[216:217], v[16:17]
	v_pk_mul_f32 v[18:19], v[218:219], v[18:19]
	v_pk_fma_f32 v[20:21], v[228:229], v[20:21], v[150:151]
	v_pk_fma_f32 v[22:23], v[230:231], v[22:23], v[152:153]
	v_pk_fma_f32 v[16:17], v[232:233], v[16:17], v[162:163]
	v_pk_fma_f32 v[18:19], v[234:235], v[18:19], v[164:165]
	v_cvt_pk_bf16_f32 v20, v20, v21
	v_cvt_pk_bf16_f32 v21, v22, v23
	v_cvt_pk_bf16_f32 v22, v16, v17
	v_cvt_pk_bf16_f32 v23, v18, v19
	global_store_dwordx4 v144, v[20:23], s[14:15] offset:256
	s_add_u32 s14, s14, 0x8000
	s_addc_u32 s15, s15, 0
	v_pk_mul_f32 v[84:85], v[84:85], v[194:195] op_sel_hi:[1,0]
	v_pk_mul_f32 v[86:87], v[86:87], v[194:195] op_sel_hi:[1,0]
	v_pk_mul_f32 v[80:81], v[80:81], v[194:195] op_sel_hi:[1,0]
	v_pk_mul_f32 v[82:83], v[82:83], v[194:195] op_sel_hi:[1,0]
	v_pk_mul_f32 v[84:85], v[204:205], v[84:85]
	v_pk_mul_f32 v[86:87], v[206:207], v[86:87]
	v_pk_mul_f32 v[80:81], v[208:209], v[80:81]
	v_pk_mul_f32 v[82:83], v[210:211], v[82:83]
	v_pk_fma_f32 v[84:85], v[220:221], v[84:85], v[236:237]
	v_pk_fma_f32 v[86:87], v[222:223], v[86:87], v[238:239]
	v_pk_fma_f32 v[80:81], v[224:225], v[80:81], v[146:147]
	v_pk_fma_f32 v[82:83], v[226:227], v[82:83], v[148:149]
	v_cvt_pk_bf16_f32 v84, v84, v85
	v_cvt_pk_bf16_f32 v85, v86, v87
	v_cvt_pk_bf16_f32 v86, v80, v81
	v_cvt_pk_bf16_f32 v87, v82, v83
	global_store_dwordx4 v144, v[84:87], s[14:15]
	v_pk_mul_f32 v[12:13], v[12:13], v[194:195] op_sel_hi:[1,0]
	v_pk_mul_f32 v[14:15], v[14:15], v[194:195] op_sel_hi:[1,0]
	v_pk_mul_f32 v[8:9], v[8:9], v[194:195] op_sel_hi:[1,0]
	v_pk_mul_f32 v[10:11], v[10:11], v[194:195] op_sel_hi:[1,0]
	v_pk_mul_f32 v[12:13], v[212:213], v[12:13]
	v_pk_mul_f32 v[14:15], v[214:215], v[14:15]
	v_pk_mul_f32 v[8:9], v[216:217], v[8:9]
	v_pk_mul_f32 v[10:11], v[218:219], v[10:11]
	v_pk_fma_f32 v[12:13], v[228:229], v[12:13], v[150:151]
	v_pk_fma_f32 v[14:15], v[230:231], v[14:15], v[152:153]
	v_pk_fma_f32 v[8:9], v[232:233], v[8:9], v[162:163]
	v_pk_fma_f32 v[10:11], v[234:235], v[10:11], v[164:165]
	v_cvt_pk_bf16_f32 v12, v12, v13
	v_cvt_pk_bf16_f32 v13, v14, v15
	v_cvt_pk_bf16_f32 v14, v8, v9
	v_cvt_pk_bf16_f32 v15, v10, v11
	global_store_dwordx4 v144, v[12:15], s[14:15] offset:256
	s_add_u32 s14, s14, 0x8000
	s_addc_u32 s15, s15, 0
	v_pk_mul_f32 v[68:69], v[68:69], v[198:199] op_sel_hi:[1,0]
	v_pk_mul_f32 v[70:71], v[70:71], v[198:199] op_sel_hi:[1,0]
	v_pk_mul_f32 v[64:65], v[64:65], v[198:199] op_sel_hi:[1,0]
	v_pk_mul_f32 v[66:67], v[66:67], v[198:199] op_sel_hi:[1,0]
	v_pk_mul_f32 v[68:69], v[204:205], v[68:69]
	v_pk_mul_f32 v[70:71], v[206:207], v[70:71]
	v_pk_mul_f32 v[64:65], v[208:209], v[64:65]
	v_pk_mul_f32 v[66:67], v[210:211], v[66:67]
	v_pk_fma_f32 v[68:69], v[220:221], v[68:69], v[236:237]
	v_pk_fma_f32 v[70:71], v[222:223], v[70:71], v[238:239]
	v_pk_fma_f32 v[64:65], v[224:225], v[64:65], v[146:147]
	v_pk_fma_f32 v[66:67], v[226:227], v[66:67], v[148:149]
	v_cvt_pk_bf16_f32 v68, v68, v69
	v_cvt_pk_bf16_f32 v69, v70, v71
	v_cvt_pk_bf16_f32 v70, v64, v65
	v_cvt_pk_bf16_f32 v71, v66, v67
	global_store_dwordx4 v144, v[68:71], s[14:15]
	v_pk_mul_f32 v[246:247], v[246:247], v[198:199] op_sel_hi:[1,0]
	v_pk_mul_f32 v[248:249], v[248:249], v[198:199] op_sel_hi:[1,0]
	v_pk_mul_f32 v[242:243], v[242:243], v[198:199] op_sel_hi:[1,0]
	v_pk_mul_f32 v[244:245], v[244:245], v[198:199] op_sel_hi:[1,0]
	v_pk_mul_f32 v[246:247], v[212:213], v[246:247]
	v_pk_mul_f32 v[248:249], v[214:215], v[248:249]
	v_pk_mul_f32 v[242:243], v[216:217], v[242:243]
	v_pk_mul_f32 v[244:245], v[218:219], v[244:245]
	v_pk_fma_f32 v[246:247], v[228:229], v[246:247], v[150:151]
	v_pk_fma_f32 v[248:249], v[230:231], v[248:249], v[152:153]
	v_pk_fma_f32 v[242:243], v[232:233], v[242:243], v[162:163]
	v_pk_fma_f32 v[244:245], v[234:235], v[244:245], v[164:165]
	v_cvt_pk_bf16_f32 v246, v246, v247
	v_cvt_pk_bf16_f32 v247, v248, v249
	v_cvt_pk_bf16_f32 v248, v242, v243
	v_cvt_pk_bf16_f32 v249, v244, v245
	global_store_dwordx4 v144, v[246:249], s[14:15] offset:256
	s_branch .LBB0_189
	v_readlane_b32 s0, v253, 0
	v_readfirstlane_b32 s1, v2
	s_ashr_i32 s1, s1, 6
	s_lshl_b32 s0, s0, 3
	s_and_b32 s1, s1, -4
	v_lshrrev_b32_e32 v1, 6, v0
	s_add_i32 s1, s1, s0
	v_and_or_b32 v16, v1, 3, s1
	s_movk_i32 s0, 0x4000
	v_cmp_gt_i32_e32 vcc, s0, v16
	s_and_saveexec_b64 s[0:1], vcc
	v_readlane_b32 s8, v254, 47
	v_readlane_b32 s10, v254, 49
	s_movk_i32 s6, 0x3fff
	v_readlane_b32 s9, v254, 48
	v_readlane_b32 s11, v254, 50
	s_cbranch_execz .LBB0_189
	v_readlane_b32 s4, v254, 58
	v_readlane_b32 s5, v254, 59
	v_readlane_b32 s36, v253, 11
	s_lshl_b64 s[4:5], s[4:5], 2
	v_readlane_b32 s50, v253, 25
	v_readlane_b32 s51, v253, 26
	s_add_u32 s4, s50, s4
	v_and_b32_e32 v2, 63, v0
	s_addc_u32 s5, s51, s5
	v_lshlrev_b32_e32 v136, 5, v2
	v_lshl_add_u64 v[18:19], s[4:5], 0, v[136:137]
	v_readlane_b32 s4, v254, 55
	v_lshlrev_b32_e32 v0, 2, v2
	v_readlane_b32 s5, v254, 56
	v_xor_b32_e32 v29, 64, v0
	v_xor_b32_e32 v34, 0x80, v0
	v_lshl_add_u64 v[0:1], s[4:5], 0, v[136:137]
	s_mov_b64 s[4:5], 0x4000
	v_lshl_add_u64 v[20:21], v[0:1], 0, s[4:5]
	s_mov_b64 s[4:5], 0x3000
	v_ashrrev_i32_e32 v17, 31, v16
	v_lshl_add_u64 v[22:23], v[0:1], 0, s[4:5]
	v_lshlrev_b64 v[0:1], 11, v[16:17]
	v_readlane_b32 s4, v253, 47
	v_lshl_or_b32 v0, v2, 4, v0
	v_readlane_b32 s5, v253, 48
	v_readlane_b32 s37, v253, 12
	v_readlane_b32 s38, v253, 13
	v_lshl_add_u64 v[24:25], s[4:5], 0, v[0:1]
	v_lshlrev_b64 v[0:1], 12, v[16:17]
	v_or_b32_e32 v0, v0, v136
	v_lshl_add_u64 v[26:27], s[70:71], 0, v[0:1]
	s_mov_b64 s[4:5], 0
	v_readlane_b32 s39, v253, 14
	v_readlane_b32 s40, v253, 15
	v_readlane_b32 s41, v253, 16
	v_readlane_b32 s42, v253, 17
	v_readlane_b32 s43, v253, 18
	v_readlane_b32 s44, v253, 19
	v_readlane_b32 s45, v253, 20
	v_readlane_b32 s46, v253, 21
	v_readlane_b32 s47, v253, 22
	v_readlane_b32 s48, v253, 23
	v_readlane_b32 s49, v253, 24

.LBB0_587:
	s_or_b64 exec, exec, s[4:5]
	v_mov_b32_e32 v80, v154
	s_lshl_b32 s4, s15, 8
	v_and_b32_e32 v136, 15, v80
	v_lshrrev_b32_e32 v81, 1, v80
	v_ashrrev_i32_e32 v80, 2, v80
	v_and_b32_e32 v152, 0xffffffc0, v80
	v_ashrrev_i32_e32 v153, 31, v152
	s_mov_b32 s5, s52
	s_lshr_b32 s1, s14, 3
	v_and_b32_e32 v81, 0x78, v81
	v_lshl_add_u64 v[140:141], v[152:153], 0, s[4:5]
	v_lshl_or_b32 v144, s0, 8, v81
	s_mul_i32 s1, s1, 0x9000
	v_or_b32_e32 v140, v140, v136
	s_add_u32 s0, s11, s1
	v_ashrrev_i32_e32 v145, 31, v144
	v_lshlrev_b64 v[140:141], 12, v[140:141]
	s_addc_u32 s1, s12, 0
	v_lshlrev_b64 v[150:151], 2, v[144:145]
	v_lshl_add_u64 v[170:171], s[70:71], 0, v[140:141]
	v_lshl_add_u64 v[146:147], s[0:1], 0, v[150:151]
	v_lshl_add_u64 v[148:149], v[170:171], 0, v[150:151]
	s_nop 1
	v_readfirstlane_b32 s38, v148
	v_readfirstlane_b32 s39, v149
	s_nop 1
	v_subrev_u32_e32 v139, s38, v148
	s_mov_b64 s[40:41], s[38:39]
	s_mov_b64 s[42:43], s[38:39]
	s_mov_b64 s[44:45], s[40:41]
	s_mov_b64 s[46:47], s[42:43]
	s_mov_b64 s[36:37], 0x20000
	global_load_dwordx4 v[234:237], v[146:147], off
	global_load_dwordx4 v[238:241], v[146:147], off offset:16
	global_load_dwordx4 v[242:245], v[146:147], off offset:512
	global_load_dwordx4 v[246:249], v[146:147], off offset:528
	global_load_dwordx4 v[178:181], v139, s[40:41]
	global_load_dwordx4 v[182:185], v139, s[40:41] offset:16
	s_add_u32 s40, s40, 0x10000
	s_addc_u32 s41, s41, 0
	global_load_dwordx4 v[186:189], v139, s[40:41]
	global_load_dwordx4 v[190:193], v139, s[40:41] offset:16
	s_add_u32 s40, s40, 0x10000
	s_addc_u32 s41, s41, 0
	global_load_dwordx4 v[194:197], v139, s[40:41]
	global_load_dwordx4 v[198:201], v139, s[40:41] offset:16
	s_add_u32 s40, s40, 0x10000
	s_addc_u32 s41, s41, 0
	global_load_dwordx4 v[202:205], v139, s[40:41]
	global_load_dwordx4 v[206:209], v139, s[40:41] offset:16
	s_add_u32 s40, s40, 0x50000
	s_addc_u32 s41, s41, 0
	global_load_dwordx4 v[210:213], v139, s[40:41]
	global_load_dwordx4 v[214:217], v139, s[40:41] offset:16
	s_add_u32 s40, s40, 0x10000
	s_addc_u32 s41, s41, 0
	global_load_dwordx4 v[218:221], v139, s[40:41]
	global_load_dwordx4 v[222:225], v139, s[40:41] offset:16
	s_add_u32 s40, s40, 0x10000
	s_addc_u32 s41, s41, 0
	global_load_dwordx4 v[226:229], v139, s[40:41]
	global_load_dwordx4 v[230:233], v139, s[40:41] offset:16
	s_add_u32 s40, s40, 0x10000
	s_addc_u32 s41, s41, 0
	s_waitcnt vmcnt(12)
	v_pk_fma_f32 v[128:129], v[128:129], v[234:235], v[178:179]
	v_pk_fma_f32 v[130:131], v[130:131], v[236:237], v[180:181]
	v_pk_fma_f32 v[132:133], v[132:133], v[238:239], v[182:183]
	v_pk_fma_f32 v[134:135], v[134:135], v[240:241], v[184:185]
	global_store_dwordx4 v139, v[128:131], s[42:43]
	global_store_dwordx4 v139, v[132:135], s[42:43] offset:16
	s_add_u32 s42, s42, 0x10000
	s_addc_u32 s43, s43, 0
	global_load_dwordx4 v[178:181], v139, s[40:41]
	global_load_dwordx4 v[182:185], v139, s[40:41] offset:16
	s_mov_b64 s[40:41], s[44:45]
	s_waitcnt vmcnt(14)
	v_pk_fma_f32 v[124:125], v[124:125], v[234:235], v[186:187]
	v_pk_fma_f32 v[126:127], v[126:127], v[236:237], v[188:189]
	v_pk_fma_f32 v[120:121], v[120:121], v[238:239], v[190:191]
	v_pk_fma_f32 v[122:123], v[122:123], v[240:241], v[192:193]
	global_store_dwordx4 v139, v[124:127], s[42:43]
	global_store_dwordx4 v139, v[120:123], s[42:43] offset:16
	s_add_u32 s42, s42, 0x10000
	s_addc_u32 s43, s43, 0
	global_load_dwordx4 v[186:189], v139, s[40:41] offset:512
	global_load_dwordx4 v[190:193], v139, s[40:41] offset:528
	s_add_u32 s40, s40, 0x10000
	s_addc_u32 s41, s41, 0
	s_waitcnt vmcnt(16)
	v_pk_fma_f32 v[112:113], v[112:113], v[234:235], v[194:195]
	v_pk_fma_f32 v[114:115], v[114:115], v[236:237], v[196:197]
	v_pk_fma_f32 v[116:117], v[116:117], v[238:239], v[198:199]
	v_pk_fma_f32 v[118:119], v[118:119], v[240:241], v[200:201]
	global_store_dwordx4 v139, v[112:115], s[42:43]
	global_store_dwordx4 v139, v[116:119], s[42:43] offset:16
	s_add_u32 s42, s42, 0x10000
	s_addc_u32 s43, s43, 0
	global_load_dwordx4 v[194:197], v139, s[40:41] offset:512
	global_load_dwordx4 v[198:201], v139, s[40:41] offset:528
	s_add_u32 s40, s40, 0x10000
	s_addc_u32 s41, s41, 0
	s_waitcnt vmcnt(18)
	v_pk_fma_f32 v[100:101], v[100:101], v[234:235], v[202:203]
	v_pk_fma_f32 v[102:103], v[102:103], v[236:237], v[204:205]
	v_pk_fma_f32 v[96:97], v[96:97], v[238:239], v[206:207]
	v_pk_fma_f32 v[98:99], v[98:99], v[240:241], v[208:209]
	global_store_dwordx4 v139, v[100:103], s[42:43]
	global_store_dwordx4 v139, v[96:99], s[42:43] offset:16
	s_add_u32 s42, s42, 0x50000
	s_addc_u32 s43, s43, 0
	global_load_dwordx4 v[202:205], v139, s[40:41] offset:512
	global_load_dwordx4 v[206:209], v139, s[40:41] offset:528
	s_add_u32 s40, s40, 0x10000
	s_addc_u32 s41, s41, 0
	s_waitcnt vmcnt(20)
	v_pk_fma_f32 v[104:105], v[104:105], v[234:235], v[210:211]
	v_pk_fma_f32 v[106:107], v[106:107], v[236:237], v[212:213]
	v_pk_fma_f32 v[108:109], v[108:109], v[238:239], v[214:215]
	v_pk_fma_f32 v[110:111], v[110:111], v[240:241], v[216:217]
	global_store_dwordx4 v139, v[104:107], s[42:43]
	global_store_dwordx4 v139, v[108:111], s[42:43] offset:16
	s_add_u32 s42, s42, 0x10000
	s_addc_u32 s43, s43, 0
	global_load_dwordx4 v[210:213], v139, s[40:41] offset:512
	global_load_dwordx4 v[214:217], v139, s[40:41] offset:528
	s_add_u32 s40, s40, 0x50000
	s_addc_u32 s41, s41, 0
	s_waitcnt vmcnt(22)
	v_pk_fma_f32 v[92:93], v[92:93], v[234:235], v[218:219]
	v_pk_fma_f32 v[94:95], v[94:95], v[236:237], v[220:221]
	v_pk_fma_f32 v[84:85], v[84:85], v[238:239], v[222:223]
	v_pk_fma_f32 v[86:87], v[86:87], v[240:241], v[224:225]
	global_store_dwordx4 v139, v[92:95], s[42:43]
	global_store_dwordx4 v139, v[84:87], s[42:43] offset:16
	s_add_u32 s42, s42, 0x10000
	s_addc_u32 s43, s43, 0
	global_load_dwordx4 v[218:221], v139, s[40:41] offset:512
	global_load_dwordx4 v[222:225], v139, s[40:41] offset:528
	s_add_u32 s40, s40, 0x10000
	s_addc_u32 s41, s41, 0
	s_waitcnt vmcnt(24)
	v_pk_fma_f32 v[72:73], v[72:73], v[234:235], v[226:227]
	v_pk_fma_f32 v[74:75], v[74:75], v[236:237], v[228:229]
	v_pk_fma_f32 v[76:77], v[76:77], v[238:239], v[230:231]
	v_pk_fma_f32 v[78:79], v[78:79], v[240:241], v[232:233]
	global_store_dwordx4 v139, v[72:75], s[42:43]
	global_store_dwordx4 v139, v[76:79], s[42:43] offset:16
	s_add_u32 s42, s42, 0x10000
	s_addc_u32 s43, s43, 0
	global_load_dwordx4 v[226:229], v139, s[40:41] offset:512
	global_load_dwordx4 v[230:233], v139, s[40:41] offset:528
	s_add_u32 s40, s40, 0x10000
	s_addc_u32 s41, s41, 0
	s_waitcnt vmcnt(24)
	v_pk_fma_f32 v[68:69], v[68:69], v[234:235], v[178:179]
	v_pk_fma_f32 v[70:71], v[70:71], v[236:237], v[180:181]
	v_pk_fma_f32 v[64:65], v[64:65], v[238:239], v[182:183]
	v_pk_fma_f32 v[66:67], v[66:67], v[240:241], v[184:185]
	global_store_dwordx4 v139, v[68:71], s[42:43]
	global_store_dwordx4 v139, v[64:67], s[42:43] offset:16
	s_mov_b64 s[42:43], s[46:47]
	global_load_dwordx4 v[178:181], v139, s[40:41] offset:512
	global_load_dwordx4 v[182:185], v139, s[40:41] offset:528
	s_add_u32 s40, s40, 0x10000
	s_addc_u32 s41, s41, 0
	s_waitcnt vmcnt(24)
	v_pk_fma_f32 v[56:57], v[56:57], v[242:243], v[186:187]
	v_pk_fma_f32 v[58:59], v[58:59], v[244:245], v[188:189]
	v_pk_fma_f32 v[60:61], v[60:61], v[246:247], v[190:191]
	v_pk_fma_f32 v[62:63], v[62:63], v[248:249], v[192:193]
	global_store_dwordx4 v139, v[56:59], s[42:43] offset:512
	global_store_dwordx4 v139, v[60:63], s[42:43] offset:528
	s_add_u32 s42, s42, 0x10000
	s_addc_u32 s43, s43, 0
	global_load_dwordx4 v[186:189], v139, s[40:41] offset:512
	global_load_dwordx4 v[190:193], v139, s[40:41] offset:528
	s_waitcnt vmcnt(24)
	v_pk_fma_f32 v[52:53], v[52:53], v[242:243], v[194:195]
	v_pk_fma_f32 v[54:55], v[54:55], v[244:245], v[196:197]
	v_pk_fma_f32 v[48:49], v[48:49], v[246:247], v[198:199]
	v_pk_fma_f32 v[50:51], v[50:51], v[248:249], v[200:201]
	global_store_dwordx4 v139, v[52:55], s[42:43] offset:512
	global_store_dwordx4 v139, v[48:51], s[42:43] offset:528
	s_add_u32 s42, s42, 0x10000
	s_addc_u32 s43, s43, 0
	s_waitcnt vmcnt(22)
	v_pk_fma_f32 v[40:41], v[40:41], v[242:243], v[202:203]
	v_pk_fma_f32 v[42:43], v[42:43], v[244:245], v[204:205]
	v_pk_fma_f32 v[44:45], v[44:45], v[246:247], v[206:207]
	v_pk_fma_f32 v[46:47], v[46:47], v[248:249], v[208:209]
	global_store_dwordx4 v139, v[40:43], s[42:43] offset:512
	global_store_dwordx4 v139, v[44:47], s[42:43] offset:528
	s_add_u32 s42, s42, 0x10000
	s_addc_u32 s43, s43, 0
	s_waitcnt vmcnt(20)
	v_pk_fma_f32 v[32:33], v[32:33], v[242:243], v[210:211]
	v_pk_fma_f32 v[34:35], v[34:35], v[244:245], v[212:213]
	v_pk_fma_f32 v[24:25], v[24:25], v[246:247], v[214:215]
	v_pk_fma_f32 v[26:27], v[26:27], v[248:249], v[216:217]
	global_store_dwordx4 v139, v[32:35], s[42:43] offset:512
	global_store_dwordx4 v139, v[24:27], s[42:43] offset:528
	s_add_u32 s42, s42, 0x50000
	s_addc_u32 s43, s43, 0
	s_waitcnt vmcnt(18)
	v_pk_fma_f32 v[36:37], v[36:37], v[242:243], v[218:219]
	v_pk_fma_f32 v[38:39], v[38:39], v[244:245], v[220:221]
	v_pk_fma_f32 v[28:29], v[28:29], v[246:247], v[222:223]
	v_pk_fma_f32 v[30:31], v[30:31], v[248:249], v[224:225]
	global_store_dwordx4 v139, v[36:39], s[42:43] offset:512
	global_store_dwordx4 v139, v[28:31], s[42:43] offset:528
	s_add_u32 s42, s42, 0x10000
	s_addc_u32 s43, s43, 0
	s_waitcnt vmcnt(16)
	v_pk_fma_f32 v[20:21], v[20:21], v[242:243], v[226:227]
	v_pk_fma_f32 v[22:23], v[22:23], v[244:245], v[228:229]
	v_pk_fma_f32 v[16:17], v[16:17], v[246:247], v[230:231]
	v_pk_fma_f32 v[18:19], v[18:19], v[248:249], v[232:233]
	global_store_dwordx4 v139, v[20:23], s[42:43] offset:512
	global_store_dwordx4 v139, v[16:19], s[42:43] offset:528
	s_add_u32 s42, s42, 0x10000
	s_addc_u32 s43, s43, 0
	s_waitcnt vmcnt(14)
	v_pk_fma_f32 v[12:13], v[12:13], v[242:243], v[178:179]
	v_pk_fma_f32 v[14:15], v[14:15], v[244:245], v[180:181]
	v_pk_fma_f32 v[8:9], v[8:9], v[246:247], v[182:183]
	v_pk_fma_f32 v[10:11], v[10:11], v[248:249], v[184:185]
	global_store_dwordx4 v139, v[12:15], s[42:43] offset:512
	global_store_dwordx4 v139, v[8:11], s[42:43] offset:528
	s_add_u32 s42, s42, 0x10000
	s_addc_u32 s43, s43, 0
	s_waitcnt vmcnt(12)
	v_pk_fma_f32 v[4:5], v[4:5], v[242:243], v[186:187]
	v_pk_fma_f32 v[6:7], v[6:7], v[244:245], v[188:189]
	v_pk_fma_f32 v[0:1], v[0:1], v[246:247], v[190:191]
	v_pk_fma_f32 v[2:3], v[2:3], v[248:249], v[192:193]
	global_store_dwordx4 v139, v[4:7], s[42:43] offset:512
	global_store_dwordx4 v139, v[0:3], s[42:43] offset:528
	v_pk_mul_f32 v[200:201], v[128:129], v[128:129]
	v_pk_mul_f32 v[202:203], v[124:125], v[124:125]
	v_pk_mul_f32 v[204:205], v[112:113], v[112:113]
	v_pk_mul_f32 v[206:207], v[100:101], v[100:101]
	v_pk_mul_f32 v[208:209], v[104:105], v[104:105]
	v_pk_mul_f32 v[210:211], v[92:93], v[92:93]
	v_pk_mul_f32 v[212:213], v[72:73], v[72:73]
	v_pk_mul_f32 v[214:215], v[68:69], v[68:69]
	v_pk_fma_f32 v[200:201], v[130:131], v[130:131], v[200:201]
	v_pk_fma_f32 v[202:203], v[126:127], v[126:127], v[202:203]
	v_pk_fma_f32 v[204:205], v[114:115], v[114:115], v[204:205]
	v_pk_fma_f32 v[206:207], v[102:103], v[102:103], v[206:207]
	v_pk_fma_f32 v[208:209], v[106:107], v[106:107], v[208:209]
	v_pk_fma_f32 v[210:211], v[94:95], v[94:95], v[210:211]
	v_pk_fma_f32 v[212:213], v[74:75], v[74:75], v[212:213]
	v_pk_fma_f32 v[214:215], v[70:71], v[70:71], v[214:215]
	v_pk_fma_f32 v[200:201], v[132:133], v[132:133], v[200:201]
	v_pk_fma_f32 v[202:203], v[120:121], v[120:121], v[202:203]
	v_pk_fma_f32 v[204:205], v[116:117], v[116:117], v[204:205]
	v_pk_fma_f32 v[206:207], v[96:97], v[96:97], v[206:207]
	v_pk_fma_f32 v[208:209], v[108:109], v[108:109], v[208:209]
	v_pk_fma_f32 v[210:211], v[84:85], v[84:85], v[210:211]
	v_pk_fma_f32 v[212:213], v[76:77], v[76:77], v[212:213]
	v_pk_fma_f32 v[214:215], v[64:65], v[64:65], v[214:215]
	v_pk_fma_f32 v[200:201], v[134:135], v[134:135], v[200:201]
	v_pk_fma_f32 v[202:203], v[122:123], v[122:123], v[202:203]
	v_pk_fma_f32 v[204:205], v[118:119], v[118:119], v[204:205]
	v_pk_fma_f32 v[206:207], v[98:99], v[98:99], v[206:207]
	v_pk_fma_f32 v[208:209], v[110:111], v[110:111], v[208:209]
	v_pk_fma_f32 v[210:211], v[86:87], v[86:87], v[210:211]
	v_pk_fma_f32 v[212:213], v[78:79], v[78:79], v[212:213]
	v_pk_fma_f32 v[214:215], v[66:67], v[66:67], v[214:215]
	v_pk_fma_f32 v[200:201], v[56:57], v[56:57], v[200:201]
	v_pk_fma_f32 v[202:203], v[52:53], v[52:53], v[202:203]
	v_pk_fma_f32 v[204:205], v[40:41], v[40:41], v[204:205]
	v_pk_fma_f32 v[206:207], v[32:33], v[32:33], v[206:207]
	v_pk_fma_f32 v[208:209], v[36:37], v[36:37], v[208:209]
	v_pk_fma_f32 v[210:211], v[20:21], v[20:21], v[210:211]
	v_pk_fma_f32 v[212:213], v[12:13], v[12:13], v[212:213]
	v_pk_fma_f32 v[214:215], v[4:5], v[4:5], v[214:215]
	v_pk_fma_f32 v[200:201], v[58:59], v[58:59], v[200:201]
	v_pk_fma_f32 v[202:203], v[54:55], v[54:55], v[202:203]
	v_pk_fma_f32 v[204:205], v[42:43], v[42:43], v[204:205]
	v_pk_fma_f32 v[206:207], v[34:35], v[34:35], v[206:207]
	v_pk_fma_f32 v[208:209], v[38:39], v[38:39], v[208:209]
	v_pk_fma_f32 v[210:211], v[22:23], v[22:23], v[210:211]
	v_pk_fma_f32 v[212:213], v[14:15], v[14:15], v[212:213]
	v_pk_fma_f32 v[214:215], v[6:7], v[6:7], v[214:215]
	v_pk_fma_f32 v[200:201], v[60:61], v[60:61], v[200:201]
	v_pk_fma_f32 v[202:203], v[48:49], v[48:49], v[202:203]
	v_pk_fma_f32 v[204:205], v[44:45], v[44:45], v[204:205]
	v_pk_fma_f32 v[206:207], v[24:25], v[24:25], v[206:207]
	v_pk_fma_f32 v[208:209], v[28:29], v[28:29], v[208:209]
	v_pk_fma_f32 v[210:211], v[16:17], v[16:17], v[210:211]
	v_pk_fma_f32 v[212:213], v[8:9], v[8:9], v[212:213]
	v_pk_fma_f32 v[214:215], v[0:1], v[0:1], v[214:215]
	v_pk_fma_f32 v[200:201], v[62:63], v[62:63], v[200:201]
	v_pk_fma_f32 v[202:203], v[50:51], v[50:51], v[202:203]
	v_pk_fma_f32 v[204:205], v[46:47], v[46:47], v[204:205]
	v_pk_fma_f32 v[206:207], v[26:27], v[26:27], v[206:207]
	v_pk_fma_f32 v[208:209], v[30:31], v[30:31], v[208:209]
	v_pk_fma_f32 v[210:211], v[18:19], v[18:19], v[210:211]
	v_pk_fma_f32 v[212:213], v[10:11], v[10:11], v[212:213]
	v_pk_fma_f32 v[214:215], v[2:3], v[2:3], v[214:215]
	v_add_f32_e32 v216, v200, v201
	v_add_f32_e32 v217, v202, v203
	v_add_f32_e32 v218, v204, v205
	v_add_f32_e32 v219, v206, v207
	v_add_f32_e32 v220, v208, v209
	v_add_f32_e32 v221, v210, v211
	v_add_f32_e32 v222, v212, v213
	v_add_f32_e32 v223, v214, v215
	v_and_b32_e32 v224, 63, v154
	v_xor_b32_e32 v225, 32, v224
	v_xor_b32_e32 v224, 16, v224
	v_lshlrev_b32_e32 v224, 2, v224
	v_lshlrev_b32_e32 v225, 2, v225
	ds_bpermute_b32 v226, v224, v216
	ds_bpermute_b32 v227, v224, v217
	ds_bpermute_b32 v228, v224, v218
	ds_bpermute_b32 v229, v224, v219
	ds_bpermute_b32 v230, v224, v220
	ds_bpermute_b32 v231, v224, v221
	ds_bpermute_b32 v232, v224, v222
	ds_bpermute_b32 v233, v224, v223
	s_waitcnt lgkmcnt(0)
	v_add_f32_e32 v216, v216, v226
	v_add_f32_e32 v217, v217, v227
	v_add_f32_e32 v218, v218, v228
	v_add_f32_e32 v219, v219, v229
	v_add_f32_e32 v220, v220, v230
	v_add_f32_e32 v221, v221, v231
	v_add_f32_e32 v222, v222, v232
	v_add_f32_e32 v223, v223, v233
	ds_bpermute_b32 v226, v225, v216
	ds_bpermute_b32 v227, v225, v217
	ds_bpermute_b32 v228, v225, v218
	ds_bpermute_b32 v229, v225, v219
	ds_bpermute_b32 v230, v225, v220
	ds_bpermute_b32 v231, v225, v221
	ds_bpermute_b32 v232, v225, v222
	ds_bpermute_b32 v233, v225, v223
	s_waitcnt lgkmcnt(0)
	v_add_f32_e32 v216, v216, v226
	v_add_f32_e32 v217, v217, v227
	v_add_f32_e32 v218, v218, v228
	v_add_f32_e32 v219, v219, v229
	v_add_f32_e32 v220, v220, v230
	v_add_f32_e32 v221, v221, v231
	v_add_f32_e32 v222, v222, v232
	v_add_f32_e32 v223, v223, v233
	v_bfe_u32 v234, v154, 6, 2
	v_lshlrev_b32_e32 v234, 8, v234
	v_lshrrev_b32_e32 v235, 8, v154
	v_lshl_add_u32 v234, v235, 6, v234
	v_and_b32_e32 v235, 15, v154
	v_add_u32_e32 v234, v234, v235
	v_lshlrev_b32_e32 v234, 2, v234
	ds_write_b32 v234, v216 offset:0
	ds_write_b32 v234, v217 offset:64
	ds_write_b32 v234, v218 offset:128
	ds_write_b32 v234, v219 offset:192
	ds_write_b32 v234, v220 offset:512
	ds_write_b32 v234, v221 offset:576
	ds_write_b32 v234, v222 offset:640
	ds_write_b32 v234, v223 offset:704
	s_waitcnt lgkmcnt(0)
	s_barrier
	v_cmp_gt_u32_e32 vcc, 0x100, v154
	s_and_saveexec_b64 s[48:49], vcc
	v_lshlrev_b32_e32 v235, 2, v154
	ds_read_b32 v236, v235
	ds_read_b32 v237, v235 offset:1024
	ds_read_b32 v238, v235 offset:2048
	ds_read_b32 v239, v235 offset:3072
	s_lshl_b32 s50, s8, 3
	s_and_b32 s50, s50, 56
	s_bfe_u32 s51, s8, 0x30003
	s_or_b32 s50, s50, s51
	s_lshl_b32 s50, s50, 2
	s_lshr_b32 s51, s8, 6
	s_or_b32 s50, s50, s51
	s_lshl_b32 s50, s50, 10
	s_add_u32 s50, s50, s72
	s_addc_u32 s51, s73, 0
	s_add_u32 s50, s50, 0x19500000
	s_addc_u32 s51, s51, 0
	s_waitcnt lgkmcnt(0)
	v_add_f32_e32 v236, v236, v237
	v_add_f32_e32 v238, v238, v239
	v_add_f32_e32 v236, v236, v238
	global_store_dword v235, v236, s[50:51]
	s_mov_b64 exec, s[48:49]
	s_mov_b32 s92, s8
	v_mov_b64_e32 v[242:243], v[0:1]
	v_mov_b64_e32 v[244:245], v[2:3]
	v_mov_b64_e32 v[246:247], v[4:5]
	v_mov_b64_e32 v[248:249], v[6:7]
	s_add_i32 s8, s8, s74
	s_add_i32 s13, s13, s20
	s_cmpk_lt_i32 s8, 0x100
	s_cbranch_scc0 .LBB0_594

.LBB0_624:
	s_or_b64 exec, exec, s[0:1]
	v_mov_b32_e32 v0, v154
	v_mov_b32_e32 v2, v154
	s_waitcnt lgkmcnt(0)
	s_barrier
	s_lshl_b32 s0, s92, 3
	s_and_b32 s0, s0, 56
	s_bfe_u32 s1, s92, 0x30003
	s_or_b32 s0, s0, s1
	s_lshr_b32 s1, s92, 6
	v_lshrrev_b32_e32 v140, 8, v154
	v_and_b32_e32 v141, 15, v154
	v_lshl_add_u32 v140, v140, 6, v141
	v_bfe_u32 v141, v154, 6, 2
	v_bfe_u32 v142, v154, 4, 2
	v_lshlrev_b32_e32 v141, 5, v141
	v_lshl_add_u32 v141, v142, 3, v141
	v_lshlrev_b32_e32 v142, 2, v140
	v_lshlrev_b32_e32 v143, 2, v141
	v_lshlrev_b32_e32 v144, 11, v140
	v_lshl_add_u32 v144, v141, 1, v144
	s_lshl_b32 s6, s0, 12
	s_add_u32 s6, s6, s72
	s_addc_u32 s7, s73, 0
	s_add_u32 s6, s6, 0x19500000
	s_addc_u32 s7, s7, 0
	global_load_dword v170, v142, s[6:7] offset:0
	global_load_dword v171, v142, s[6:7] offset:1024
	global_load_dword v172, v142, s[6:7] offset:2048
	global_load_dword v173, v142, s[6:7] offset:3072
	global_load_dword v174, v142, s[6:7] offset:64
	global_load_dword v175, v142, s[6:7] offset:1088
	global_load_dword v176, v142, s[6:7] offset:2112
	global_load_dword v177, v142, s[6:7] offset:3136
	global_load_dword v178, v142, s[6:7] offset:128
	global_load_dword v179, v142, s[6:7] offset:1152
	global_load_dword v180, v142, s[6:7] offset:2176
	global_load_dword v181, v142, s[6:7] offset:3200
	global_load_dword v182, v142, s[6:7] offset:192
	global_load_dword v183, v142, s[6:7] offset:1216
	global_load_dword v184, v142, s[6:7] offset:2240
	global_load_dword v185, v142, s[6:7] offset:3264
	global_load_dword v186, v142, s[6:7] offset:512
	global_load_dword v187, v142, s[6:7] offset:1536
	global_load_dword v188, v142, s[6:7] offset:2560
	global_load_dword v189, v142, s[6:7] offset:3584
	global_load_dword v190, v142, s[6:7] offset:576
	global_load_dword v191, v142, s[6:7] offset:1600
	global_load_dword v192, v142, s[6:7] offset:2624
	global_load_dword v193, v142, s[6:7] offset:3648
	global_load_dword v194, v142, s[6:7] offset:640
	global_load_dword v195, v142, s[6:7] offset:1664
	global_load_dword v196, v142, s[6:7] offset:2688
	global_load_dword v197, v142, s[6:7] offset:3712
	global_load_dword v198, v142, s[6:7] offset:704
	global_load_dword v199, v142, s[6:7] offset:1728
	global_load_dword v200, v142, s[6:7] offset:2752
	global_load_dword v201, v142, s[6:7] offset:3776
	v_readlane_b32 s4, v254, 57
	s_lshl_b32 s4, s4, 12
	s_lshl_b32 s1, s1, 10
	v_readlane_b32 s8, v253, 5
	v_readlane_b32 s9, v253, 6
	s_add_u32 s8, s8, s4
	s_addc_u32 s9, s9, 0
	s_add_u32 s8, s8, s1
	s_addc_u32 s9, s9, 0
	s_lshr_b32 s4, s0, 3
	s_mul_i32 s4, s4, 0x9000
	s_add_u32 s4, s4, s1
	v_readlane_b32 s10, v254, 55
	v_readlane_b32 s11, v254, 56
	s_add_u32 s10, s10, s4
	s_addc_u32 s11, s11, 0
	s_add_u32 s12, s10, 0x6000
	s_addc_u32 s13, s11, 0
	s_add_u32 s10, s10, 0x7000
	s_addc_u32 s11, s11, 0
	global_load_dwordx4 v[204:207], v143, s[8:9]
	global_load_dwordx4 v[220:223], v143, s[10:11]
	global_load_dwordx4 v[236:239], v143, s[12:13]
	global_load_dwordx4 v[208:211], v143, s[8:9] offset:16
	global_load_dwordx4 v[224:227], v143, s[10:11] offset:16
	global_load_dwordx4 v[146:149], v143, s[12:13] offset:16
	global_load_dwordx4 v[212:215], v143, s[8:9] offset:512
	global_load_dwordx4 v[228:231], v143, s[10:11] offset:512
	global_load_dwordx4 v[150:153], v143, s[12:13] offset:512
	global_load_dwordx4 v[216:219], v143, s[8:9] offset:528
	global_load_dwordx4 v[232:235], v143, s[10:11] offset:528
	global_load_dwordx4 v[162:165], v143, s[12:13] offset:528
	v_readlane_b32 s14, v253, 47
	v_readlane_b32 s15, v253, 48
	s_lshl_b32 s4, s0, 19
	s_add_u32 s14, s14, s4
	s_addc_u32 s15, s15, 0
	s_lshr_b32 s4, s1, 1
	s_add_u32 s14, s14, s4
	s_addc_u32 s15, s15, 0
	s_waitcnt vmcnt(0)
	v_add_f32_e32 v170, v170, v171
	v_add_f32_e32 v172, v172, v173
	v_add_f32_e32 v174, v174, v175
	v_add_f32_e32 v176, v176, v177
	v_add_f32_e32 v178, v178, v179
	v_add_f32_e32 v180, v180, v181
	v_add_f32_e32 v182, v182, v183
	v_add_f32_e32 v184, v184, v185
	v_add_f32_e32 v186, v186, v187
	v_add_f32_e32 v188, v188, v189
	v_add_f32_e32 v190, v190, v191
	v_add_f32_e32 v192, v192, v193
	v_add_f32_e32 v194, v194, v195
	v_add_f32_e32 v196, v196, v197
	v_add_f32_e32 v198, v198, v199
	v_add_f32_e32 v200, v200, v201
	v_add_f32_e32 v170, v170, v172
	v_add_f32_e32 v174, v174, v176
	v_add_f32_e32 v178, v178, v180
	v_add_f32_e32 v182, v182, v184
	v_add_f32_e32 v186, v186, v188
	v_add_f32_e32 v190, v190, v192
	v_add_f32_e32 v194, v194, v196
	v_add_f32_e32 v198, v198, v200
	v_fmamk_f32 v170, v170, 0x3a800000, v155
	v_fmamk_f32 v174, v174, 0x3a800000, v155
	v_fmamk_f32 v178, v178, 0x3a800000, v155
	v_fmamk_f32 v182, v182, 0x3a800000, v155
	v_fmamk_f32 v186, v186, 0x3a800000, v155
	v_fmamk_f32 v190, v190, 0x3a800000, v155
	v_fmamk_f32 v194, v194, 0x3a800000, v155
	v_fmamk_f32 v198, v198, 0x3a800000, v155
	v_rsq_f32_e32 v170, v170
	v_rsq_f32_e32 v174, v174
	v_rsq_f32_e32 v178, v178
	v_rsq_f32_e32 v182, v182
	v_rsq_f32_e32 v186, v186
	v_rsq_f32_e32 v190, v190
	v_rsq_f32_e32 v194, v194
	v_rsq_f32_e32 v198, v198
	v_pk_add_f32 v[220:221], v[220:221], 1.0 op_sel_hi:[1,0]
	v_pk_add_f32 v[222:223], v[222:223], 1.0 op_sel_hi:[1,0]
	v_pk_add_f32 v[224:225], v[224:225], 1.0 op_sel_hi:[1,0]
	v_pk_add_f32 v[226:227], v[226:227], 1.0 op_sel_hi:[1,0]
	v_pk_add_f32 v[228:229], v[228:229], 1.0 op_sel_hi:[1,0]
	v_pk_add_f32 v[230:231], v[230:231], 1.0 op_sel_hi:[1,0]
	v_pk_add_f32 v[232:233], v[232:233], 1.0 op_sel_hi:[1,0]
	v_pk_add_f32 v[234:235], v[234:235], 1.0 op_sel_hi:[1,0]
	v_pk_mul_f32 v[128:129], v[128:129], v[170:171] op_sel_hi:[1,0]
	v_pk_mul_f32 v[130:131], v[130:131], v[170:171] op_sel_hi:[1,0]
	v_pk_mul_f32 v[132:133], v[132:133], v[170:171] op_sel_hi:[1,0]
	v_pk_mul_f32 v[134:135], v[134:135], v[170:171] op_sel_hi:[1,0]
	v_pk_mul_f32 v[128:129], v[204:205], v[128:129]
	v_pk_mul_f32 v[130:131], v[206:207], v[130:131]
	v_pk_mul_f32 v[132:133], v[208:209], v[132:133]
	v_pk_mul_f32 v[134:135], v[210:211], v[134:135]
	v_pk_fma_f32 v[128:129], v[220:221], v[128:129], v[236:237]
	v_pk_fma_f32 v[130:131], v[222:223], v[130:131], v[238:239]
	v_pk_fma_f32 v[132:133], v[224:225], v[132:133], v[146:147]
	v_pk_fma_f32 v[134:135], v[226:227], v[134:135], v[148:149]
	v_cvt_pk_bf16_f32 v128, v128, v129
	v_cvt_pk_bf16_f32 v129, v130, v131
	v_cvt_pk_bf16_f32 v130, v132, v133
	v_cvt_pk_bf16_f32 v131, v134, v135
	global_store_dwordx4 v144, v[128:131], s[14:15]
	v_pk_mul_f32 v[56:57], v[56:57], v[170:171] op_sel_hi:[1,0]
	v_pk_mul_f32 v[58:59], v[58:59], v[170:171] op_sel_hi:[1,0]
	v_pk_mul_f32 v[60:61], v[60:61], v[170:171] op_sel_hi:[1,0]
	v_pk_mul_f32 v[62:63], v[62:63], v[170:171] op_sel_hi:[1,0]
	v_pk_mul_f32 v[56:57], v[212:213], v[56:57]
	v_pk_mul_f32 v[58:59], v[214:215], v[58:59]
	v_pk_mul_f32 v[60:61], v[216:217], v[60:61]
	v_pk_mul_f32 v[62:63], v[218:219], v[62:63]
	v_pk_fma_f32 v[56:57], v[228:229], v[56:57], v[150:151]
	v_pk_fma_f32 v[58:59], v[230:231], v[58:59], v[152:153]
	v_pk_fma_f32 v[60:61], v[232:233], v[60:61], v[162:163]
	v_pk_fma_f32 v[62:63], v[234:235], v[62:63], v[164:165]
	v_cvt_pk_bf16_f32 v56, v56, v57
	v_cvt_pk_bf16_f32 v57, v58, v59
	v_cvt_pk_bf16_f32 v58, v60, v61
	v_cvt_pk_bf16_f32 v59, v62, v63
	global_store_dwordx4 v144, v[56:59], s[14:15] offset:256
	s_add_u32 s14, s14, 0x8000
	s_addc_u32 s15, s15, 0
	v_pk_mul_f32 v[124:125], v[124:125], v[174:175] op_sel_hi:[1,0]
	v_pk_mul_f32 v[126:127], v[126:127], v[174:175] op_sel_hi:[1,0]
	v_pk_mul_f32 v[120:121], v[120:121], v[174:175] op_sel_hi:[1,0]
	v_pk_mul_f32 v[122:123], v[122:123], v[174:175] op_sel_hi:[1,0]
	v_pk_mul_f32 v[124:125], v[204:205], v[124:125]
	v_pk_mul_f32 v[126:127], v[206:207], v[126:127]
	v_pk_mul_f32 v[120:121], v[208:209], v[120:121]
	v_pk_mul_f32 v[122:123], v[210:211], v[122:123]
	v_pk_fma_f32 v[124:125], v[220:221], v[124:125], v[236:237]
	v_pk_fma_f32 v[126:127], v[222:223], v[126:127], v[238:239]
	v_pk_fma_f32 v[120:121], v[224:225], v[120:121], v[146:147]
	v_pk_fma_f32 v[122:123], v[226:227], v[122:123], v[148:149]
	v_cvt_pk_bf16_f32 v124, v124, v125
	v_cvt_pk_bf16_f32 v125, v126, v127
	v_cvt_pk_bf16_f32 v126, v120, v121
	v_cvt_pk_bf16_f32 v127, v122, v123
	global_store_dwordx4 v144, v[124:127], s[14:15]
	v_pk_mul_f32 v[52:53], v[52:53], v[174:175] op_sel_hi:[1,0]
	v_pk_mul_f32 v[54:55], v[54:55], v[174:175] op_sel_hi:[1,0]
	v_pk_mul_f32 v[48:49], v[48:49], v[174:175] op_sel_hi:[1,0]
	v_pk_mul_f32 v[50:51], v[50:51], v[174:175] op_sel_hi:[1,0]
	v_pk_mul_f32 v[52:53], v[212:213], v[52:53]
	v_pk_mul_f32 v[54:55], v[214:215], v[54:55]
	v_pk_mul_f32 v[48:49], v[216:217], v[48:49]
	v_pk_mul_f32 v[50:51], v[218:219], v[50:51]
	v_pk_fma_f32 v[52:53], v[228:229], v[52:53], v[150:151]
	v_pk_fma_f32 v[54:55], v[230:231], v[54:55], v[152:153]
	v_pk_fma_f32 v[48:49], v[232:233], v[48:49], v[162:163]
	v_pk_fma_f32 v[50:51], v[234:235], v[50:51], v[164:165]
	v_cvt_pk_bf16_f32 v52, v52, v53
	v_cvt_pk_bf16_f32 v53, v54, v55
	v_cvt_pk_bf16_f32 v54, v48, v49
	v_cvt_pk_bf16_f32 v55, v50, v51
	global_store_dwordx4 v144, v[52:55], s[14:15] offset:256
	s_add_u32 s14, s14, 0x8000
	s_addc_u32 s15, s15, 0
	v_pk_mul_f32 v[112:113], v[112:113], v[178:179] op_sel_hi:[1,0]
	v_pk_mul_f32 v[114:115], v[114:115], v[178:179] op_sel_hi:[1,0]
	v_pk_mul_f32 v[116:117], v[116:117], v[178:179] op_sel_hi:[1,0]
	v_pk_mul_f32 v[118:119], v[118:119], v[178:179] op_sel_hi:[1,0]
	v_pk_mul_f32 v[112:113], v[204:205], v[112:113]
	v_pk_mul_f32 v[114:115], v[206:207], v[114:115]
	v_pk_mul_f32 v[116:117], v[208:209], v[116:117]
	v_pk_mul_f32 v[118:119], v[210:211], v[118:119]
	v_pk_fma_f32 v[112:113], v[220:221], v[112:113], v[236:237]
	v_pk_fma_f32 v[114:115], v[222:223], v[114:115], v[238:239]
	v_pk_fma_f32 v[116:117], v[224:225], v[116:117], v[146:147]
	v_pk_fma_f32 v[118:119], v[226:227], v[118:119], v[148:149]
	v_cvt_pk_bf16_f32 v112, v112, v113
	v_cvt_pk_bf16_f32 v113, v114, v115
	v_cvt_pk_bf16_f32 v114, v116, v117
	v_cvt_pk_bf16_f32 v115, v118, v119
	global_store_dwordx4 v144, v[112:115], s[14:15]
	v_pk_mul_f32 v[40:41], v[40:41], v[178:179] op_sel_hi:[1,0]
	v_pk_mul_f32 v[42:43], v[42:43], v[178:179] op_sel_hi:[1,0]
	v_pk_mul_f32 v[44:45], v[44:45], v[178:179] op_sel_hi:[1,0]
	v_pk_mul_f32 v[46:47], v[46:47], v[178:179] op_sel_hi:[1,0]
	v_pk_mul_f32 v[40:41], v[212:213], v[40:41]
	v_pk_mul_f32 v[42:43], v[214:215], v[42:43]
	v_pk_mul_f32 v[44:45], v[216:217], v[44:45]
	v_pk_mul_f32 v[46:47], v[218:219], v[46:47]
	v_pk_fma_f32 v[40:41], v[228:229], v[40:41], v[150:151]
	v_pk_fma_f32 v[42:43], v[230:231], v[42:43], v[152:153]
	v_pk_fma_f32 v[44:45], v[232:233], v[44:45], v[162:163]
	v_pk_fma_f32 v[46:47], v[234:235], v[46:47], v[164:165]
	v_cvt_pk_bf16_f32 v40, v40, v41
	v_cvt_pk_bf16_f32 v41, v42, v43
	v_cvt_pk_bf16_f32 v42, v44, v45
	v_cvt_pk_bf16_f32 v43, v46, v47
	global_store_dwordx4 v144, v[40:43], s[14:15] offset:256
	s_add_u32 s14, s14, 0x8000
	s_addc_u32 s15, s15, 0
	v_pk_mul_f32 v[100:101], v[100:101], v[182:183] op_sel_hi:[1,0]
	v_pk_mul_f32 v[102:103], v[102:103], v[182:183] op_sel_hi:[1,0]
	v_pk_mul_f32 v[96:97], v[96:97], v[182:183] op_sel_hi:[1,0]
	v_pk_mul_f32 v[98:99], v[98:99], v[182:183] op_sel_hi:[1,0]
	v_pk_mul_f32 v[100:101], v[204:205], v[100:101]
	v_pk_mul_f32 v[102:103], v[206:207], v[102:103]
	v_pk_mul_f32 v[96:97], v[208:209], v[96:97]
	v_pk_mul_f32 v[98:99], v[210:211], v[98:99]
	v_pk_fma_f32 v[100:101], v[220:221], v[100:101], v[236:237]
	v_pk_fma_f32 v[102:103], v[222:223], v[102:103], v[238:239]
	v_pk_fma_f32 v[96:97], v[224:225], v[96:97], v[146:147]
	v_pk_fma_f32 v[98:99], v[226:227], v[98:99], v[148:149]
	v_cvt_pk_bf16_f32 v100, v100, v101
	v_cvt_pk_bf16_f32 v101, v102, v103
	v_cvt_pk_bf16_f32 v102, v96, v97
	v_cvt_pk_bf16_f32 v103, v98, v99
	global_store_dwordx4 v144, v[100:103], s[14:15]
	v_pk_mul_f32 v[32:33], v[32:33], v[182:183] op_sel_hi:[1,0]
	v_pk_mul_f32 v[34:35], v[34:35], v[182:183] op_sel_hi:[1,0]
	v_pk_mul_f32 v[24:25], v[24:25], v[182:183] op_sel_hi:[1,0]
	v_pk_mul_f32 v[26:27], v[26:27], v[182:183] op_sel_hi:[1,0]
	v_pk_mul_f32 v[32:33], v[212:213], v[32:33]
	v_pk_mul_f32 v[34:35], v[214:215], v[34:35]
	v_pk_mul_f32 v[24:25], v[216:217], v[24:25]
	v_pk_mul_f32 v[26:27], v[218:219], v[26:27]
	v_pk_fma_f32 v[32:33], v[228:229], v[32:33], v[150:151]
	v_pk_fma_f32 v[34:35], v[230:231], v[34:35], v[152:153]
	v_pk_fma_f32 v[24:25], v[232:233], v[24:25], v[162:163]
	v_pk_fma_f32 v[26:27], v[234:235], v[26:27], v[164:165]
	v_cvt_pk_bf16_f32 v32, v32, v33
	v_cvt_pk_bf16_f32 v33, v34, v35
	v_cvt_pk_bf16_f32 v34, v24, v25
	v_cvt_pk_bf16_f32 v35, v26, v27
	global_store_dwordx4 v144, v[32:35], s[14:15] offset:256
	s_add_u32 s14, s14, 0x28000
	s_addc_u32 s15, s15, 0
	v_pk_mul_f32 v[104:105], v[104:105], v[186:187] op_sel_hi:[1,0]
	v_pk_mul_f32 v[106:107], v[106:107], v[186:187] op_sel_hi:[1,0]
	v_pk_mul_f32 v[108:109], v[108:109], v[186:187] op_sel_hi:[1,0]
	v_pk_mul_f32 v[110:111], v[110:111], v[186:187] op_sel_hi:[1,0]
	v_pk_mul_f32 v[104:105], v[204:205], v[104:105]
	v_pk_mul_f32 v[106:107], v[206:207], v[106:107]
	v_pk_mul_f32 v[108:109], v[208:209], v[108:109]
	v_pk_mul_f32 v[110:111], v[210:211], v[110:111]
	v_pk_fma_f32 v[104:105], v[220:221], v[104:105], v[236:237]
	v_pk_fma_f32 v[106:107], v[222:223], v[106:107], v[238:239]
	v_pk_fma_f32 v[108:109], v[224:225], v[108:109], v[146:147]
	v_pk_fma_f32 v[110:111], v[226:227], v[110:111], v[148:149]
	v_cvt_pk_bf16_f32 v104, v104, v105
	v_cvt_pk_bf16_f32 v105, v106, v107
	v_cvt_pk_bf16_f32 v106, v108, v109
	v_cvt_pk_bf16_f32 v107, v110, v111
	global_store_dwordx4 v144, v[104:107], s[14:15]
	v_pk_mul_f32 v[36:37], v[36:37], v[186:187] op_sel_hi:[1,0]
	v_pk_mul_f32 v[38:39], v[38:39], v[186:187] op_sel_hi:[1,0]
	v_pk_mul_f32 v[28:29], v[28:29], v[186:187] op_sel_hi:[1,0]
	v_pk_mul_f32 v[30:31], v[30:31], v[186:187] op_sel_hi:[1,0]
	v_pk_mul_f32 v[36:37], v[212:213], v[36:37]
	v_pk_mul_f32 v[38:39], v[214:215], v[38:39]
	v_pk_mul_f32 v[28:29], v[216:217], v[28:29]
	v_pk_mul_f32 v[30:31], v[218:219], v[30:31]
	v_pk_fma_f32 v[36:37], v[228:229], v[36:37], v[150:151]
	v_pk_fma_f32 v[38:39], v[230:231], v[38:39], v[152:153]
	v_pk_fma_f32 v[28:29], v[232:233], v[28:29], v[162:163]
	v_pk_fma_f32 v[30:31], v[234:235], v[30:31], v[164:165]
	v_cvt_pk_bf16_f32 v36, v36, v37
	v_cvt_pk_bf16_f32 v37, v38, v39
	v_cvt_pk_bf16_f32 v38, v28, v29
	v_cvt_pk_bf16_f32 v39, v30, v31
	global_store_dwordx4 v144, v[36:39], s[14:15] offset:256
	s_add_u32 s14, s14, 0x8000
	s_addc_u32 s15, s15, 0
	v_pk_mul_f32 v[92:93], v[92:93], v[190:191] op_sel_hi:[1,0]
	v_pk_mul_f32 v[94:95], v[94:95], v[190:191] op_sel_hi:[1,0]
	v_pk_mul_f32 v[84:85], v[84:85], v[190:191] op_sel_hi:[1,0]
	v_pk_mul_f32 v[86:87], v[86:87], v[190:191] op_sel_hi:[1,0]
	v_pk_mul_f32 v[92:93], v[204:205], v[92:93]
	v_pk_mul_f32 v[94:95], v[206:207], v[94:95]
	v_pk_mul_f32 v[84:85], v[208:209], v[84:85]
	v_pk_mul_f32 v[86:87], v[210:211], v[86:87]
	v_pk_fma_f32 v[92:93], v[220:221], v[92:93], v[236:237]
	v_pk_fma_f32 v[94:95], v[222:223], v[94:95], v[238:239]
	v_pk_fma_f32 v[84:85], v[224:225], v[84:85], v[146:147]
	v_pk_fma_f32 v[86:87], v[226:227], v[86:87], v[148:149]
	v_cvt_pk_bf16_f32 v92, v92, v93
	v_cvt_pk_bf16_f32 v93, v94, v95
	v_cvt_pk_bf16_f32 v94, v84, v85
	v_cvt_pk_bf16_f32 v95, v86, v87
	global_store_dwordx4 v144, v[92:95], s[14:15]
	v_pk_mul_f32 v[20:21], v[20:21], v[190:191] op_sel_hi:[1,0]
	v_pk_mul_f32 v[22:23], v[22:23], v[190:191] op_sel_hi:[1,0]
	v_pk_mul_f32 v[16:17], v[16:17], v[190:191] op_sel_hi:[1,0]
	v_pk_mul_f32 v[18:19], v[18:19], v[190:191] op_sel_hi:[1,0]
	v_pk_mul_f32 v[20:21], v[212:213], v[20:21]
	v_pk_mul_f32 v[22:23], v[214:215], v[22:23]
	v_pk_mul_f32 v[16:17], v[216:217], v[16:17]
	v_pk_mul_f32 v[18:19], v[218:219], v[18:19]
	v_pk_fma_f32 v[20:21], v[228:229], v[20:21], v[150:151]
	v_pk_fma_f32 v[22:23], v[230:231], v[22:23], v[152:153]
	v_pk_fma_f32 v[16:17], v[232:233], v[16:17], v[162:163]
	v_pk_fma_f32 v[18:19], v[234:235], v[18:19], v[164:165]
	v_cvt_pk_bf16_f32 v20, v20, v21
	v_cvt_pk_bf16_f32 v21, v22, v23
	v_cvt_pk_bf16_f32 v22, v16, v17
	v_cvt_pk_bf16_f32 v23, v18, v19
	global_store_dwordx4 v144, v[20:23], s[14:15] offset:256
	s_add_u32 s14, s14, 0x8000
	s_addc_u32 s15, s15, 0
	v_pk_mul_f32 v[72:73], v[72:73], v[194:195] op_sel_hi:[1,0]
	v_pk_mul_f32 v[74:75], v[74:75], v[194:195] op_sel_hi:[1,0]
	v_pk_mul_f32 v[76:77], v[76:77], v[194:195] op_sel_hi:[1,0]
	v_pk_mul_f32 v[78:79], v[78:79], v[194:195] op_sel_hi:[1,0]
	v_pk_mul_f32 v[72:73], v[204:205], v[72:73]
	v_pk_mul_f32 v[74:75], v[206:207], v[74:75]
	v_pk_mul_f32 v[76:77], v[208:209], v[76:77]
	v_pk_mul_f32 v[78:79], v[210:211], v[78:79]
	v_pk_fma_f32 v[72:73], v[220:221], v[72:73], v[236:237]
	v_pk_fma_f32 v[74:75], v[222:223], v[74:75], v[238:239]
	v_pk_fma_f32 v[76:77], v[224:225], v[76:77], v[146:147]
	v_pk_fma_f32 v[78:79], v[226:227], v[78:79], v[148:149]
	v_cvt_pk_bf16_f32 v72, v72, v73
	v_cvt_pk_bf16_f32 v73, v74, v75
	v_cvt_pk_bf16_f32 v74, v76, v77
	v_cvt_pk_bf16_f32 v75, v78, v79
	global_store_dwordx4 v144, v[72:75], s[14:15]
	v_pk_mul_f32 v[12:13], v[12:13], v[194:195] op_sel_hi:[1,0]
	v_pk_mul_f32 v[14:15], v[14:15], v[194:195] op_sel_hi:[1,0]
	v_pk_mul_f32 v[8:9], v[8:9], v[194:195] op_sel_hi:[1,0]
	v_pk_mul_f32 v[10:11], v[10:11], v[194:195] op_sel_hi:[1,0]
	v_pk_mul_f32 v[12:13], v[212:213], v[12:13]
	v_pk_mul_f32 v[14:15], v[214:215], v[14:15]
	v_pk_mul_f32 v[8:9], v[216:217], v[8:9]
	v_pk_mul_f32 v[10:11], v[218:219], v[10:11]
	v_pk_fma_f32 v[12:13], v[228:229], v[12:13], v[150:151]
	v_pk_fma_f32 v[14:15], v[230:231], v[14:15], v[152:153]
	v_pk_fma_f32 v[8:9], v[232:233], v[8:9], v[162:163]
	v_pk_fma_f32 v[10:11], v[234:235], v[10:11], v[164:165]
	v_cvt_pk_bf16_f32 v12, v12, v13
	v_cvt_pk_bf16_f32 v13, v14, v15
	v_cvt_pk_bf16_f32 v14, v8, v9
	v_cvt_pk_bf16_f32 v15, v10, v11
	global_store_dwordx4 v144, v[12:15], s[14:15] offset:256
	s_add_u32 s14, s14, 0x8000
	s_addc_u32 s15, s15, 0
	v_pk_mul_f32 v[68:69], v[68:69], v[198:199] op_sel_hi:[1,0]
	v_pk_mul_f32 v[70:71], v[70:71], v[198:199] op_sel_hi:[1,0]
	v_pk_mul_f32 v[64:65], v[64:65], v[198:199] op_sel_hi:[1,0]
	v_pk_mul_f32 v[66:67], v[66:67], v[198:199] op_sel_hi:[1,0]
	v_pk_mul_f32 v[68:69], v[204:205], v[68:69]
	v_pk_mul_f32 v[70:71], v[206:207], v[70:71]
	v_pk_mul_f32 v[64:65], v[208:209], v[64:65]
	v_pk_mul_f32 v[66:67], v[210:211], v[66:67]
	v_pk_fma_f32 v[68:69], v[220:221], v[68:69], v[236:237]
	v_pk_fma_f32 v[70:71], v[222:223], v[70:71], v[238:239]
	v_pk_fma_f32 v[64:65], v[224:225], v[64:65], v[146:147]
	v_pk_fma_f32 v[66:67], v[226:227], v[66:67], v[148:149]
	v_cvt_pk_bf16_f32 v68, v68, v69
	v_cvt_pk_bf16_f32 v69, v70, v71
	v_cvt_pk_bf16_f32 v70, v64, v65
	v_cvt_pk_bf16_f32 v71, v66, v67
	global_store_dwordx4 v144, v[68:71], s[14:15]
	v_pk_mul_f32 v[246:247], v[246:247], v[198:199] op_sel_hi:[1,0]
	v_pk_mul_f32 v[248:249], v[248:249], v[198:199] op_sel_hi:[1,0]
	v_pk_mul_f32 v[242:243], v[242:243], v[198:199] op_sel_hi:[1,0]
	v_pk_mul_f32 v[244:245], v[244:245], v[198:199] op_sel_hi:[1,0]
	v_pk_mul_f32 v[246:247], v[212:213], v[246:247]
	v_pk_mul_f32 v[248:249], v[214:215], v[248:249]
	v_pk_mul_f32 v[242:243], v[216:217], v[242:243]
	v_pk_mul_f32 v[244:245], v[218:219], v[244:245]
	v_pk_fma_f32 v[246:247], v[228:229], v[246:247], v[150:151]
	v_pk_fma_f32 v[248:249], v[230:231], v[248:249], v[152:153]
	v_pk_fma_f32 v[242:243], v[232:233], v[242:243], v[162:163]
	v_pk_fma_f32 v[244:245], v[234:235], v[244:245], v[164:165]
	v_cvt_pk_bf16_f32 v246, v246, v247
	v_cvt_pk_bf16_f32 v247, v248, v249
	v_cvt_pk_bf16_f32 v248, v242, v243
	v_cvt_pk_bf16_f32 v249, v244, v245
	global_store_dwordx4 v144, v[246:249], s[14:15] offset:256
	s_branch .LBB0_627
	v_readlane_b32 s0, v253, 0
	v_readfirstlane_b32 s1, v2
	s_ashr_i32 s1, s1, 6
	s_lshl_b32 s0, s0, 3
	s_and_b32 s1, s1, -4
	v_lshrrev_b32_e32 v1, 6, v0
	s_add_i32 s1, s1, s0
	v_and_or_b32 v16, v1, 3, s1
	s_movk_i32 s0, 0x4000
	v_cmp_gt_i32_e32 vcc, s0, v16
	s_and_saveexec_b64 s[0:1], vcc
	v_readlane_b32 s26, v254, 47
	v_readlane_b32 s36, v254, 49
	s_movk_i32 s6, 0x3fff
	v_readlane_b32 s27, v254, 48
	v_readlane_b32 s37, v254, 50
	s_cbranch_execz .LBB0_627
	v_readlane_b32 s4, v254, 58
	v_readlane_b32 s5, v254, 59
	v_readlane_b32 s8, v253, 1
	s_lshl_b64 s[4:5], s[4:5], 2
	v_readlane_b32 s12, v253, 5
	v_readlane_b32 s13, v253, 6
	s_add_u32 s4, s12, s4
	v_and_b32_e32 v2, 63, v0
	s_addc_u32 s5, s13, s5
	v_lshlrev_b32_e32 v136, 5, v2
	v_lshl_add_u64 v[18:19], s[4:5], 0, v[136:137]
	v_readlane_b32 s4, v254, 55
	v_lshlrev_b32_e32 v0, 2, v2
	v_readlane_b32 s5, v254, 56
	v_xor_b32_e32 v29, 64, v0
	v_xor_b32_e32 v34, 0x80, v0
	v_lshl_add_u64 v[0:1], s[4:5], 0, v[136:137]
	s_mov_b64 s[4:5], 0x7000
	v_lshl_add_u64 v[20:21], v[0:1], 0, s[4:5]
	s_mov_b64 s[4:5], 0x6000
	v_ashrrev_i32_e32 v17, 31, v16
	v_lshl_add_u64 v[22:23], v[0:1], 0, s[4:5]
	v_lshlrev_b64 v[0:1], 11, v[16:17]
	v_readlane_b32 s4, v253, 47
	v_lshl_or_b32 v0, v2, 4, v0
	v_readlane_b32 s5, v253, 48
	v_readlane_b32 s9, v253, 2
	v_readlane_b32 s10, v253, 3
	v_lshl_add_u64 v[24:25], s[4:5], 0, v[0:1]
	v_lshlrev_b64 v[0:1], 12, v[16:17]
	v_or_b32_e32 v0, v0, v136
	v_lshl_add_u64 v[26:27], s[70:71], 0, v[0:1]
	s_mov_b64 s[4:5], 0
	v_readlane_b32 s11, v253, 4
	v_readlane_b32 s14, v253, 7
	v_readlane_b32 s15, v253, 8

.Lt2_skip_up2:
	v_mov_b32_e32 v128, v154
	v_mul_f32_e32 v130, 0xbfb8aa3b, v121
	v_ashrrev_i32_e32 v129, 2, v128
	v_and_b32_e32 v129, 0xffffffc0, v129
	v_lshl_add_u32 v129, s12, 8, v129
	v_and_or_b32 v132, v128, 15, v129
	v_mul_f32_e32 v129, 0xbfb8aa3b, v120
	v_exp_f32_e32 v129, v129
	v_exp_f32_e32 v130, v130
	v_lshrrev_b32_e32 v131, 1, v128
	s_add_i32 s8, s8, s74
	v_add_f32_e32 v128, 1.0, v129
	v_add_f32_e32 v129, 1.0, v130
	v_rcp_f32_e32 v128, v128
	v_rcp_f32_e32 v129, v129
	v_and_b32_e32 v130, 0x78, v131
	v_lshl_or_b32 v130, s0, 7, v130
	v_readlane_b32 s0, v255, 2
	v_pk_mul_f32 v[120:121], v[120:121], v[128:129]
	v_mul_f32_e32 v128, 0xbfb8aa3b, v122
	v_mul_f32_e32 v129, 0xbfb8aa3b, v123
	v_exp_f32_e32 v128, v128
	v_exp_f32_e32 v129, v129
	v_pk_mul_f32 v[120:121], v[120:121], v[124:125]
	v_readlane_b32 s1, v255, 3
	v_add_f32_e32 v124, 1.0, v128
	v_add_f32_e32 v125, 1.0, v129
	v_mul_f32_e32 v128, 0xbfb8aa3b, v112
	v_mul_f32_e32 v129, 0xbfb8aa3b, v113
	v_rcp_f32_e32 v124, v124
	v_rcp_f32_e32 v125, v125
	v_exp_f32_e32 v128, v128
	v_exp_f32_e32 v129, v129
	v_ashrrev_i32_e32 v131, 31, v130
	v_pk_mul_f32 v[122:123], v[122:123], v[124:125]
	v_add_f32_e32 v124, 1.0, v128
	v_add_f32_e32 v125, 1.0, v129
	v_mul_f32_e32 v128, 0xbfb8aa3b, v114
	v_mul_f32_e32 v129, 0xbfb8aa3b, v115
	v_exp_f32_e32 v128, v128
	v_exp_f32_e32 v129, v129
	v_rcp_f32_e32 v124, v124
	v_rcp_f32_e32 v125, v125
	v_add_f32_e32 v128, 1.0, v128
	v_add_f32_e32 v129, 1.0, v129
	v_rcp_f32_e32 v128, v128
	v_rcp_f32_e32 v129, v129
	v_pk_mul_f32 v[112:113], v[112:113], v[124:125]
	v_pk_mul_f32 v[122:123], v[122:123], v[126:127]
	v_pk_mul_f32 v[112:113], v[112:113], v[116:117]
	v_pk_mul_f32 v[114:115], v[114:115], v[128:129]
	v_cvt_pk_bf16_f32 v116, v120, v121
	v_pk_mul_f32 v[114:115], v[114:115], v[118:119]
	v_cvt_pk_bf16_f32 v118, v112, v113
	v_cvt_pk_bf16_f32 v119, v114, v115
	v_mul_f32_e32 v114, 0xbfb8aa3b, v104
	v_exp_f32_e32 v114, v114
	v_mul_f32_e32 v115, 0xbfb8aa3b, v105
	v_exp_f32_e32 v115, v115
	v_mov_b64_e32 v[112:113], s[0:1]
	v_add_f32_e32 v114, 1.0, v114
	v_rcp_f32_e32 v120, v114
	v_add_f32_e32 v114, 1.0, v115
	v_mad_i64_i32 v[112:113], s[0:1], v132, s33, v[112:113]
	v_rcp_f32_e32 v121, v114
	v_lshlrev_b64 v[114:115], 1, v[130:131]
	v_cvt_pk_bf16_f32 v117, v122, v123
	v_lshl_add_u64 v[112:113], v[112:113], 0, v[114:115]
	global_store_dwordx4 v[112:113], v[116:119], off
	v_pk_mul_f32 v[104:105], v[104:105], v[120:121]
	v_readlane_b32 s0, v253, 51
	v_mul_f32_e32 v116, 0xbfb8aa3b, v106
	v_mul_f32_e32 v117, 0xbfb8aa3b, v107
	v_exp_f32_e32 v116, v116
	v_exp_f32_e32 v117, v117
	v_pk_mul_f32 v[104:105], v[104:105], v[108:109]
	v_readlane_b32 s1, v253, 52
	v_add_f32_e32 v108, 1.0, v116
	v_add_f32_e32 v109, 1.0, v117
	v_mul_f32_e32 v116, 0xbfb8aa3b, v96
	v_mul_f32_e32 v117, 0xbfb8aa3b, v97
	v_rcp_f32_e32 v108, v108
	v_rcp_f32_e32 v109, v109
	v_exp_f32_e32 v116, v116
	v_exp_f32_e32 v117, v117
	s_add_i32 s11, s11, s20
	v_pk_mul_f32 v[106:107], v[106:107], v[108:109]
	v_add_f32_e32 v108, 1.0, v116
	v_add_f32_e32 v109, 1.0, v117
	v_mul_f32_e32 v116, 0xbfb8aa3b, v98
	v_mul_f32_e32 v117, 0xbfb8aa3b, v99
	v_exp_f32_e32 v116, v116
	v_exp_f32_e32 v117, v117
	v_rcp_f32_e32 v108, v108
	v_rcp_f32_e32 v109, v109
	v_add_f32_e32 v116, 1.0, v116
	v_add_f32_e32 v117, 1.0, v117
	v_rcp_f32_e32 v116, v116
	v_rcp_f32_e32 v117, v117
	v_pk_mul_f32 v[96:97], v[96:97], v[108:109]
	v_pk_mul_f32 v[106:107], v[106:107], v[110:111]
	v_pk_mul_f32 v[96:97], v[96:97], v[100:101]
	v_pk_mul_f32 v[98:99], v[98:99], v[116:117]
	v_cvt_pk_bf16_f32 v100, v96, v97
	v_pk_mul_f32 v[102:103], v[98:99], v[102:103]
	v_mul_f32_e32 v96, 0xbfb8aa3b, v88
	v_cvt_pk_bf16_f32 v101, v102, v103
	v_exp_f32_e32 v102, v96
	v_mul_f32_e32 v96, 0xbfb8aa3b, v89
	v_exp_f32_e32 v103, v96
	v_mov_b64_e32 v[96:97], s[0:1]
	v_mad_i64_i32 v[96:97], s[0:1], v132, s33, v[96:97]
	v_cvt_pk_bf16_f32 v98, v104, v105
	v_cvt_pk_bf16_f32 v99, v106, v107
	v_add_f32_e32 v102, 1.0, v102
	v_add_f32_e32 v103, 1.0, v103
	v_lshl_add_u64 v[96:97], v[96:97], 0, v[114:115]
	v_rcp_f32_e32 v102, v102
	v_rcp_f32_e32 v103, v103
	global_store_dwordx4 v[96:97], v[98:101], off
	v_readlane_b32 s0, v253, 53
	v_readlane_b32 s1, v253, 54
	v_mul_f32_e32 v98, 0xbfb8aa3b, v90
	v_mul_f32_e32 v99, 0xbfb8aa3b, v91
	v_exp_f32_e32 v98, v98
	v_exp_f32_e32 v99, v99
	v_pk_mul_f32 v[88:89], v[88:89], v[102:103]
	s_cmpk_lt_i32 s8, 0x580
	v_pk_mul_f32 v[88:89], v[88:89], v[92:93]
	v_add_f32_e32 v92, 1.0, v98
	v_add_f32_e32 v93, 1.0, v99
	v_mul_f32_e32 v98, 0xbfb8aa3b, v80
	v_mul_f32_e32 v99, 0xbfb8aa3b, v81
	v_rcp_f32_e32 v92, v92
	v_rcp_f32_e32 v93, v93
	v_exp_f32_e32 v98, v98
	v_exp_f32_e32 v99, v99
	v_pk_mul_f32 v[90:91], v[90:91], v[92:93]
	v_add_f32_e32 v92, 1.0, v98
	v_add_f32_e32 v93, 1.0, v99
	v_mul_f32_e32 v98, 0xbfb8aa3b, v82
	v_mul_f32_e32 v99, 0xbfb8aa3b, v83
	v_exp_f32_e32 v98, v98
	v_exp_f32_e32 v99, v99
	v_rcp_f32_e32 v92, v92
	v_rcp_f32_e32 v93, v93
	v_add_f32_e32 v98, 1.0, v98
	v_add_f32_e32 v99, 1.0, v99
	v_rcp_f32_e32 v98, v98
	v_rcp_f32_e32 v99, v99
	v_pk_mul_f32 v[80:81], v[80:81], v[92:93]
	v_pk_mul_f32 v[90:91], v[90:91], v[94:95]
	v_pk_mul_f32 v[80:81], v[80:81], v[84:85]
	v_pk_mul_f32 v[82:83], v[82:83], v[98:99]
	v_cvt_pk_bf16_f32 v84, v80, v81
	v_pk_mul_f32 v[86:87], v[82:83], v[86:87]
	v_mul_f32_e32 v80, 0xbfb8aa3b, v72
	v_cvt_pk_bf16_f32 v85, v86, v87
	v_exp_f32_e32 v86, v80
	v_mul_f32_e32 v80, 0xbfb8aa3b, v73
	v_exp_f32_e32 v87, v80
	v_mov_b64_e32 v[80:81], s[0:1]
	v_mad_i64_i32 v[80:81], s[0:1], v132, s33, v[80:81]
	v_cvt_pk_bf16_f32 v82, v88, v89
	v_cvt_pk_bf16_f32 v83, v90, v91
	v_add_f32_e32 v86, 1.0, v86
	v_add_f32_e32 v87, 1.0, v87
	v_lshl_add_u64 v[80:81], v[80:81], 0, v[114:115]
	v_rcp_f32_e32 v86, v86
	v_rcp_f32_e32 v87, v87
	global_store_dwordx4 v[80:81], v[82:85], off
	v_readlane_b32 s0, v253, 55
	v_readlane_b32 s1, v253, 56
	v_mul_f32_e32 v82, 0xbfb8aa3b, v74
	v_mul_f32_e32 v83, 0xbfb8aa3b, v75
	v_exp_f32_e32 v82, v82
	v_exp_f32_e32 v83, v83
	v_pk_mul_f32 v[72:73], v[72:73], v[86:87]
	s_nop 0
	v_pk_mul_f32 v[72:73], v[72:73], v[76:77]
	v_add_f32_e32 v76, 1.0, v82
	v_add_f32_e32 v77, 1.0, v83
	v_mul_f32_e32 v82, 0xbfb8aa3b, v64
	v_mul_f32_e32 v83, 0xbfb8aa3b, v65
	v_rcp_f32_e32 v76, v76
	v_rcp_f32_e32 v77, v77
	v_exp_f32_e32 v82, v82
	v_exp_f32_e32 v83, v83
	v_pk_mul_f32 v[74:75], v[74:75], v[76:77]
	v_add_f32_e32 v76, 1.0, v82
	v_add_f32_e32 v77, 1.0, v83
	v_mul_f32_e32 v82, 0xbfb8aa3b, v66
	v_mul_f32_e32 v83, 0xbfb8aa3b, v67
	v_exp_f32_e32 v82, v82
	v_exp_f32_e32 v83, v83
	v_rcp_f32_e32 v76, v76
	v_rcp_f32_e32 v77, v77
	v_add_f32_e32 v82, 1.0, v82
	v_add_f32_e32 v83, 1.0, v83
	v_rcp_f32_e32 v82, v82
	v_rcp_f32_e32 v83, v83
	v_pk_mul_f32 v[64:65], v[64:65], v[76:77]
	v_pk_mul_f32 v[74:75], v[74:75], v[78:79]
	v_pk_mul_f32 v[64:65], v[64:65], v[68:69]
	v_pk_mul_f32 v[66:67], v[66:67], v[82:83]
	v_cvt_pk_bf16_f32 v68, v64, v65
	v_pk_mul_f32 v[70:71], v[66:67], v[70:71]
	v_mul_f32_e32 v64, 0xbfb8aa3b, v60
	v_cvt_pk_bf16_f32 v69, v70, v71
	v_exp_f32_e32 v70, v64
	v_mul_f32_e32 v64, 0xbfb8aa3b, v61
	v_exp_f32_e32 v71, v64
	v_mov_b64_e32 v[64:65], s[0:1]
	v_mad_i64_i32 v[64:65], s[0:1], v132, s33, v[64:65]
	v_cvt_pk_bf16_f32 v66, v72, v73
	v_cvt_pk_bf16_f32 v67, v74, v75
	v_add_f32_e32 v70, 1.0, v70
	v_add_f32_e32 v71, 1.0, v71
	v_lshl_add_u64 v[64:65], v[64:65], 0, v[114:115]
	v_rcp_f32_e32 v70, v70
	v_rcp_f32_e32 v71, v71
	global_store_dwordx4 v[64:65], v[66:69], off
	s_mov_b32 s0, 0xb0000
	v_pk_mul_f32 v[60:61], v[60:61], v[70:71]
	v_mul_f32_e32 v66, 0xbfb8aa3b, v62
	v_mul_f32_e32 v67, 0xbfb8aa3b, v63
	v_exp_f32_e32 v66, v66
	v_exp_f32_e32 v67, v67
	v_pk_mul_f32 v[56:57], v[60:61], v[56:57]
	v_add_f32_e32 v60, 1.0, v66
	v_add_f32_e32 v61, 1.0, v67
	v_mul_f32_e32 v66, 0xbfb8aa3b, v48
	v_mul_f32_e32 v67, 0xbfb8aa3b, v49
	v_rcp_f32_e32 v60, v60
	v_rcp_f32_e32 v61, v61
	v_exp_f32_e32 v66, v66
	v_exp_f32_e32 v67, v67
	v_pk_mul_f32 v[60:61], v[62:63], v[60:61]
	v_add_f32_e32 v62, 1.0, v66
	v_add_f32_e32 v63, 1.0, v67
	v_mul_f32_e32 v66, 0xbfb8aa3b, v50
	v_mul_f32_e32 v67, 0xbfb8aa3b, v51
	v_exp_f32_e32 v66, v66
	v_exp_f32_e32 v67, v67
	v_rcp_f32_e32 v62, v62
	v_rcp_f32_e32 v63, v63
	v_add_f32_e32 v66, 1.0, v66
	v_add_f32_e32 v67, 1.0, v67
	v_rcp_f32_e32 v66, v66
	v_rcp_f32_e32 v67, v67
	v_pk_mul_f32 v[48:49], v[48:49], v[62:63]
	v_pk_mul_f32 v[58:59], v[60:61], v[58:59]
	v_pk_mul_f32 v[52:53], v[48:49], v[52:53]
	v_pk_mul_f32 v[48:49], v[50:51], v[66:67]
	v_mul_f32_e32 v51, 0xbfb8aa3b, v44
	v_cvt_pk_bf16_f32 v50, v52, v53
	v_exp_f32_e32 v52, v51
	v_mul_f32_e32 v51, 0xbfb8aa3b, v45
	v_exp_f32_e32 v53, v51
	v_pk_mul_f32 v[54:55], v[48:49], v[54:55]
	v_cvt_pk_bf16_f32 v48, v56, v57
	v_cvt_pk_bf16_f32 v51, v54, v55
	v_add_co_u32_e32 v54, vcc, s0, v112
	v_cvt_pk_bf16_f32 v49, v58, v59
	v_add_f32_e32 v52, 1.0, v52
	v_add_f32_e32 v53, 1.0, v53
	v_addc_co_u32_e32 v55, vcc, 0, v113, vcc
	v_rcp_f32_e32 v52, v52
	v_rcp_f32_e32 v53, v53
	global_store_dwordx4 v[54:55], v[48:51], off
	v_pk_mul_f32 v[44:45], v[44:45], v[52:53]
	s_nop 0
	v_mul_f32_e32 v48, 0xbfb8aa3b, v46
	v_mul_f32_e32 v49, 0xbfb8aa3b, v47
	v_exp_f32_e32 v48, v48
	v_exp_f32_e32 v49, v49
	v_pk_mul_f32 v[40:41], v[44:45], v[40:41]
	v_add_f32_e32 v44, 1.0, v48
	v_add_f32_e32 v45, 1.0, v49
	v_mul_f32_e32 v48, 0xbfb8aa3b, v32
	v_mul_f32_e32 v49, 0xbfb8aa3b, v33
	v_rcp_f32_e32 v44, v44
	v_rcp_f32_e32 v45, v45
	v_exp_f32_e32 v48, v48
	v_exp_f32_e32 v49, v49
	v_pk_mul_f32 v[44:45], v[46:47], v[44:45]
	v_add_f32_e32 v46, 1.0, v48
	v_add_f32_e32 v47, 1.0, v49
	v_mul_f32_e32 v48, 0xbfb8aa3b, v34
	v_mul_f32_e32 v49, 0xbfb8aa3b, v35
	v_exp_f32_e32 v48, v48
	v_exp_f32_e32 v49, v49
	v_rcp_f32_e32 v46, v46
	v_rcp_f32_e32 v47, v47
	v_add_f32_e32 v48, 1.0, v48
	v_add_f32_e32 v49, 1.0, v49
	v_rcp_f32_e32 v48, v48
	v_rcp_f32_e32 v49, v49
	v_pk_mul_f32 v[32:33], v[32:33], v[46:47]
	v_pk_mul_f32 v[42:43], v[44:45], v[42:43]
	v_pk_mul_f32 v[36:37], v[32:33], v[36:37]
	v_pk_mul_f32 v[32:33], v[34:35], v[48:49]
	v_mul_f32_e32 v35, 0xbfb8aa3b, v28
	v_cvt_pk_bf16_f32 v34, v36, v37
	v_exp_f32_e32 v36, v35
	v_mul_f32_e32 v35, 0xbfb8aa3b, v29
	v_exp_f32_e32 v37, v35
	v_pk_mul_f32 v[38:39], v[32:33], v[38:39]
	v_cvt_pk_bf16_f32 v32, v40, v41
	v_cvt_pk_bf16_f32 v35, v38, v39
	v_add_co_u32_e32 v38, vcc, s0, v96
	v_cvt_pk_bf16_f32 v33, v42, v43
	v_add_f32_e32 v36, 1.0, v36
	v_add_f32_e32 v37, 1.0, v37
	v_addc_co_u32_e32 v39, vcc, 0, v97, vcc
	v_rcp_f32_e32 v36, v36
	v_rcp_f32_e32 v37, v37
	global_store_dwordx4 v[38:39], v[32:35], off
	v_pk_mul_f32 v[28:29], v[28:29], v[36:37]
	s_nop 0
	v_mul_f32_e32 v32, 0xbfb8aa3b, v30
	v_mul_f32_e32 v33, 0xbfb8aa3b, v31
	v_exp_f32_e32 v32, v32
	v_exp_f32_e32 v33, v33
	v_pk_mul_f32 v[24:25], v[28:29], v[24:25]
	v_add_f32_e32 v28, 1.0, v32
	v_add_f32_e32 v29, 1.0, v33
	v_mul_f32_e32 v32, 0xbfb8aa3b, v16
	v_mul_f32_e32 v33, 0xbfb8aa3b, v17
	v_rcp_f32_e32 v28, v28
	v_rcp_f32_e32 v29, v29
	v_exp_f32_e32 v32, v32
	v_exp_f32_e32 v33, v33
	v_pk_mul_f32 v[28:29], v[30:31], v[28:29]
	v_add_f32_e32 v30, 1.0, v32
	v_add_f32_e32 v31, 1.0, v33
	v_mul_f32_e32 v32, 0xbfb8aa3b, v18
	v_mul_f32_e32 v33, 0xbfb8aa3b, v19
	v_exp_f32_e32 v32, v32
	v_exp_f32_e32 v33, v33
	v_rcp_f32_e32 v30, v30
	v_rcp_f32_e32 v31, v31
	v_add_f32_e32 v32, 1.0, v32
	v_add_f32_e32 v33, 1.0, v33
	v_rcp_f32_e32 v32, v32
	v_rcp_f32_e32 v33, v33
	v_pk_mul_f32 v[16:17], v[16:17], v[30:31]
	v_pk_mul_f32 v[26:27], v[28:29], v[26:27]
	v_pk_mul_f32 v[20:21], v[16:17], v[20:21]
	v_pk_mul_f32 v[16:17], v[18:19], v[32:33]
	v_mul_f32_e32 v19, 0xbfb8aa3b, v12
	v_cvt_pk_bf16_f32 v18, v20, v21
	v_exp_f32_e32 v20, v19
	v_mul_f32_e32 v19, 0xbfb8aa3b, v13
	v_exp_f32_e32 v21, v19
	v_pk_mul_f32 v[22:23], v[16:17], v[22:23]
	v_cvt_pk_bf16_f32 v16, v24, v25
	v_cvt_pk_bf16_f32 v19, v22, v23
	v_add_co_u32_e32 v22, vcc, s0, v80
	v_cvt_pk_bf16_f32 v17, v26, v27
	v_add_f32_e32 v20, 1.0, v20
	v_add_f32_e32 v21, 1.0, v21
	v_addc_co_u32_e32 v23, vcc, 0, v81, vcc
	v_rcp_f32_e32 v20, v20
	v_rcp_f32_e32 v21, v21
	global_store_dwordx4 v[22:23], v[16:19], off
	v_pk_mul_f32 v[12:13], v[12:13], v[20:21]
	s_nop 0
	v_mul_f32_e32 v16, 0xbfb8aa3b, v14
	v_mul_f32_e32 v17, 0xbfb8aa3b, v15
	v_exp_f32_e32 v16, v16
	v_exp_f32_e32 v17, v17
	v_pk_mul_f32 v[8:9], v[12:13], v[8:9]
	v_add_f32_e32 v12, 1.0, v16
	v_add_f32_e32 v13, 1.0, v17
	v_mul_f32_e32 v16, 0xbfb8aa3b, v0
	v_mul_f32_e32 v17, 0xbfb8aa3b, v1
	v_rcp_f32_e32 v12, v12
	v_rcp_f32_e32 v13, v13
	v_exp_f32_e32 v16, v16
	v_exp_f32_e32 v17, v17
	v_pk_mul_f32 v[12:13], v[14:15], v[12:13]
	v_add_f32_e32 v14, 1.0, v16
	v_add_f32_e32 v15, 1.0, v17
	v_mul_f32_e32 v16, 0xbfb8aa3b, v2
	v_mul_f32_e32 v17, 0xbfb8aa3b, v3
	v_exp_f32_e32 v16, v16
	v_exp_f32_e32 v17, v17
	v_rcp_f32_e32 v14, v14
	v_rcp_f32_e32 v15, v15
	v_add_f32_e32 v16, 1.0, v16
	v_add_f32_e32 v17, 1.0, v17
	v_rcp_f32_e32 v16, v16
	v_rcp_f32_e32 v17, v17
	v_pk_mul_f32 v[0:1], v[0:1], v[14:15]
	v_pk_mul_f32 v[10:11], v[12:13], v[10:11]
	v_pk_mul_f32 v[4:5], v[0:1], v[4:5]
	v_pk_mul_f32 v[0:1], v[2:3], v[16:17]
	v_cvt_pk_bf16_f32 v2, v4, v5
	v_pk_mul_f32 v[6:7], v[0:1], v[6:7]
	v_add_co_u32_e32 v4, vcc, 0xb0000, v64
	v_cvt_pk_bf16_f32 v0, v8, v9
	v_cvt_pk_bf16_f32 v1, v10, v11
	v_cvt_pk_bf16_f32 v3, v6, v7
	v_addc_co_u32_e32 v5, vcc, 0, v65, vcc
	global_store_dwordx4 v[4:5], v[0:3], off
	s_cbranch_scc0 .LBB0_666
	s_branch .LP2_up2

.LBB0_698:
	s_or_b64 exec, exec, s[0:1]
	v_mov_b32_e32 v80, v154
	s_lshr_b32 s1, s10, 3
	v_and_b32_e32 v136, 15, v80
	v_lshrrev_b32_e32 v81, 1, v80
	v_ashrrev_i32_e32 v80, 2, v80
	s_lshl_b32 s0, s12, 8
	s_mul_i32 s1, s1, 0x9000
	v_and_b32_e32 v152, 0xffffffc0, v80
	v_and_b32_e32 v81, 0x78, v81
	s_add_u32 s10, s7, s1
	v_ashrrev_i32_e32 v153, 31, v152
	s_mov_b32 s1, s52
	v_lshl_or_b32 v144, s11, 8, v81
	v_lshl_add_u64 v[140:141], v[152:153], 0, s[0:1]
	v_ashrrev_i32_e32 v145, 31, v144
	v_or_b32_e32 v140, v140, v136
	s_addc_u32 s11, s8, 0
	v_lshlrev_b64 v[150:151], 2, v[144:145]
	v_lshlrev_b64 v[140:141], 12, v[140:141]
	v_lshl_add_u64 v[148:149], s[10:11], 0, v[150:151]
	v_lshl_add_u64 v[170:171], s[70:71], 0, v[140:141]
	v_lshl_add_u64 v[146:147], v[170:171], 0, v[150:151]
	s_nop 1
	v_readfirstlane_b32 s38, v146
	v_readfirstlane_b32 s39, v147
	s_nop 1
	v_subrev_u32_e32 v139, s38, v146
	s_mov_b64 s[40:41], s[38:39]
	s_mov_b64 s[42:43], s[38:39]
	s_mov_b64 s[44:45], s[40:41]
	s_mov_b64 s[46:47], s[42:43]
	global_load_dwordx4 v[234:237], v[148:149], off
	global_load_dwordx4 v[238:241], v[148:149], off offset:16
	global_load_dwordx4 v[242:245], v[148:149], off offset:512
	global_load_dwordx4 v[246:249], v[148:149], off offset:528
	global_load_dwordx4 v[178:181], v139, s[40:41]
	global_load_dwordx4 v[182:185], v139, s[40:41] offset:16
	s_add_u32 s40, s40, 0x10000
	s_addc_u32 s41, s41, 0
	global_load_dwordx4 v[186:189], v139, s[40:41]
	global_load_dwordx4 v[190:193], v139, s[40:41] offset:16
	s_add_u32 s40, s40, 0x10000
	s_addc_u32 s41, s41, 0
	global_load_dwordx4 v[194:197], v139, s[40:41]
	global_load_dwordx4 v[198:201], v139, s[40:41] offset:16
	s_add_u32 s40, s40, 0x10000
	s_addc_u32 s41, s41, 0
	global_load_dwordx4 v[202:205], v139, s[40:41]
	global_load_dwordx4 v[206:209], v139, s[40:41] offset:16
	s_add_u32 s40, s40, 0x50000
	s_addc_u32 s41, s41, 0
	global_load_dwordx4 v[210:213], v139, s[40:41]
	global_load_dwordx4 v[214:217], v139, s[40:41] offset:16
	s_add_u32 s40, s40, 0x10000
	s_addc_u32 s41, s41, 0
	global_load_dwordx4 v[218:221], v139, s[40:41]
	global_load_dwordx4 v[222:225], v139, s[40:41] offset:16
	s_add_u32 s40, s40, 0x10000
	s_addc_u32 s41, s41, 0
	global_load_dwordx4 v[226:229], v139, s[40:41]
	global_load_dwordx4 v[230:233], v139, s[40:41] offset:16
	s_add_u32 s40, s40, 0x10000
	s_addc_u32 s41, s41, 0
	s_waitcnt vmcnt(12)
	v_pk_mul_f32 v[132:133], v[132:133], v[234:235]
	v_pk_mul_f32 v[134:135], v[134:135], v[236:237]
	v_pk_mul_f32 v[128:129], v[128:129], v[238:239]
	v_pk_mul_f32 v[130:131], v[130:131], v[240:241]
	v_pk_fma_f32 v[132:133], v[132:133], 0.5, v[178:179] op_sel_hi:[1,0,1]
	v_pk_fma_f32 v[134:135], v[134:135], 0.5, v[180:181] op_sel_hi:[1,0,1]
	v_pk_fma_f32 v[128:129], v[128:129], 0.5, v[182:183] op_sel_hi:[1,0,1]
	v_pk_fma_f32 v[130:131], v[130:131], 0.5, v[184:185] op_sel_hi:[1,0,1]
	global_store_dwordx4 v139, v[132:135], s[42:43]
	global_store_dwordx4 v139, v[128:131], s[42:43] offset:16
	s_add_u32 s42, s42, 0x10000
	s_addc_u32 s43, s43, 0
	global_load_dwordx4 v[178:181], v139, s[40:41]
	global_load_dwordx4 v[182:185], v139, s[40:41] offset:16
	s_mov_b64 s[40:41], s[44:45]
	s_waitcnt vmcnt(14)
	v_pk_mul_f32 v[124:125], v[124:125], v[234:235]
	v_pk_mul_f32 v[126:127], v[126:127], v[236:237]
	v_pk_mul_f32 v[120:121], v[120:121], v[238:239]
	v_pk_mul_f32 v[122:123], v[122:123], v[240:241]
	v_pk_fma_f32 v[124:125], v[124:125], 0.5, v[186:187] op_sel_hi:[1,0,1]
	v_pk_fma_f32 v[126:127], v[126:127], 0.5, v[188:189] op_sel_hi:[1,0,1]
	v_pk_fma_f32 v[120:121], v[120:121], 0.5, v[190:191] op_sel_hi:[1,0,1]
	v_pk_fma_f32 v[122:123], v[122:123], 0.5, v[192:193] op_sel_hi:[1,0,1]
	global_store_dwordx4 v139, v[124:127], s[42:43]
	global_store_dwordx4 v139, v[120:123], s[42:43] offset:16
	s_add_u32 s42, s42, 0x10000
	s_addc_u32 s43, s43, 0
	global_load_dwordx4 v[186:189], v139, s[40:41] offset:512
	global_load_dwordx4 v[190:193], v139, s[40:41] offset:528
	s_add_u32 s40, s40, 0x10000
	s_addc_u32 s41, s41, 0
	s_waitcnt vmcnt(16)
	v_pk_mul_f32 v[116:117], v[116:117], v[234:235]
	v_pk_mul_f32 v[118:119], v[118:119], v[236:237]
	v_pk_mul_f32 v[112:113], v[112:113], v[238:239]
	v_pk_mul_f32 v[114:115], v[114:115], v[240:241]
	v_pk_fma_f32 v[116:117], v[116:117], 0.5, v[194:195] op_sel_hi:[1,0,1]
	v_pk_fma_f32 v[118:119], v[118:119], 0.5, v[196:197] op_sel_hi:[1,0,1]
	v_pk_fma_f32 v[112:113], v[112:113], 0.5, v[198:199] op_sel_hi:[1,0,1]
	v_pk_fma_f32 v[114:115], v[114:115], 0.5, v[200:201] op_sel_hi:[1,0,1]
	global_store_dwordx4 v139, v[116:119], s[42:43]
	global_store_dwordx4 v139, v[112:115], s[42:43] offset:16
	s_add_u32 s42, s42, 0x10000
	s_addc_u32 s43, s43, 0
	global_load_dwordx4 v[194:197], v139, s[40:41] offset:512
	global_load_dwordx4 v[198:201], v139, s[40:41] offset:528
	s_add_u32 s40, s40, 0x10000
	s_addc_u32 s41, s41, 0
	s_waitcnt vmcnt(18)
	v_pk_mul_f32 v[108:109], v[108:109], v[234:235]
	v_pk_mul_f32 v[110:111], v[110:111], v[236:237]
	v_pk_mul_f32 v[104:105], v[104:105], v[238:239]
	v_pk_mul_f32 v[106:107], v[106:107], v[240:241]
	v_pk_fma_f32 v[108:109], v[108:109], 0.5, v[202:203] op_sel_hi:[1,0,1]
	v_pk_fma_f32 v[110:111], v[110:111], 0.5, v[204:205] op_sel_hi:[1,0,1]
	v_pk_fma_f32 v[104:105], v[104:105], 0.5, v[206:207] op_sel_hi:[1,0,1]
	v_pk_fma_f32 v[106:107], v[106:107], 0.5, v[208:209] op_sel_hi:[1,0,1]
	global_store_dwordx4 v139, v[108:111], s[42:43]
	global_store_dwordx4 v139, v[104:107], s[42:43] offset:16
	s_add_u32 s42, s42, 0x50000
	s_addc_u32 s43, s43, 0
	global_load_dwordx4 v[202:205], v139, s[40:41] offset:512
	global_load_dwordx4 v[206:209], v139, s[40:41] offset:528
	s_add_u32 s40, s40, 0x10000
	s_addc_u32 s41, s41, 0
	s_waitcnt vmcnt(20)
	v_pk_mul_f32 v[100:101], v[100:101], v[234:235]
	v_pk_mul_f32 v[102:103], v[102:103], v[236:237]
	v_pk_mul_f32 v[96:97], v[96:97], v[238:239]
	v_pk_mul_f32 v[98:99], v[98:99], v[240:241]
	v_pk_fma_f32 v[100:101], v[100:101], 0.5, v[210:211] op_sel_hi:[1,0,1]
	v_pk_fma_f32 v[102:103], v[102:103], 0.5, v[212:213] op_sel_hi:[1,0,1]
	v_pk_fma_f32 v[96:97], v[96:97], 0.5, v[214:215] op_sel_hi:[1,0,1]
	v_pk_fma_f32 v[98:99], v[98:99], 0.5, v[216:217] op_sel_hi:[1,0,1]
	global_store_dwordx4 v139, v[100:103], s[42:43]
	global_store_dwordx4 v139, v[96:99], s[42:43] offset:16
	s_add_u32 s42, s42, 0x10000
	s_addc_u32 s43, s43, 0
	global_load_dwordx4 v[210:213], v139, s[40:41] offset:512
	global_load_dwordx4 v[214:217], v139, s[40:41] offset:528
	s_add_u32 s40, s40, 0x50000
	s_addc_u32 s41, s41, 0
	s_waitcnt vmcnt(22)
	v_pk_mul_f32 v[92:93], v[92:93], v[234:235]
	v_pk_mul_f32 v[94:95], v[94:95], v[236:237]
	v_pk_mul_f32 v[88:89], v[88:89], v[238:239]
	v_pk_mul_f32 v[90:91], v[90:91], v[240:241]
	v_pk_fma_f32 v[92:93], v[92:93], 0.5, v[218:219] op_sel_hi:[1,0,1]
	v_pk_fma_f32 v[94:95], v[94:95], 0.5, v[220:221] op_sel_hi:[1,0,1]
	v_pk_fma_f32 v[88:89], v[88:89], 0.5, v[222:223] op_sel_hi:[1,0,1]
	v_pk_fma_f32 v[90:91], v[90:91], 0.5, v[224:225] op_sel_hi:[1,0,1]
	global_store_dwordx4 v139, v[92:95], s[42:43]
	global_store_dwordx4 v139, v[88:91], s[42:43] offset:16
	s_add_u32 s42, s42, 0x10000
	s_addc_u32 s43, s43, 0
	global_load_dwordx4 v[218:221], v139, s[40:41] offset:512
	global_load_dwordx4 v[222:225], v139, s[40:41] offset:528
	s_add_u32 s40, s40, 0x10000
	s_addc_u32 s41, s41, 0
	s_waitcnt vmcnt(24)
	v_pk_mul_f32 v[76:77], v[76:77], v[234:235]
	v_pk_mul_f32 v[78:79], v[78:79], v[236:237]
	v_pk_mul_f32 v[72:73], v[72:73], v[238:239]
	v_pk_mul_f32 v[74:75], v[74:75], v[240:241]
	v_pk_fma_f32 v[76:77], v[76:77], 0.5, v[226:227] op_sel_hi:[1,0,1]
	v_pk_fma_f32 v[78:79], v[78:79], 0.5, v[228:229] op_sel_hi:[1,0,1]
	v_pk_fma_f32 v[72:73], v[72:73], 0.5, v[230:231] op_sel_hi:[1,0,1]
	v_pk_fma_f32 v[74:75], v[74:75], 0.5, v[232:233] op_sel_hi:[1,0,1]
	global_store_dwordx4 v139, v[76:79], s[42:43]
	global_store_dwordx4 v139, v[72:75], s[42:43] offset:16
	s_add_u32 s42, s42, 0x10000
	s_addc_u32 s43, s43, 0
	global_load_dwordx4 v[226:229], v139, s[40:41] offset:512
	global_load_dwordx4 v[230:233], v139, s[40:41] offset:528
	s_add_u32 s40, s40, 0x10000
	s_addc_u32 s41, s41, 0
	s_waitcnt vmcnt(24)
	v_pk_mul_f32 v[68:69], v[68:69], v[234:235]
	v_pk_mul_f32 v[70:71], v[70:71], v[236:237]
	v_pk_mul_f32 v[64:65], v[64:65], v[238:239]
	v_pk_mul_f32 v[66:67], v[66:67], v[240:241]
	v_pk_fma_f32 v[68:69], v[68:69], 0.5, v[178:179] op_sel_hi:[1,0,1]
	v_pk_fma_f32 v[70:71], v[70:71], 0.5, v[180:181] op_sel_hi:[1,0,1]
	v_pk_fma_f32 v[64:65], v[64:65], 0.5, v[182:183] op_sel_hi:[1,0,1]
	v_pk_fma_f32 v[66:67], v[66:67], 0.5, v[184:185] op_sel_hi:[1,0,1]
	global_store_dwordx4 v139, v[68:71], s[42:43]
	global_store_dwordx4 v139, v[64:67], s[42:43] offset:16
	s_mov_b64 s[42:43], s[46:47]
	global_load_dwordx4 v[178:181], v139, s[40:41] offset:512
	global_load_dwordx4 v[182:185], v139, s[40:41] offset:528
	s_add_u32 s40, s40, 0x10000
	s_addc_u32 s41, s41, 0
	s_waitcnt vmcnt(24)
	v_pk_mul_f32 v[60:61], v[60:61], v[242:243]
	v_pk_mul_f32 v[62:63], v[62:63], v[244:245]
	v_pk_mul_f32 v[56:57], v[56:57], v[246:247]
	v_pk_mul_f32 v[58:59], v[58:59], v[248:249]
	v_pk_fma_f32 v[60:61], v[60:61], 0.5, v[186:187] op_sel_hi:[1,0,1]
	v_pk_fma_f32 v[62:63], v[62:63], 0.5, v[188:189] op_sel_hi:[1,0,1]
	v_pk_fma_f32 v[56:57], v[56:57], 0.5, v[190:191] op_sel_hi:[1,0,1]
	v_pk_fma_f32 v[58:59], v[58:59], 0.5, v[192:193] op_sel_hi:[1,0,1]
	global_store_dwordx4 v139, v[60:63], s[42:43] offset:512
	global_store_dwordx4 v139, v[56:59], s[42:43] offset:528
	s_add_u32 s42, s42, 0x10000
	s_addc_u32 s43, s43, 0
	global_load_dwordx4 v[186:189], v139, s[40:41] offset:512
	global_load_dwordx4 v[190:193], v139, s[40:41] offset:528
	s_waitcnt vmcnt(24)
	v_pk_mul_f32 v[52:53], v[52:53], v[242:243]
	v_pk_mul_f32 v[54:55], v[54:55], v[244:245]
	v_pk_mul_f32 v[48:49], v[48:49], v[246:247]
	v_pk_mul_f32 v[50:51], v[50:51], v[248:249]
	v_pk_fma_f32 v[52:53], v[52:53], 0.5, v[194:195] op_sel_hi:[1,0,1]
	v_pk_fma_f32 v[54:55], v[54:55], 0.5, v[196:197] op_sel_hi:[1,0,1]
	v_pk_fma_f32 v[48:49], v[48:49], 0.5, v[198:199] op_sel_hi:[1,0,1]
	v_pk_fma_f32 v[50:51], v[50:51], 0.5, v[200:201] op_sel_hi:[1,0,1]
	global_store_dwordx4 v139, v[52:55], s[42:43] offset:512
	global_store_dwordx4 v139, v[48:51], s[42:43] offset:528
	s_add_u32 s42, s42, 0x10000
	s_addc_u32 s43, s43, 0
	s_waitcnt vmcnt(22)
	v_pk_mul_f32 v[44:45], v[44:45], v[242:243]
	v_pk_mul_f32 v[46:47], v[46:47], v[244:245]
	v_pk_mul_f32 v[40:41], v[40:41], v[246:247]
	v_pk_mul_f32 v[42:43], v[42:43], v[248:249]
	v_pk_fma_f32 v[44:45], v[44:45], 0.5, v[202:203] op_sel_hi:[1,0,1]
	v_pk_fma_f32 v[46:47], v[46:47], 0.5, v[204:205] op_sel_hi:[1,0,1]
	v_pk_fma_f32 v[40:41], v[40:41], 0.5, v[206:207] op_sel_hi:[1,0,1]
	v_pk_fma_f32 v[42:43], v[42:43], 0.5, v[208:209] op_sel_hi:[1,0,1]
	global_store_dwordx4 v139, v[44:47], s[42:43] offset:512
	global_store_dwordx4 v139, v[40:43], s[42:43] offset:528
	s_add_u32 s42, s42, 0x10000
	s_addc_u32 s43, s43, 0
	s_waitcnt vmcnt(20)
	v_pk_mul_f32 v[36:37], v[36:37], v[242:243]
	v_pk_mul_f32 v[38:39], v[38:39], v[244:245]
	v_pk_mul_f32 v[32:33], v[32:33], v[246:247]
	v_pk_mul_f32 v[34:35], v[34:35], v[248:249]
	v_pk_fma_f32 v[36:37], v[36:37], 0.5, v[210:211] op_sel_hi:[1,0,1]
	v_pk_fma_f32 v[38:39], v[38:39], 0.5, v[212:213] op_sel_hi:[1,0,1]
	v_pk_fma_f32 v[32:33], v[32:33], 0.5, v[214:215] op_sel_hi:[1,0,1]
	v_pk_fma_f32 v[34:35], v[34:35], 0.5, v[216:217] op_sel_hi:[1,0,1]
	global_store_dwordx4 v139, v[36:39], s[42:43] offset:512
	global_store_dwordx4 v139, v[32:35], s[42:43] offset:528
	s_add_u32 s42, s42, 0x50000
	s_addc_u32 s43, s43, 0
	s_waitcnt vmcnt(18)
	v_pk_mul_f32 v[28:29], v[28:29], v[242:243]
	v_pk_mul_f32 v[30:31], v[30:31], v[244:245]
	v_pk_mul_f32 v[24:25], v[24:25], v[246:247]
	v_pk_mul_f32 v[26:27], v[26:27], v[248:249]
	v_pk_fma_f32 v[28:29], v[28:29], 0.5, v[218:219] op_sel_hi:[1,0,1]
	v_pk_fma_f32 v[30:31], v[30:31], 0.5, v[220:221] op_sel_hi:[1,0,1]
	v_pk_fma_f32 v[24:25], v[24:25], 0.5, v[222:223] op_sel_hi:[1,0,1]
	v_pk_fma_f32 v[26:27], v[26:27], 0.5, v[224:225] op_sel_hi:[1,0,1]
	global_store_dwordx4 v139, v[28:31], s[42:43] offset:512
	global_store_dwordx4 v139, v[24:27], s[42:43] offset:528
	s_add_u32 s42, s42, 0x10000
	s_addc_u32 s43, s43, 0
	s_waitcnt vmcnt(16)
	v_pk_mul_f32 v[20:21], v[20:21], v[242:243]
	v_pk_mul_f32 v[22:23], v[22:23], v[244:245]
	v_pk_mul_f32 v[16:17], v[16:17], v[246:247]
	v_pk_mul_f32 v[18:19], v[18:19], v[248:249]
	v_pk_fma_f32 v[20:21], v[20:21], 0.5, v[226:227] op_sel_hi:[1,0,1]
	v_pk_fma_f32 v[22:23], v[22:23], 0.5, v[228:229] op_sel_hi:[1,0,1]
	v_pk_fma_f32 v[16:17], v[16:17], 0.5, v[230:231] op_sel_hi:[1,0,1]
	v_pk_fma_f32 v[18:19], v[18:19], 0.5, v[232:233] op_sel_hi:[1,0,1]
	global_store_dwordx4 v139, v[20:23], s[42:43] offset:512
	global_store_dwordx4 v139, v[16:19], s[42:43] offset:528
	s_add_u32 s42, s42, 0x10000
	s_addc_u32 s43, s43, 0
	s_waitcnt vmcnt(14)
	v_pk_mul_f32 v[12:13], v[12:13], v[242:243]
	v_pk_mul_f32 v[14:15], v[14:15], v[244:245]
	v_pk_mul_f32 v[8:9], v[8:9], v[246:247]
	v_pk_mul_f32 v[10:11], v[10:11], v[248:249]
	v_pk_fma_f32 v[12:13], v[12:13], 0.5, v[178:179] op_sel_hi:[1,0,1]
	v_pk_fma_f32 v[14:15], v[14:15], 0.5, v[180:181] op_sel_hi:[1,0,1]
	v_pk_fma_f32 v[8:9], v[8:9], 0.5, v[182:183] op_sel_hi:[1,0,1]
	v_pk_fma_f32 v[10:11], v[10:11], 0.5, v[184:185] op_sel_hi:[1,0,1]
	global_store_dwordx4 v139, v[12:15], s[42:43] offset:512
	global_store_dwordx4 v139, v[8:11], s[42:43] offset:528
	s_add_u32 s42, s42, 0x10000
	s_addc_u32 s43, s43, 0
	s_waitcnt vmcnt(12)
	v_pk_mul_f32 v[4:5], v[4:5], v[242:243]
	v_pk_mul_f32 v[6:7], v[6:7], v[244:245]
	v_pk_mul_f32 v[0:1], v[0:1], v[246:247]
	v_pk_mul_f32 v[2:3], v[2:3], v[248:249]
	v_pk_fma_f32 v[4:5], v[4:5], 0.5, v[186:187] op_sel_hi:[1,0,1]
	v_pk_fma_f32 v[6:7], v[6:7], 0.5, v[188:189] op_sel_hi:[1,0,1]
	v_pk_fma_f32 v[0:1], v[0:1], 0.5, v[190:191] op_sel_hi:[1,0,1]
	v_pk_fma_f32 v[2:3], v[2:3], 0.5, v[192:193] op_sel_hi:[1,0,1]
	global_store_dwordx4 v139, v[4:7], s[42:43] offset:512
	global_store_dwordx4 v139, v[0:3], s[42:43] offset:528
	v_pk_mul_f32 v[200:201], v[132:133], v[132:133]
	v_pk_mul_f32 v[202:203], v[124:125], v[124:125]
	v_pk_mul_f32 v[204:205], v[116:117], v[116:117]
	v_pk_mul_f32 v[206:207], v[108:109], v[108:109]
	v_pk_mul_f32 v[208:209], v[100:101], v[100:101]
	v_pk_mul_f32 v[210:211], v[92:93], v[92:93]
	v_pk_mul_f32 v[212:213], v[76:77], v[76:77]
	v_pk_mul_f32 v[214:215], v[68:69], v[68:69]
	v_pk_fma_f32 v[200:201], v[134:135], v[134:135], v[200:201]
	v_pk_fma_f32 v[202:203], v[126:127], v[126:127], v[202:203]
	v_pk_fma_f32 v[204:205], v[118:119], v[118:119], v[204:205]
	v_pk_fma_f32 v[206:207], v[110:111], v[110:111], v[206:207]
	v_pk_fma_f32 v[208:209], v[102:103], v[102:103], v[208:209]
	v_pk_fma_f32 v[210:211], v[94:95], v[94:95], v[210:211]
	v_pk_fma_f32 v[212:213], v[78:79], v[78:79], v[212:213]
	v_pk_fma_f32 v[214:215], v[70:71], v[70:71], v[214:215]
	v_pk_fma_f32 v[200:201], v[128:129], v[128:129], v[200:201]
	v_pk_fma_f32 v[202:203], v[120:121], v[120:121], v[202:203]
	v_pk_fma_f32 v[204:205], v[112:113], v[112:113], v[204:205]
	v_pk_fma_f32 v[206:207], v[104:105], v[104:105], v[206:207]
	v_pk_fma_f32 v[208:209], v[96:97], v[96:97], v[208:209]
	v_pk_fma_f32 v[210:211], v[88:89], v[88:89], v[210:211]
	v_pk_fma_f32 v[212:213], v[72:73], v[72:73], v[212:213]
	v_pk_fma_f32 v[214:215], v[64:65], v[64:65], v[214:215]
	v_pk_fma_f32 v[200:201], v[130:131], v[130:131], v[200:201]
	v_pk_fma_f32 v[202:203], v[122:123], v[122:123], v[202:203]
	v_pk_fma_f32 v[204:205], v[114:115], v[114:115], v[204:205]
	v_pk_fma_f32 v[206:207], v[106:107], v[106:107], v[206:207]
	v_pk_fma_f32 v[208:209], v[98:99], v[98:99], v[208:209]
	v_pk_fma_f32 v[210:211], v[90:91], v[90:91], v[210:211]
	v_pk_fma_f32 v[212:213], v[74:75], v[74:75], v[212:213]
	v_pk_fma_f32 v[214:215], v[66:67], v[66:67], v[214:215]
	v_pk_fma_f32 v[200:201], v[60:61], v[60:61], v[200:201]
	v_pk_fma_f32 v[202:203], v[52:53], v[52:53], v[202:203]
	v_pk_fma_f32 v[204:205], v[44:45], v[44:45], v[204:205]
	v_pk_fma_f32 v[206:207], v[36:37], v[36:37], v[206:207]
	v_pk_fma_f32 v[208:209], v[28:29], v[28:29], v[208:209]
	v_pk_fma_f32 v[210:211], v[20:21], v[20:21], v[210:211]
	v_pk_fma_f32 v[212:213], v[12:13], v[12:13], v[212:213]
	v_pk_fma_f32 v[214:215], v[4:5], v[4:5], v[214:215]
	v_pk_fma_f32 v[200:201], v[62:63], v[62:63], v[200:201]
	v_pk_fma_f32 v[202:203], v[54:55], v[54:55], v[202:203]
	v_pk_fma_f32 v[204:205], v[46:47], v[46:47], v[204:205]
	v_pk_fma_f32 v[206:207], v[38:39], v[38:39], v[206:207]
	v_pk_fma_f32 v[208:209], v[30:31], v[30:31], v[208:209]
	v_pk_fma_f32 v[210:211], v[22:23], v[22:23], v[210:211]
	v_pk_fma_f32 v[212:213], v[14:15], v[14:15], v[212:213]
	v_pk_fma_f32 v[214:215], v[6:7], v[6:7], v[214:215]
	v_pk_fma_f32 v[200:201], v[56:57], v[56:57], v[200:201]
	v_pk_fma_f32 v[202:203], v[48:49], v[48:49], v[202:203]
	v_pk_fma_f32 v[204:205], v[40:41], v[40:41], v[204:205]
	v_pk_fma_f32 v[206:207], v[32:33], v[32:33], v[206:207]
	v_pk_fma_f32 v[208:209], v[24:25], v[24:25], v[208:209]
	v_pk_fma_f32 v[210:211], v[16:17], v[16:17], v[210:211]
	v_pk_fma_f32 v[212:213], v[8:9], v[8:9], v[212:213]
	v_pk_fma_f32 v[214:215], v[0:1], v[0:1], v[214:215]
	v_pk_fma_f32 v[200:201], v[58:59], v[58:59], v[200:201]
	v_pk_fma_f32 v[202:203], v[50:51], v[50:51], v[202:203]
	v_pk_fma_f32 v[204:205], v[42:43], v[42:43], v[204:205]
	v_pk_fma_f32 v[206:207], v[34:35], v[34:35], v[206:207]
	v_pk_fma_f32 v[208:209], v[26:27], v[26:27], v[208:209]
	v_pk_fma_f32 v[210:211], v[18:19], v[18:19], v[210:211]
	v_pk_fma_f32 v[212:213], v[10:11], v[10:11], v[212:213]
	v_pk_fma_f32 v[214:215], v[2:3], v[2:3], v[214:215]
	v_add_f32_e32 v216, v200, v201
	v_add_f32_e32 v217, v202, v203
	v_add_f32_e32 v218, v204, v205
	v_add_f32_e32 v219, v206, v207
	v_add_f32_e32 v220, v208, v209
	v_add_f32_e32 v221, v210, v211
	v_add_f32_e32 v222, v212, v213
	v_add_f32_e32 v223, v214, v215
	v_and_b32_e32 v224, 63, v154
	v_xor_b32_e32 v225, 32, v224
	v_xor_b32_e32 v224, 16, v224
	v_lshlrev_b32_e32 v224, 2, v224
	v_lshlrev_b32_e32 v225, 2, v225
	ds_bpermute_b32 v226, v224, v216
	ds_bpermute_b32 v227, v224, v217
	ds_bpermute_b32 v228, v224, v218
	ds_bpermute_b32 v229, v224, v219
	ds_bpermute_b32 v230, v224, v220
	ds_bpermute_b32 v231, v224, v221
	ds_bpermute_b32 v232, v224, v222
	ds_bpermute_b32 v233, v224, v223
	s_waitcnt lgkmcnt(0)
	v_add_f32_e32 v216, v216, v226
	v_add_f32_e32 v217, v217, v227
	v_add_f32_e32 v218, v218, v228
	v_add_f32_e32 v219, v219, v229
	v_add_f32_e32 v220, v220, v230
	v_add_f32_e32 v221, v221, v231
	v_add_f32_e32 v222, v222, v232
	v_add_f32_e32 v223, v223, v233
	ds_bpermute_b32 v226, v225, v216
	ds_bpermute_b32 v227, v225, v217
	ds_bpermute_b32 v228, v225, v218
	ds_bpermute_b32 v229, v225, v219
	ds_bpermute_b32 v230, v225, v220
	ds_bpermute_b32 v231, v225, v221
	ds_bpermute_b32 v232, v225, v222
	ds_bpermute_b32 v233, v225, v223
	s_waitcnt lgkmcnt(0)
	v_add_f32_e32 v216, v216, v226
	v_add_f32_e32 v217, v217, v227
	v_add_f32_e32 v218, v218, v228
	v_add_f32_e32 v219, v219, v229
	v_add_f32_e32 v220, v220, v230
	v_add_f32_e32 v221, v221, v231
	v_add_f32_e32 v222, v222, v232
	v_add_f32_e32 v223, v223, v233
	v_bfe_u32 v234, v154, 6, 2
	v_lshlrev_b32_e32 v234, 8, v234
	v_lshrrev_b32_e32 v235, 8, v154
	v_lshl_add_u32 v234, v235, 6, v234
	v_and_b32_e32 v235, 15, v154
	v_add_u32_e32 v234, v234, v235
	v_lshlrev_b32_e32 v234, 2, v234
	ds_write_b32 v234, v216 offset:0
	ds_write_b32 v234, v217 offset:64
	ds_write_b32 v234, v218 offset:128
	ds_write_b32 v234, v219 offset:192
	ds_write_b32 v234, v220 offset:512
	ds_write_b32 v234, v221 offset:576
	ds_write_b32 v234, v222 offset:640
	ds_write_b32 v234, v223 offset:704
	s_waitcnt lgkmcnt(0)
	s_barrier
	v_cmp_gt_u32_e32 vcc, 0x100, v154
	s_and_saveexec_b64 s[48:49], vcc
	v_lshlrev_b32_e32 v235, 2, v154
	ds_read_b32 v236, v235
	ds_read_b32 v237, v235 offset:1024
	ds_read_b32 v238, v235 offset:2048
	ds_read_b32 v239, v235 offset:3072
	s_lshl_b32 s50, s4, 3
	s_and_b32 s50, s50, 56
	s_bfe_u32 s51, s4, 0x30003
	s_or_b32 s50, s50, s51
	s_lshl_b32 s50, s50, 2
	s_lshr_b32 s51, s4, 6
	s_or_b32 s50, s50, s51
	s_lshl_b32 s50, s50, 10
	s_add_u32 s50, s50, s72
	s_addc_u32 s51, s73, 0
	s_add_u32 s50, s50, 0x19500000
	s_addc_u32 s51, s51, 0
	s_waitcnt lgkmcnt(0)
	v_add_f32_e32 v236, v236, v237
	v_add_f32_e32 v238, v238, v239
	v_add_f32_e32 v236, v236, v238
	global_store_dword v235, v236, s[50:51]
	s_mov_b64 exec, s[48:49]
	s_mov_b32 s92, s4
	v_mov_b64_e32 v[242:243], v[0:1]
	v_mov_b64_e32 v[244:245], v[2:3]
	v_mov_b64_e32 v[246:247], v[4:5]
	v_mov_b64_e32 v[248:249], v[6:7]
	s_add_i32 s4, s4, s74
	s_add_i32 s9, s9, s20
	s_cmpk_lt_i32 s4, 0x100
	s_cbranch_scc0 .LBB0_705
.LBB0_699:
	s_lshl_b32 s0, s4, 3
	v_mov_b32_e32 v139, v154
	s_and_b32 s10, s0, 56
	s_bfe_u32 s0, s4, 0x30003
	s_or_b32 s12, s10, s0
	v_ashrrev_i32_e32 v5, 6, v139
	v_ashrrev_i32_e32 v4, 3, v139
	v_lshrrev_b32_e32 v1, 2, v139
	v_bfi_b32 v9, -16, v4, v1
	v_lshlrev_b32_e32 v1, 5, v5
	s_ashr_i32 s11, s4, 6
	s_mul_i32 s0, s12, 0x160000
	v_readlane_b32 s14, v255, 2
	v_lshrrev_b32_e32 v0, 4, v139
	v_and_b32_e32 v2, 32, v1
	v_and_b32_e32 v1, 3, v139
	v_readlane_b32 s15, v255, 3
	s_add_u32 s0, s14, s0
	v_bitop3_b32 v0, v0, v1, 2 bitop3:0x6c
	s_addc_u32 s1, s15, 0
	s_mul_i32 s14, s11, 0x160000
	v_lshlrev_b32_e32 v3, 3, v0
	s_mul_hi_i32 s13, s11, 0x160000
	s_add_u32 s26, s5, s14
	v_or_b32_e32 v10, v3, v2
	v_mov_b64_e32 v[0:1], s[0:1]
	s_addc_u32 s27, s6, s13
	v_and_b32_e32 v6, 15, v139
	v_mad_i64_i32 v[0:1], s[0:1], v9, s33, v[0:1]
	v_lshlrev_b32_e32 v136, 1, v10
	v_lshlrev_b32_e32 v10, 2, v139
	v_ashrrev_i32_e32 v8, 8, v139
	v_and_b32_e32 v7, 48, v139
	v_lshl_add_u64 v[128:129], v[0:1], 0, v[136:137]
	v_mov_b64_e32 v[0:1], s[26:27]
	v_lshlrev_b32_e32 v6, 6, v6
	v_and_b32_e32 v10, 32, v10
	v_mad_i64_i32 v[0:1], s[0:1], v9, s33, v[0:1]
	v_or_b32_e32 v9, v6, v7
	v_bitop3_b32 v6, v6, v10, v7 bitop3:0x36
	v_lshlrev_b32_e32 v7, 13, v8
	v_lshlrev_b32_e32 v5, 12, v5
	v_lshlrev_b32_e32 v146, 4, v139
	v_bitop3_b32 v134, v9, v7, v10 bitop3:0xde
	v_and_or_b32 v5, v5, s75, v6
	v_add_u32_e32 v147, 0x10000, v146
	v_add_u32_e32 v144, 0x10000, v134
	v_or_b32_e32 v135, 0x8000, v5
	v_or_b32_e32 v145, 0x18000, v5
	v_lshl_add_u64 v[0:1], v[0:1], 0, v[136:137]
	v_add_u32_e32 v148, 0x8000, v146
	v_add_u32_e32 v149, 0xa000, v146
	v_readfirstlane_b32 s0, v148
	s_waitcnt vmcnt(0)
	s_mov_b32 m0, s0
	s_mov_b64 s[26:27], 0x58000
	v_readfirstlane_b32 s0, v149
	global_load_lds_dwordx4 v[0:1], off
	v_lshl_add_u64 v[6:7], v[0:1], 0, s[26:27]
	s_mov_b32 m0, s0
	v_readfirstlane_b32 s0, v146
	v_add_u32_e32 v150, 0x2000, v146
	global_load_lds_dwordx4 v[6:7], off
	s_mov_b32 m0, s0
	v_readfirstlane_b32 s0, v150
	v_add_u32_e32 v151, 0xc000, v146
	global_load_lds_dwordx4 v[128:129], off
	v_lshl_add_u64 v[6:7], v[128:129], 0, s[26:27]
	s_mov_b32 m0, s0
	s_mov_b64 s[26:27], 0xb0000
	v_readfirstlane_b32 s0, v151
	v_add_u32_e32 v152, 0xe000, v146
	global_load_lds_dwordx4 v[6:7], off
	v_lshl_add_u64 v[6:7], v[0:1], 0, s[26:27]
	s_mov_b32 m0, s0
	s_mov_b64 s[36:37], 0x108000
	v_readfirstlane_b32 s0, v152
	v_add_u32_e32 v153, 0x4000, v146
	global_load_lds_dwordx4 v[6:7], off
	v_lshl_add_u64 v[6:7], v[0:1], 0, s[36:37]
	s_mov_b32 m0, s0
	v_readfirstlane_b32 s0, v153
	v_add_u32_e32 v170, 0x6000, v146
	global_load_lds_dwordx4 v[6:7], off
	v_lshl_add_u64 v[6:7], v[128:129], 0, s[26:27]
	s_mov_b32 m0, s0
	v_readfirstlane_b32 s0, v170
	global_load_lds_dwordx4 v[6:7], off
	v_lshl_add_u64 v[6:7], v[128:129], 0, s[36:37]
	s_mov_b32 m0, s0
	v_cmp_eq_u32_e32 vcc, 1, v8
	global_load_lds_dwordx4 v[6:7], off
	s_and_saveexec_b64 s[0:1], vcc
	s_cbranch_execz .LBB0_701
	s_barrier
.LBB0_701:
	s_or_b64 exec, exec, s[0:1]
	s_lshr_b32 s0, s4, 3
	s_bfe_u32 s1, s9, 0x30003
	s_and_b32 s0, s0, 7
	s_mul_i32 s1, s1, 0x580000
	s_mul_i32 s0, s0, 0xb0000
	v_add_u32_e32 v171, 0x8000, v147
	s_add_i32 s1, s1, s0
	s_mov_b64 s[26:27], 0x80
	v_readfirstlane_b32 s0, v171
	v_add_u32_e32 v172, 0xa000, v147
	v_and_b32_e32 v6, -16, v4
	v_lshl_add_u64 v[4:5], v[0:1], 0, s[26:27]
	s_mov_b32 m0, s0
	s_mov_b64 s[36:37], 0x58080
	v_readfirstlane_b32 s0, v172
	s_waitcnt vmcnt(4)
	s_barrier
	global_load_lds_dwordx4 v[4:5], off
	v_lshl_add_u64 v[4:5], v[0:1], 0, s[36:37]
	s_mov_b32 m0, s0
	v_readfirstlane_b32 s0, v147
	v_add_u32_e32 v173, 0x2000, v147
	global_load_lds_dwordx4 v[4:5], off
	v_lshl_add_u64 v[4:5], v[128:129], 0, s[26:27]
	s_mov_b32 m0, s0
	v_readfirstlane_b32 s0, v173
	s_lshl_b32 s15, s1, 1
	global_load_lds_dwordx4 v[4:5], off
	v_lshl_add_u64 v[4:5], v[128:129], 0, s[36:37]
	s_mov_b32 m0, s0
	s_mov_b64 s[0:1], 0xb0080
	v_add_u32_e32 v174, 0xc000, v147
	global_load_lds_dwordx4 v[4:5], off
	v_lshl_add_u64 v[4:5], v[0:1], 0, s[0:1]
	v_readfirstlane_b32 s0, v174
	s_mov_b32 m0, s0
	s_mov_b64 s[0:1], 0x108080
	v_add_u32_e32 v175, 0xe000, v147
	v_lshl_add_u64 v[0:1], v[0:1], 0, s[0:1]
	v_readfirstlane_b32 s0, v175
	global_load_lds_dwordx4 v[4:5], off
	s_mov_b32 m0, s0
	s_add_u32 s0, s21, s14
	global_load_lds_dwordx4 v[0:1], off
	v_bfe_u32 v7, v139, 2, 4
	s_addc_u32 s1, s22, s13
	v_add_lshl_u32 v136, v2, v3, 1
	v_add_u32_e32 v2, v6, v7
	v_mov_b64_e32 v[0:1], s[0:1]
	v_mad_i64_i32 v[130:131], s[0:1], v2, s33, v[0:1]
	s_add_u32 s0, s72, s15
	s_addc_u32 s1, s73, 0
	s_waitcnt vmcnt(6)
	v_mov_b64_e32 v[0:1], s[0:1]
	v_mad_i64_i32 v[132:133], s[0:1], v2, s33, v[0:1]
	v_mov_b32_e32 v0, 0
	s_mov_b32 s0, -2
	v_mov_b32_e32 v1, v0
	v_mov_b32_e32 v2, v0
	v_mov_b32_e32 v3, v0
	v_mov_b32_e32 v4, v0
	v_mov_b32_e32 v5, v0
	v_mov_b32_e32 v6, v0
	v_mov_b32_e32 v7, v0
	v_mov_b32_e32 v12, v0
	v_mov_b32_e32 v13, v0
	v_mov_b32_e32 v14, v0
	v_mov_b32_e32 v15, v0
	v_mov_b32_e32 v20, v0
	v_mov_b32_e32 v21, v0
	v_mov_b32_e32 v22, v0
	v_mov_b32_e32 v23, v0
	v_mov_b32_e32 v8, v0
	v_mov_b32_e32 v9, v0
	v_mov_b32_e32 v10, v0
	v_mov_b32_e32 v11, v0
	v_mov_b32_e32 v16, v0
	v_mov_b32_e32 v17, v0
	v_mov_b32_e32 v18, v0
	v_mov_b32_e32 v19, v0
	v_mov_b32_e32 v28, v0
	v_mov_b32_e32 v29, v0
	v_mov_b32_e32 v30, v0
	v_mov_b32_e32 v31, v0
	v_mov_b32_e32 v36, v0
	v_mov_b32_e32 v37, v0
	v_mov_b32_e32 v38, v0
	v_mov_b32_e32 v39, v0
	v_mov_b32_e32 v24, v0
	v_mov_b32_e32 v25, v0
	v_mov_b32_e32 v26, v0
	v_mov_b32_e32 v27, v0
	v_mov_b32_e32 v32, v0
	v_mov_b32_e32 v33, v0
	v_mov_b32_e32 v34, v0
	v_mov_b32_e32 v35, v0
	v_mov_b32_e32 v44, v0
	v_mov_b32_e32 v45, v0
	v_mov_b32_e32 v46, v0
	v_mov_b32_e32 v47, v0
	v_mov_b32_e32 v52, v0
	v_mov_b32_e32 v53, v0
	v_mov_b32_e32 v54, v0
	v_mov_b32_e32 v55, v0
	v_mov_b32_e32 v40, v0
	v_mov_b32_e32 v41, v0
	v_mov_b32_e32 v42, v0
	v_mov_b32_e32 v43, v0
	v_mov_b32_e32 v48, v0
	v_mov_b32_e32 v49, v0
	v_mov_b32_e32 v50, v0
	v_mov_b32_e32 v51, v0
	v_mov_b32_e32 v56, v0
	v_mov_b32_e32 v57, v0
	v_mov_b32_e32 v58, v0
	v_mov_b32_e32 v59, v0
	v_mov_b32_e32 v60, v0
	v_mov_b32_e32 v61, v0
	v_mov_b32_e32 v62, v0
	v_mov_b32_e32 v63, v0
	v_mov_b32_e32 v64, v0
	v_mov_b32_e32 v65, v0
	v_mov_b32_e32 v66, v0
	v_mov_b32_e32 v67, v0
	v_mov_b32_e32 v68, v0
	v_mov_b32_e32 v69, v0
	v_mov_b32_e32 v70, v0
	v_mov_b32_e32 v71, v0
	v_mov_b32_e32 v80, v0
	v_mov_b32_e32 v81, v0
	v_mov_b32_e32 v82, v0
	v_mov_b32_e32 v83, v0
	v_mov_b32_e32 v84, v0
	v_mov_b32_e32 v85, v0
	v_mov_b32_e32 v86, v0
	v_mov_b32_e32 v87, v0
	v_mov_b32_e32 v72, v0
	v_mov_b32_e32 v73, v0
	v_mov_b32_e32 v74, v0
	v_mov_b32_e32 v75, v0
	v_mov_b32_e32 v76, v0
	v_mov_b32_e32 v77, v0
	v_mov_b32_e32 v78, v0
	v_mov_b32_e32 v79, v0
	v_mov_b32_e32 v96, v0
	v_mov_b32_e32 v97, v0
	v_mov_b32_e32 v98, v0
	v_mov_b32_e32 v99, v0
	v_mov_b32_e32 v100, v0
	v_mov_b32_e32 v101, v0
	v_mov_b32_e32 v102, v0
	v_mov_b32_e32 v103, v0
	v_mov_b32_e32 v88, v0
	v_mov_b32_e32 v89, v0
	v_mov_b32_e32 v90, v0
	v_mov_b32_e32 v91, v0
	v_mov_b32_e32 v92, v0
	v_mov_b32_e32 v93, v0
	v_mov_b32_e32 v94, v0
	v_mov_b32_e32 v95, v0
	v_mov_b32_e32 v112, v0
	v_mov_b32_e32 v113, v0
	v_mov_b32_e32 v114, v0
	v_mov_b32_e32 v115, v0
	v_mov_b32_e32 v116, v0
	v_mov_b32_e32 v117, v0
	v_mov_b32_e32 v118, v0
	v_mov_b32_e32 v119, v0
	v_mov_b32_e32 v104, v0
	v_mov_b32_e32 v105, v0
	v_mov_b32_e32 v106, v0
	v_mov_b32_e32 v107, v0
	v_mov_b32_e32 v108, v0
	v_mov_b32_e32 v109, v0
	v_mov_b32_e32 v110, v0
	v_mov_b32_e32 v111, v0
	v_mov_b32_e32 v120, v0
	v_mov_b32_e32 v121, v0
	v_mov_b32_e32 v122, v0
	v_mov_b32_e32 v123, v0
	v_mov_b32_e32 v124, v0
	v_mov_b32_e32 v125, v0
	v_mov_b32_e32 v126, v0
	v_mov_b32_e32 v127, v0
	s_mov_b64 s[26:27], 0x1f5b0080
	s_mov_b64 s[36:37], 0x1f558180
	s_barrier
